# handoff N=2 prio2 with next-segment ds_reads hoisted above leftover MFMAs
# baseline (speedup 1.0000x reference)
; #define PG8_STAGE(bufoff, gbase, voff) do { _Pragma("unroll") for (int _i = 0; _i < 2; ++_i) \
;         asm volatile("s_mov_b32 m0, %2\n\ts_nop 0\n\tglobal_load_lds_dwordx4 %0, %1" :: "v"((voff)[_i]), "s"((const char*)(gbase)), "s"(ldsbase + (unsigned)(bufoff) + ldsw + (unsigned)_i * 8192u) : "memory", "m0"); } while (0)
; #define PG8_LDA(dst, b, h) do { _Pragma("unroll") for (int m = 0; m < 4; ++m) _Pragma("unroll") for (int k = 0; k < 2; ++k) dst[m][k] = *(const PG8_LAS bf16x8*)(lds + PG8_SA(b, h) + aoff + m * 2048 + k * 1024); } while (0)
; #define PG8_WAIT_V(n) asm volatile("s_waitcnt vmcnt(" #n ")" ::: "memory")
; template <class Epi, class Sched, bool ALIGN_EPI = false, bool SP2 = false>
; __device__ __forceinline__ void gemm_phase(PG8_LAS unsigned char* lds, const Gemm g, const Sched& S, const Epi& E) {
;     ...
;             const bool last = (t == nt - 2);
;             const char* a1 = cA + (size_t)(t + 1) * kstep;
;             const char* a2 = last ? nA : cA + (size_t)(t + 2) * kstep; const char* b2 = last ? nB : cB + (size_t)(t + 2) * kstep;
;             const char* a3 = a2 + kstep; const char* b3 = b2 + kstep;
;             if (last && has_next) S.a_ready(nxt);
;             if constexpr (epi_has_mid<Epi>::value) { if (t == Epi::MID_T) E.mid(acc, cur, wr, wc, fr, fq); }
;             if constexpr (SP2) {
;             PG8_LDB(B0, 0, 0); PG8_LDB(B1, 0, 1); PG8_SCHED; PG8_LDA(At, 0, 0); PG8_STAGE(PG8_SA(1, 1), a1 + hstep, voffA);
;             PG8_WAIT_V(8); PG8_WAIT_L(0); PG8_BAR; PG8_MMA(0, 0, At, B0); PG8_MMA(0, 1, At, B1); PG8_BAR; PG8_SCHED;
;             PG8_LDA(At, 0, 1); PG8_STAGE(PG8_SB(0, 0), b2, voffB); PG8_STAGE(PG8_SB(0, 1), b2 + hstep, voffB); PG8_STAGE(PG8_SA(0, 0), a2, voffA);
;             PG8_WAIT_V(8); PG8_WAIT_L(0); PG8_BAR; PG8_MMA(1, 0, At, B0); PG8_MMA(1, 1, At, B1); PG8_BAR; PG8_SCHED;
;             PG8_LDB(B0, 1, 0); PG8_LDB(B1, 1, 1); PG8_SCHED; PG8_LDA(At, 1, 0); PG8_STAGE(PG8_SA(0, 1), a2 + hstep, voffA);
;             PG8_WAIT_V(8); PG8_WAIT_L(0); PG8_BAR; PG8_MMA(0, 0, At, B0); PG8_MMA(0, 1, At, B1); PG8_BAR; PG8_SCHED;
;             PG8_LDA(At, 1, 1); PG8_STAGE(PG8_SB(1, 0), b3, voffB); PG8_STAGE(PG8_SB(1, 1), b3 + hstep, voffB); PG8_STAGE(PG8_SA(1, 0), a3, voffA);
;             PG8_WAIT_V(8); PG8_WAIT_L(0); PG8_BAR; PG8_MMA(1, 0, At, B0); PG8_MMA(1, 1, At, B1); PG8_BAR; PG8_SCHED;
.LBB0_138:
	ds_read_b128 v[148:151], v142
	ds_read_b128 v[152:155], v142 offset:1024
	ds_read_b128 v[156:159], v142 offset:2048
	ds_read_b128 v[160:163], v142 offset:3072
	ds_read_b128 v[164:167], v143
	ds_read_b128 v[168:171], v143 offset:1024
	ds_read_b128 v[172:175], v143 offset:2048
	ds_read_b128 v[176:179], v143 offset:3072
	s_add_u32 s62, s66, 0x100
	s_addc_u32 s63, s67, 0
	s_cmp_eq_u32 s96, 60
	s_cselect_b32 s86, s92, s62
	s_cselect_b32 s87, s13, s63
	s_cselect_b32 s84, s93, s94
	s_cselect_b32 s85, s11, s95
	s_add_u32 s76, s86, 0x80
	s_addc_u32 s77, s87, 0
	ds_read_b128 v[180:183], v144
	ds_read_b128 v[184:187], v144 offset:1024
	ds_read_b128 v[188:191], v144 offset:2048
	ds_read_b128 v[192:195], v144 offset:3072
	ds_read_b128 v[196:199], v144 offset:4096
	ds_read_b128 v[200:203], v144 offset:5120
	ds_read_b128 v[204:207], v144 offset:6144
	ds_read_b128 v[208:211], v144 offset:7168
	s_add_u32 s66, s66, 0x100080
	s_addc_u32 s67, s67, 0
	s_mov_b32 m0, s83
	s_nop 0
	global_load_lds_dwordx4 v136, s[66:67]
	s_nop 0
	s_mov_b32 m0, s88
	s_nop 0
	global_load_lds_dwordx4 v138, s[66:67]
	s_waitcnt vmcnt(8)
	s_waitcnt lgkmcnt(0)
	s_barrier
	s_setprio 1
	s_waitcnt lgkmcnt(7)
	v_mfma_f32_16x16x32_bf16 v[126:129], v[148:151], v[180:183], v[126:129]
	v_mfma_f32_16x16x32_bf16 v[122:125], v[156:159], v[180:183], v[122:125]
	s_waitcnt lgkmcnt(5)
	v_mfma_f32_16x16x32_bf16 v[110:113], v[148:151], v[188:191], v[110:113]
	v_mfma_f32_16x16x32_bf16 v[106:109], v[156:159], v[188:191], v[106:109]
	s_waitcnt lgkmcnt(3)
	v_mfma_f32_16x16x32_bf16 v[94:97], v[148:151], v[196:199], v[94:97]
	v_mfma_f32_16x16x32_bf16 v[90:93], v[156:159], v[196:199], v[90:93]
	s_waitcnt lgkmcnt(1)
	v_mfma_f32_16x16x32_bf16 v[78:81], v[148:151], v[204:207], v[78:81]
	v_mfma_f32_16x16x32_bf16 v[74:77], v[156:159], v[204:207], v[74:77]
	v_mfma_f32_16x16x32_bf16 v[126:129], v[152:155], v[184:187], v[126:129]
	v_mfma_f32_16x16x32_bf16 v[122:125], v[160:163], v[184:187], v[122:125]
	v_mfma_f32_16x16x32_bf16 v[110:113], v[152:155], v[192:195], v[110:113]
	v_mfma_f32_16x16x32_bf16 v[106:109], v[160:163], v[192:195], v[106:109]
	v_mfma_f32_16x16x32_bf16 v[94:97], v[152:155], v[200:203], v[94:97]
	v_mfma_f32_16x16x32_bf16 v[90:93], v[160:163], v[200:203], v[90:93]
	s_waitcnt lgkmcnt(0)
	v_mfma_f32_16x16x32_bf16 v[78:81], v[152:155], v[208:211], v[78:81]
	v_mfma_f32_16x16x32_bf16 v[74:77], v[160:163], v[208:211], v[74:77]
	s_setprio 0
	s_setprio 1
	v_mfma_f32_16x16x32_bf16 v[118:121], v[164:167], v[180:183], v[118:121]
	v_mfma_f32_16x16x32_bf16 v[114:117], v[172:175], v[180:183], v[114:117]
	v_mfma_f32_16x16x32_bf16 v[102:105], v[164:167], v[188:191], v[102:105]
	v_mfma_f32_16x16x32_bf16 v[98:101], v[172:175], v[188:191], v[98:101]
	v_mfma_f32_16x16x32_bf16 v[86:89], v[164:167], v[196:199], v[86:89]
	v_mfma_f32_16x16x32_bf16 v[82:85], v[172:175], v[196:199], v[82:85]
	v_mfma_f32_16x16x32_bf16 v[70:73], v[164:167], v[204:207], v[70:73]
	v_mfma_f32_16x16x32_bf16 v[66:69], v[172:175], v[204:207], v[66:69]
	v_mfma_f32_16x16x32_bf16 v[118:121], v[168:171], v[184:187], v[118:121]
	v_mfma_f32_16x16x32_bf16 v[114:117], v[176:179], v[184:187], v[114:117]
	v_mfma_f32_16x16x32_bf16 v[102:105], v[168:171], v[192:195], v[102:105]
	v_mfma_f32_16x16x32_bf16 v[98:101], v[176:179], v[192:195], v[98:101]
	v_mfma_f32_16x16x32_bf16 v[86:89], v[168:171], v[200:203], v[86:89]
	v_mfma_f32_16x16x32_bf16 v[82:85], v[176:179], v[200:203], v[82:85]
	s_setprio 2
	s_barrier
	ds_read_b128 v[180:183], v144 offset:16384
	ds_read_b128 v[184:187], v144 offset:17408
	ds_read_b128 v[188:191], v144 offset:18432
	ds_read_b128 v[192:195], v144 offset:19456
	ds_read_b128 v[196:199], v144 offset:20480
	ds_read_b128 v[200:203], v144 offset:21504
	ds_read_b128 v[204:207], v144 offset:22528
	v_mfma_f32_16x16x32_bf16 v[70:73], v[168:171], v[208:211], v[70:73]
	v_mfma_f32_16x16x32_bf16 v[66:69], v[176:179], v[208:211], v[66:69]
	s_setprio 0
	ds_read_b128 v[208:211], v144 offset:23552
	s_mov_b32 m0, s55
	s_nop 0
	global_load_lds_dwordx4 v137, s[84:85]
	s_add_u32 s66, s84, 0x100000
	s_mov_b32 m0, s56
	s_nop 0
	global_load_lds_dwordx4 v139, s[84:85]
	s_addc_u32 s67, s85, 0
	s_mov_b32 m0, s57
	s_nop 0
	global_load_lds_dwordx4 v137, s[66:67]
	s_nop 0
	s_mov_b32 m0, s58
	s_nop 0
	global_load_lds_dwordx4 v139, s[66:67]
	s_nop 0
	s_mov_b32 m0, s54
	s_nop 0
	global_load_lds_dwordx4 v136, s[86:87]
	s_nop 0
	s_mov_b32 m0, s59
	s_nop 0
	global_load_lds_dwordx4 v138, s[86:87]
	s_waitcnt vmcnt(8)
	s_waitcnt lgkmcnt(0)
	s_barrier
	s_setprio 1
	s_waitcnt lgkmcnt(7)
	v_mfma_f32_16x16x32_bf16 v[62:65], v[148:151], v[180:183], v[62:65]
	v_mfma_f32_16x16x32_bf16 v[58:61], v[156:159], v[180:183], v[58:61]
	s_waitcnt lgkmcnt(5)
	v_mfma_f32_16x16x32_bf16 v[46:49], v[148:151], v[188:191], v[46:49]
	v_mfma_f32_16x16x32_bf16 v[42:45], v[156:159], v[188:191], v[42:45]
	s_waitcnt lgkmcnt(3)
	v_mfma_f32_16x16x32_bf16 v[30:33], v[148:151], v[196:199], v[30:33]
	v_mfma_f32_16x16x32_bf16 v[26:29], v[156:159], v[196:199], v[26:29]
	s_waitcnt lgkmcnt(1)
	v_mfma_f32_16x16x32_bf16 v[14:17], v[148:151], v[204:207], v[14:17]
	v_mfma_f32_16x16x32_bf16 v[10:13], v[156:159], v[204:207], v[10:13]
	v_mfma_f32_16x16x32_bf16 v[62:65], v[152:155], v[184:187], v[62:65]
	v_mfma_f32_16x16x32_bf16 v[58:61], v[160:163], v[184:187], v[58:61]
	v_mfma_f32_16x16x32_bf16 v[46:49], v[152:155], v[192:195], v[46:49]
	v_mfma_f32_16x16x32_bf16 v[42:45], v[160:163], v[192:195], v[42:45]
	v_mfma_f32_16x16x32_bf16 v[30:33], v[152:155], v[200:203], v[30:33]
	v_mfma_f32_16x16x32_bf16 v[26:29], v[160:163], v[200:203], v[26:29]
	s_waitcnt lgkmcnt(0)
	v_mfma_f32_16x16x32_bf16 v[14:17], v[152:155], v[208:211], v[14:17]
	v_mfma_f32_16x16x32_bf16 v[10:13], v[160:163], v[208:211], v[10:13]
	s_setprio 0
	s_setprio 1
	v_mfma_f32_16x16x32_bf16 v[54:57], v[164:167], v[180:183], v[54:57]
	v_mfma_f32_16x16x32_bf16 v[50:53], v[172:175], v[180:183], v[50:53]
	v_mfma_f32_16x16x32_bf16 v[38:41], v[164:167], v[188:191], v[38:41]
	v_mfma_f32_16x16x32_bf16 v[34:37], v[172:175], v[188:191], v[34:37]
	v_mfma_f32_16x16x32_bf16 v[22:25], v[164:167], v[196:199], v[22:25]
	v_mfma_f32_16x16x32_bf16 v[18:21], v[172:175], v[196:199], v[18:21]
	v_mfma_f32_16x16x32_bf16 v[6:9], v[164:167], v[204:207], v[6:9]
	v_mfma_f32_16x16x32_bf16 v[2:5], v[172:175], v[204:207], v[2:5]
	v_mfma_f32_16x16x32_bf16 v[54:57], v[168:171], v[184:187], v[54:57]
	v_mfma_f32_16x16x32_bf16 v[50:53], v[176:179], v[184:187], v[50:53]
	v_mfma_f32_16x16x32_bf16 v[38:41], v[168:171], v[192:195], v[38:41]
	v_mfma_f32_16x16x32_bf16 v[34:37], v[176:179], v[192:195], v[34:37]
	v_mfma_f32_16x16x32_bf16 v[22:25], v[168:171], v[200:203], v[22:25]
	v_mfma_f32_16x16x32_bf16 v[18:21], v[176:179], v[200:203], v[18:21]
	s_setprio 2
	s_barrier
; #define PG8_STAGE(bufoff, gbase, voff) do { _Pragma("unroll") for (int _i = 0; _i < 2; ++_i) \
;         asm volatile("s_mov_b32 m0, %2\n\ts_nop 0\n\tglobal_load_lds_dwordx4 %0, %1" :: "v"((voff)[_i]), "s"((const char*)(gbase)), "s"(ldsbase + (unsigned)(bufoff) + ldsw + (unsigned)_i * 8192u) : "memory", "m0"); } while (0)
; #define PG8_LDA(dst, b, h) do { _Pragma("unroll") for (int m = 0; m < 4; ++m) _Pragma("unroll") for (int k = 0; k < 2; ++k) dst[m][k] = *(const PG8_LAS bf16x8*)(lds + PG8_SA(b, h) + aoff + m * 2048 + k * 1024); } while (0)
; #define PG8_LDB(dst, b, h) do { _Pragma("unroll") for (int n = 0; n < 2; ++n) _Pragma("unroll") for (int k = 0; k < 2; ++k) dst[n][k] = *(const PG8_LAS bf16x8*)(lds + PG8_SB(b, h) + boff + n * 2048 + k * 1024); } while (0)
; #define PG8_MMA(ai, bj, At, Bt) do { __builtin_amdgcn_s_setprio(1); _Pragma("unroll") for (int m = 0; m < 4; ++m) _Pragma("unroll") for (int n = 0; n < 2; ++n) _Pragma("unroll") for (int k = 0; k < 2; ++k) \
;         acc[ai][bj][m][n] = __builtin_amdgcn_mfma_f32_16x16x32_bf16(Bt[n][k], At[m][k], acc[ai][bj][m][n], 0, 0, 0); __builtin_amdgcn_s_setprio(0); } while (0)
; #define PG8_WAIT_V(n) asm volatile("s_waitcnt vmcnt(" #n ")" ::: "memory")
; #define PG8_WAIT_L(n) asm volatile("s_waitcnt lgkmcnt(" #n ")" ::: "memory")
; #define PG8_BAR __builtin_amdgcn_s_barrier()
; #define PG8_SCHED __builtin_amdgcn_sched_barrier(0)
; template <class Epi, class Sched, bool ALIGN_EPI = false, bool SP2 = false>
; __device__ __forceinline__ void gemm_phase(PG8_LAS unsigned char* lds, const Gemm g, const Sched& S, const Epi& E) {
;     ...
;             PG8_LDB(B0, 1, 0); PG8_LDB(B1, 1, 1); PG8_SCHED; PG8_LDA(At, 1, 0); PG8_STAGE(PG8_SA(0, 1), a2 + hstep, voffA);
;             PG8_WAIT_V(8); PG8_WAIT_L(0); PG8_BAR; PG8_MMA(0, 0, At, B0); PG8_MMA(0, 1, At, B1); PG8_BAR; PG8_SCHED;
;             PG8_LDA(At, 1, 1); PG8_STAGE(PG8_SB(1, 0), b3, voffB); PG8_STAGE(PG8_SB(1, 1), b3 + hstep, voffB); PG8_STAGE(PG8_SA(1, 0), a3, voffA);
;             PG8_WAIT_V(8); PG8_WAIT_L(0); PG8_BAR; PG8_MMA(1, 0, At, B0); PG8_MMA(1, 1, At, B1); PG8_BAR; PG8_SCHED;
	ds_read_b128 v[148:151], v145
	ds_read_b128 v[152:155], v145 offset:1024
	ds_read_b128 v[156:159], v145 offset:2048
	ds_read_b128 v[160:163], v145 offset:3072
	ds_read_b128 v[164:167], v146
	v_mfma_f32_16x16x32_bf16 v[6:9], v[168:171], v[208:211], v[6:9]
	v_mfma_f32_16x16x32_bf16 v[2:5], v[176:179], v[208:211], v[2:5]
	s_setprio 0
	ds_read_b128 v[168:171], v146 offset:1024
	ds_read_b128 v[172:175], v146 offset:2048
	ds_read_b128 v[176:179], v146 offset:3072
	ds_read_b128 v[180:183], v144 offset:32768
	ds_read_b128 v[184:187], v144 offset:33792
	ds_read_b128 v[188:191], v144 offset:34816
	ds_read_b128 v[192:195], v144 offset:35840
	ds_read_b128 v[196:199], v144 offset:36864
	ds_read_b128 v[200:203], v144 offset:37888
	ds_read_b128 v[204:207], v144 offset:38912
	ds_read_b128 v[208:211], v144 offset:39936
	s_add_u32 s66, s86, 0x100000
	s_addc_u32 s67, s87, 0
	s_mov_b32 m0, s60
	s_nop 0
	global_load_lds_dwordx4 v136, s[66:67]
	s_nop 0
	s_mov_b32 m0, s61
	s_nop 0
	global_load_lds_dwordx4 v138, s[66:67]
	s_waitcnt vmcnt(8)
	s_waitcnt lgkmcnt(0)
	s_barrier
	s_setprio 1
	s_waitcnt lgkmcnt(7)
	v_mfma_f32_16x16x32_bf16 v[126:129], v[148:151], v[180:183], v[126:129]
	v_mfma_f32_16x16x32_bf16 v[122:125], v[156:159], v[180:183], v[122:125]
	s_waitcnt lgkmcnt(5)
	v_mfma_f32_16x16x32_bf16 v[110:113], v[148:151], v[188:191], v[110:113]
	v_mfma_f32_16x16x32_bf16 v[106:109], v[156:159], v[188:191], v[106:109]
	s_waitcnt lgkmcnt(3)
	v_mfma_f32_16x16x32_bf16 v[94:97], v[148:151], v[196:199], v[94:97]
	v_mfma_f32_16x16x32_bf16 v[90:93], v[156:159], v[196:199], v[90:93]
	s_waitcnt lgkmcnt(1)
	v_mfma_f32_16x16x32_bf16 v[78:81], v[148:151], v[204:207], v[78:81]
	v_mfma_f32_16x16x32_bf16 v[74:77], v[156:159], v[204:207], v[74:77]
	v_mfma_f32_16x16x32_bf16 v[126:129], v[152:155], v[184:187], v[126:129]
	v_mfma_f32_16x16x32_bf16 v[122:125], v[160:163], v[184:187], v[122:125]
	v_mfma_f32_16x16x32_bf16 v[110:113], v[152:155], v[192:195], v[110:113]
	v_mfma_f32_16x16x32_bf16 v[106:109], v[160:163], v[192:195], v[106:109]
	v_mfma_f32_16x16x32_bf16 v[94:97], v[152:155], v[200:203], v[94:97]
	v_mfma_f32_16x16x32_bf16 v[90:93], v[160:163], v[200:203], v[90:93]
	s_waitcnt lgkmcnt(0)
	v_mfma_f32_16x16x32_bf16 v[78:81], v[152:155], v[208:211], v[78:81]
	v_mfma_f32_16x16x32_bf16 v[74:77], v[160:163], v[208:211], v[74:77]
	s_setprio 0
	s_setprio 1
	v_mfma_f32_16x16x32_bf16 v[118:121], v[164:167], v[180:183], v[118:121]
	v_mfma_f32_16x16x32_bf16 v[114:117], v[172:175], v[180:183], v[114:117]
	v_mfma_f32_16x16x32_bf16 v[102:105], v[164:167], v[188:191], v[102:105]
	v_mfma_f32_16x16x32_bf16 v[98:101], v[172:175], v[188:191], v[98:101]
	v_mfma_f32_16x16x32_bf16 v[86:89], v[164:167], v[196:199], v[86:89]
	v_mfma_f32_16x16x32_bf16 v[82:85], v[172:175], v[196:199], v[82:85]
	v_mfma_f32_16x16x32_bf16 v[70:73], v[164:167], v[204:207], v[70:73]
	v_mfma_f32_16x16x32_bf16 v[66:69], v[172:175], v[204:207], v[66:69]
	v_mfma_f32_16x16x32_bf16 v[118:121], v[168:171], v[184:187], v[118:121]
	v_mfma_f32_16x16x32_bf16 v[114:117], v[176:179], v[184:187], v[114:117]
	v_mfma_f32_16x16x32_bf16 v[102:105], v[168:171], v[192:195], v[102:105]
	v_mfma_f32_16x16x32_bf16 v[98:101], v[176:179], v[192:195], v[98:101]
	v_mfma_f32_16x16x32_bf16 v[86:89], v[168:171], v[200:203], v[86:89]
	v_mfma_f32_16x16x32_bf16 v[82:85], v[176:179], v[200:203], v[82:85]
	s_setprio 2
	s_barrier
	ds_read_b128 v[180:183], v144 offset:49152
	ds_read_b128 v[184:187], v144 offset:50176
	ds_read_b128 v[188:191], v144 offset:51200
	ds_read_b128 v[192:195], v144 offset:52224
	ds_read_b128 v[196:199], v144 offset:53248
	ds_read_b128 v[200:203], v144 offset:54272
	ds_read_b128 v[204:207], v144 offset:55296
	v_mfma_f32_16x16x32_bf16 v[70:73], v[168:171], v[208:211], v[70:73]
	v_mfma_f32_16x16x32_bf16 v[66:69], v[176:179], v[208:211], v[66:69]
	s_setprio 0
	ds_read_b128 v[208:211], v144 offset:56320
	s_add_u32 s66, s84, 0x80
	s_addc_u32 s67, s85, 0
	s_mov_b32 m0, s64
	s_nop 0
	global_load_lds_dwordx4 v137, s[66:67]
	s_nop 0
	s_mov_b32 m0, s65
	s_nop 0
	global_load_lds_dwordx4 v139, s[66:67]
	s_add_u32 s66, s84, 0x100080
	s_addc_u32 s67, s85, 0
	s_mov_b32 m0, s70
	s_nop 0
	global_load_lds_dwordx4 v137, s[66:67]
	s_nop 0
	s_mov_b32 m0, s71
	s_nop 0
	global_load_lds_dwordx4 v139, s[66:67]
	s_nop 0
	s_mov_b32 m0, s68
	s_nop 0
	global_load_lds_dwordx4 v136, s[76:77]
	s_nop 0
	s_mov_b32 m0, s69
	s_nop 0
	global_load_lds_dwordx4 v138, s[76:77]
	s_waitcnt vmcnt(8)
	s_waitcnt lgkmcnt(0)
	s_barrier
	s_setprio 1
	s_waitcnt lgkmcnt(7)
	v_mfma_f32_16x16x32_bf16 v[62:65], v[148:151], v[180:183], v[62:65]
	v_mfma_f32_16x16x32_bf16 v[58:61], v[156:159], v[180:183], v[58:61]
	s_waitcnt lgkmcnt(5)
	v_mfma_f32_16x16x32_bf16 v[46:49], v[148:151], v[188:191], v[46:49]
	v_mfma_f32_16x16x32_bf16 v[42:45], v[156:159], v[188:191], v[42:45]
	s_waitcnt lgkmcnt(3)
	v_mfma_f32_16x16x32_bf16 v[30:33], v[148:151], v[196:199], v[30:33]
	v_mfma_f32_16x16x32_bf16 v[26:29], v[156:159], v[196:199], v[26:29]
	s_waitcnt lgkmcnt(1)
	v_mfma_f32_16x16x32_bf16 v[14:17], v[148:151], v[204:207], v[14:17]
	v_mfma_f32_16x16x32_bf16 v[10:13], v[156:159], v[204:207], v[10:13]
	v_mfma_f32_16x16x32_bf16 v[62:65], v[152:155], v[184:187], v[62:65]
	v_mfma_f32_16x16x32_bf16 v[58:61], v[160:163], v[184:187], v[58:61]
	v_mfma_f32_16x16x32_bf16 v[46:49], v[152:155], v[192:195], v[46:49]
	v_mfma_f32_16x16x32_bf16 v[42:45], v[160:163], v[192:195], v[42:45]
	v_mfma_f32_16x16x32_bf16 v[30:33], v[152:155], v[200:203], v[30:33]
	v_mfma_f32_16x16x32_bf16 v[26:29], v[160:163], v[200:203], v[26:29]
	s_waitcnt lgkmcnt(0)
	v_mfma_f32_16x16x32_bf16 v[14:17], v[152:155], v[208:211], v[14:17]
	v_mfma_f32_16x16x32_bf16 v[10:13], v[160:163], v[208:211], v[10:13]
	s_setprio 0
	s_setprio 1
	v_mfma_f32_16x16x32_bf16 v[54:57], v[164:167], v[180:183], v[54:57]
	v_mfma_f32_16x16x32_bf16 v[50:53], v[172:175], v[180:183], v[50:53]
	v_mfma_f32_16x16x32_bf16 v[38:41], v[164:167], v[188:191], v[38:41]
	v_mfma_f32_16x16x32_bf16 v[34:37], v[172:175], v[188:191], v[34:37]
	v_mfma_f32_16x16x32_bf16 v[22:25], v[164:167], v[196:199], v[22:25]
	v_mfma_f32_16x16x32_bf16 v[18:21], v[172:175], v[196:199], v[18:21]
	v_mfma_f32_16x16x32_bf16 v[6:9], v[164:167], v[204:207], v[6:9]
	v_mfma_f32_16x16x32_bf16 v[2:5], v[172:175], v[204:207], v[2:5]
	v_mfma_f32_16x16x32_bf16 v[54:57], v[168:171], v[184:187], v[54:57]
	v_mfma_f32_16x16x32_bf16 v[50:53], v[176:179], v[184:187], v[50:53]
	v_mfma_f32_16x16x32_bf16 v[38:41], v[168:171], v[192:195], v[38:41]
	v_mfma_f32_16x16x32_bf16 v[34:37], v[176:179], v[192:195], v[34:37]
	v_mfma_f32_16x16x32_bf16 v[22:25], v[168:171], v[200:203], v[22:25]
	v_mfma_f32_16x16x32_bf16 v[18:21], v[176:179], v[200:203], v[18:21]
	v_mfma_f32_16x16x32_bf16 v[6:9], v[168:171], v[208:211], v[6:9]
	s_setprio 2
	s_barrier
; __device__ __forceinline__ unsigned cvt_pk_bf16(float lo, float hi) { unsigned r; asm volatile("v_cvt_pk_bf16_f32 %0, %1, %2" : "=v"(r) : "v"(lo), "v"(hi)); return r; }
; __device__ __forceinline__ float silu_f(float x) { return x * sigmoid_f(x); }
; #define PG8_MMA(ai, bj, At, Bt) do { __builtin_amdgcn_s_setprio(1); _Pragma("unroll") for (int m = 0; m < 4; ++m) _Pragma("unroll") for (int n = 0; n < 2; ++n) _Pragma("unroll") for (int k = 0; k < 2; ++k) \
;         acc[ai][bj][m][n] = __builtin_amdgcn_mfma_f32_16x16x32_bf16(Bt[n][k], At[m][k], acc[ai][bj][m][n], 0, 0, 0); __builtin_amdgcn_s_setprio(0); } while (0)
; #define PG8_WAIT_V(n) asm volatile("s_waitcnt vmcnt(" #n ")" ::: "memory")
; #define PG8_WAIT_L(n) asm volatile("s_waitcnt lgkmcnt(" #n ")" ::: "memory")
; #define PG8_BAR __builtin_amdgcn_s_barrier()
; #define PG8_SCHED __builtin_amdgcn_sched_barrier(0)
;     __device__ __forceinline__ void operator()(const f32x4 (&acc)[2][2][4][2], const Unit& u, int wr, int wc, int fr, int fq) const {
;     ...
;             for (int m = 0; m < 4; ++m) { bf16_t* rowp = O + (size_t)(row0 + ai * HALF + m * 16) * ldc + col0;
;                 const f32x4 g0 = acc[ai][0][m][0], g1 = acc[ai][0][m][1], u0 = acc[ai][1][m][0], u1 = acc[ai][1][m][1];
;                 f32x4 v0, v1;
; #pragma unroll
;                 for (int j = 0; j < 4; ++j) { v0[j] = silu_f(g0[j]) * u0[j]; v1[j] = silu_f(g1[j]) * u1[j]; }
;                 u32x4 w; w.x = cvt_pk_bf16(v0[0], v0[1]); w.y = cvt_pk_bf16(v0[2], v0[3]); w.z = cvt_pk_bf16(v1[0], v1[1]); w.w = cvt_pk_bf16(v1[2], v1[3]);
;                 *(u32x4*)rowp = w; }
; template <class Epi, class Sched, bool ALIGN_EPI = false, bool SP2 = false>
; __device__ __forceinline__ void gemm_phase(PG8_LAS unsigned char* lds, const Gemm g, const Sched& S, const Epi& E) {
;     ...
;         for (int t = 0; t < nt; t += 2) {
;     ...
;             PG8_WAIT_V(8); PG8_WAIT_L(0); PG8_BAR; PG8_MMA(1, 0, At, B0); PG8_MMA(1, 1, At, B1); PG8_BAR; PG8_SCHED;
	v_mfma_f32_16x16x32_bf16 v[2:5], v[176:179], v[208:211], v[2:5]
	s_setprio 0
	s_add_i32 s96, s96, 2
	s_add_u32 s94, s94, 0x100
	s_addc_u32 s95, s95, 0
	s_cmp_gt_u32 s96, 61
	s_mov_b64 s[66:67], s[62:63]
	s_cbranch_scc0 .LBB0_138
	v_mul_f32_e32 v134, 0xbfb8aa3b, v126
	v_exp_f32_e32 v150, v134
	v_mul_f32_e32 v134, 0xbfb8aa3b, v122
	v_exp_f32_e32 v151, v134
	v_lshl_or_b32 v148, s91, 7, v141
	v_add_f32_e32 v150, 1.0, v150
	v_rcp_f32_e32 v152, v150
	v_add_f32_e32 v150, 1.0, v151
	v_rcp_f32_e32 v153, v150
	v_lshl_add_u32 v147, s82, 8, v140
	v_mul_f32_e32 v126, v126, v152
	v_mul_f32_e32 v118, v126, v118
	v_mul_f32_e32 v126, 0xbfb8aa3b, v127
	v_exp_f32_e32 v126, v126
	v_mul_f32_e32 v152, 0xbfb8aa3b, v123
	v_exp_f32_e32 v152, v152
	v_mul_f32_e32 v122, v122, v153
	v_mul_f32_e32 v122, v122, v114
	v_add_f32_e32 v114, 1.0, v126
	v_rcp_f32_e32 v114, v114
	v_add_f32_e32 v126, 1.0, v152
	v_mul_f32_e32 v152, 0xbfb8aa3b, v128
	v_rcp_f32_e32 v126, v126
	v_exp_f32_e32 v152, v152
	v_mul_f32_e32 v114, v127, v114
	v_mul_f32_e32 v119, v114, v119
	v_mul_f32_e32 v114, v123, v126
	v_add_f32_e32 v123, 1.0, v152
	v_rcp_f32_e32 v123, v123
	v_mul_f32_e32 v126, 0xbfb8aa3b, v124
	v_exp_f32_e32 v126, v126
	v_mul_f32_e32 v127, v114, v115
	v_mul_f32_e32 v114, v128, v123
	v_mul_f32_e32 v115, 0xbfb8aa3b, v129
	v_mul_f32_e32 v123, v114, v120
	v_exp_f32_e32 v115, v115
	v_mul_f32_e32 v120, 0xbfb8aa3b, v125
	v_exp_f32_e32 v120, v120
	v_add_f32_e32 v114, 1.0, v126
	v_rcp_f32_e32 v114, v114
	v_add_f32_e32 v115, 1.0, v115
	v_rcp_f32_e32 v115, v115
	v_add_f32_e32 v120, 1.0, v120
	v_rcp_f32_e32 v120, v120
	v_mul_f32_e32 v114, v124, v114
	v_mul_f32_e32 v124, v114, v116
	v_mul_f32_e32 v114, v129, v115
	v_ashrrev_i32_e32 v149, 31, v148
	v_mov_b64_e32 v[134:135], s[72:73]
	v_mul_f32_e32 v126, v114, v121
	v_mul_f32_e32 v114, v125, v120
	v_mad_i64_i32 v[150:151], s[62:63], v147, s90, v[134:135]
	v_mul_f32_e32 v125, v114, v117
	v_lshlrev_b64 v[114:115], 1, v[148:149]
	v_lshl_add_u64 v[120:121], v[150:151], 0, v[114:115]
	v_cvt_pk_bf16_f32 v116, v118, v119
	v_cvt_pk_bf16_f32 v117, v123, v126
	v_cvt_pk_bf16_f32 v118, v122, v127
	v_cvt_pk_bf16_f32 v119, v124, v125
	global_store_dwordx4 v[120:121], v[116:119], off
	s_and_b64 vcc, exec, s[0:1]
	s_mov_b32 s91, s10
	v_mul_f32_e32 v116, 0xbfb8aa3b, v110
	v_exp_f32_e32 v116, v116
	v_mul_f32_e32 v117, 0xbfb8aa3b, v106
	v_exp_f32_e32 v117, v117
	v_or_b32_e32 v118, 16, v147
	v_add_f32_e32 v116, 1.0, v116
	v_rcp_f32_e32 v119, v116
	v_add_f32_e32 v116, 1.0, v117
	v_rcp_f32_e32 v120, v116
	v_mad_i64_i32 v[116:117], s[62:63], v118, s90, v[134:135]
	v_mul_f32_e32 v110, v110, v119
	v_mul_f32_e32 v110, v110, v102
	v_mul_f32_e32 v102, v106, v120
	v_mul_f32_e32 v106, 0xbfb8aa3b, v111
	v_exp_f32_e32 v106, v106
	v_mul_f32_e32 v118, 0xbfb8aa3b, v107
	v_mul_f32_e32 v119, v102, v98
	v_exp_f32_e32 v118, v118
	v_add_f32_e32 v98, 1.0, v106
	v_rcp_f32_e32 v98, v98
	v_mul_f32_e32 v106, 0xbfb8aa3b, v112
	v_exp_f32_e32 v106, v106
	v_add_f32_e32 v102, 1.0, v118
	v_mul_f32_e32 v98, v111, v98
	v_rcp_f32_e32 v102, v102
	v_mul_f32_e32 v98, v98, v103
	v_add_f32_e32 v103, 1.0, v106
	v_rcp_f32_e32 v103, v103
	v_mul_f32_e32 v102, v107, v102
	v_mul_f32_e32 v106, 0xbfb8aa3b, v108
	v_mul_f32_e32 v107, v102, v99
	v_mul_f32_e32 v99, v112, v103
	v_exp_f32_e32 v106, v106
	v_mul_f32_e32 v99, v99, v104
	v_mul_f32_e32 v103, 0xbfb8aa3b, v113
	v_mul_f32_e32 v104, 0xbfb8aa3b, v109
	v_exp_f32_e32 v103, v103
	v_exp_f32_e32 v104, v104
	v_add_f32_e32 v102, 1.0, v106
	v_rcp_f32_e32 v102, v102
	v_add_f32_e32 v103, 1.0, v103
	v_add_f32_e32 v104, 1.0, v104
	v_rcp_f32_e32 v103, v103
	v_rcp_f32_e32 v104, v104
	v_mul_f32_e32 v102, v108, v102
	v_mul_f32_e32 v106, v102, v100
	v_mul_f32_e32 v100, v113, v103
	v_mul_f32_e32 v102, v109, v104
	v_mul_f32_e32 v100, v100, v105
	v_mul_f32_e32 v101, v102, v101
	v_lshl_add_u64 v[102:103], v[116:117], 0, v[114:115]
	v_cvt_pk_bf16_f32 v98, v110, v98
	v_cvt_pk_bf16_f32 v99, v99, v100
	v_cvt_pk_bf16_f32 v100, v119, v107
	v_cvt_pk_bf16_f32 v101, v106, v101
	global_store_dwordx4 v[102:103], v[98:101], off
	s_mov_b32 s82, s12
	s_mov_b64 s[66:67], s[14:15]
	v_mul_f32_e32 v98, 0xbfb8aa3b, v94
	v_exp_f32_e32 v98, v98
	v_mul_f32_e32 v99, 0xbfb8aa3b, v90
	v_exp_f32_e32 v99, v99
	v_or_b32_e32 v100, 32, v147
	v_add_f32_e32 v98, 1.0, v98
	v_rcp_f32_e32 v101, v98
	v_add_f32_e32 v98, 1.0, v99
	v_rcp_f32_e32 v102, v98
	v_mad_i64_i32 v[98:99], s[62:63], v100, s90, v[134:135]
	v_mul_f32_e32 v94, v94, v101
	v_mul_f32_e32 v94, v94, v86
	v_mul_f32_e32 v86, v90, v102
	v_mul_f32_e32 v90, 0xbfb8aa3b, v95
	v_exp_f32_e32 v90, v90
	v_mul_f32_e32 v100, 0xbfb8aa3b, v91
	v_mul_f32_e32 v101, v86, v82
	v_exp_f32_e32 v100, v100
	v_add_f32_e32 v82, 1.0, v90
	v_rcp_f32_e32 v82, v82
	v_mul_f32_e32 v90, 0xbfb8aa3b, v96
	v_exp_f32_e32 v90, v90
	v_add_f32_e32 v86, 1.0, v100
	v_mul_f32_e32 v82, v95, v82
	v_rcp_f32_e32 v86, v86
	v_mul_f32_e32 v82, v82, v87
	v_add_f32_e32 v87, 1.0, v90
	v_rcp_f32_e32 v87, v87
	v_mul_f32_e32 v86, v91, v86
	v_mul_f32_e32 v90, 0xbfb8aa3b, v92
	v_mul_f32_e32 v91, v86, v83
	v_mul_f32_e32 v83, v96, v87
	v_exp_f32_e32 v90, v90
	v_mul_f32_e32 v83, v83, v88
	v_mul_f32_e32 v87, 0xbfb8aa3b, v97
	v_mul_f32_e32 v88, 0xbfb8aa3b, v93
	v_exp_f32_e32 v87, v87
	v_exp_f32_e32 v88, v88
	v_add_f32_e32 v86, 1.0, v90
	v_rcp_f32_e32 v86, v86
	v_add_f32_e32 v87, 1.0, v87
	v_add_f32_e32 v88, 1.0, v88
	v_rcp_f32_e32 v87, v87
	v_rcp_f32_e32 v88, v88
	v_mul_f32_e32 v86, v92, v86
	v_mul_f32_e32 v90, v86, v84
	v_mul_f32_e32 v84, v97, v87
	v_mul_f32_e32 v86, v93, v88
	v_mul_f32_e32 v84, v84, v89
	v_mul_f32_e32 v85, v86, v85
	v_lshl_add_u64 v[86:87], v[98:99], 0, v[114:115]
	v_cvt_pk_bf16_f32 v82, v94, v82
; __device__ __forceinline__ unsigned cvt_pk_bf16(float lo, float hi) { unsigned r; asm volatile("v_cvt_pk_bf16_f32 %0, %1, %2" : "=v"(r) : "v"(lo), "v"(hi)); return r; }
; __device__ __forceinline__ float silu_f(float x) { return x * sigmoid_f(x); }
;     __device__ __forceinline__ void operator()(const f32x4 (&acc)[2][2][4][2], const Unit& u, int wr, int wc, int fr, int fq) const {
;     ...
;             for (int m = 0; m < 4; ++m) { bf16_t* rowp = O + (size_t)(row0 + ai * HALF + m * 16) * ldc + col0;
;                 const f32x4 g0 = acc[ai][0][m][0], g1 = acc[ai][0][m][1], u0 = acc[ai][1][m][0], u1 = acc[ai][1][m][1];
;                 f32x4 v0, v1;
; #pragma unroll
;                 for (int j = 0; j < 4; ++j) { v0[j] = silu_f(g0[j]) * u0[j]; v1[j] = silu_f(g1[j]) * u1[j]; }
;                 u32x4 w; w.x = cvt_pk_bf16(v0[0], v0[1]); w.y = cvt_pk_bf16(v0[2], v0[3]); w.z = cvt_pk_bf16(v1[0], v1[1]); w.w = cvt_pk_bf16(v1[2], v1[3]);
;                 *(u32x4*)rowp = w; }
	v_cvt_pk_bf16_f32 v83, v83, v84
	v_cvt_pk_bf16_f32 v84, v101, v91
	v_cvt_pk_bf16_f32 v85, v90, v85
	global_store_dwordx4 v[86:87], v[82:85], off
	s_nop 1
	v_mul_f32_e32 v82, 0xbfb8aa3b, v78
	v_exp_f32_e32 v82, v82
	v_mul_f32_e32 v83, 0xbfb8aa3b, v74
	v_exp_f32_e32 v83, v83
	v_or_b32_e32 v84, 48, v147
	v_add_f32_e32 v82, 1.0, v82
	v_rcp_f32_e32 v85, v82
	v_add_f32_e32 v82, 1.0, v83
	v_rcp_f32_e32 v86, v82
	v_mad_i64_i32 v[82:83], s[62:63], v84, s90, v[134:135]
	v_mul_f32_e32 v78, v78, v85
	v_mul_f32_e32 v78, v78, v70
	v_mul_f32_e32 v70, v74, v86
	v_mul_f32_e32 v74, 0xbfb8aa3b, v79
	v_exp_f32_e32 v74, v74
	v_mul_f32_e32 v84, 0xbfb8aa3b, v75
	v_mul_f32_e32 v85, v70, v66
	v_exp_f32_e32 v84, v84
	v_add_f32_e32 v66, 1.0, v74
	v_rcp_f32_e32 v66, v66
	v_mul_f32_e32 v74, 0xbfb8aa3b, v80
	v_exp_f32_e32 v74, v74
	v_add_f32_e32 v70, 1.0, v84
	v_mul_f32_e32 v66, v79, v66
	v_rcp_f32_e32 v70, v70
	v_mul_f32_e32 v66, v66, v71
	v_add_f32_e32 v71, 1.0, v74
	v_rcp_f32_e32 v71, v71
	v_mul_f32_e32 v70, v75, v70
	v_mul_f32_e32 v74, 0xbfb8aa3b, v76
	v_mul_f32_e32 v75, v70, v67
	v_mul_f32_e32 v67, v80, v71
	v_exp_f32_e32 v74, v74
	v_mul_f32_e32 v67, v67, v72
	v_mul_f32_e32 v71, 0xbfb8aa3b, v81
	v_mul_f32_e32 v72, 0xbfb8aa3b, v77
	v_exp_f32_e32 v71, v71
	v_exp_f32_e32 v72, v72
	v_add_f32_e32 v70, 1.0, v74
	v_rcp_f32_e32 v70, v70
	v_add_f32_e32 v71, 1.0, v71
	v_add_f32_e32 v72, 1.0, v72
	v_rcp_f32_e32 v71, v71
	v_rcp_f32_e32 v72, v72
	v_mul_f32_e32 v70, v76, v70
	v_mul_f32_e32 v74, v70, v68
	v_mul_f32_e32 v68, v81, v71
	v_mul_f32_e32 v70, v77, v72
	v_mul_f32_e32 v68, v68, v73
	v_mul_f32_e32 v69, v70, v69
	v_lshl_add_u64 v[70:71], v[82:83], 0, v[114:115]
	v_cvt_pk_bf16_f32 v66, v78, v66
	v_cvt_pk_bf16_f32 v67, v67, v68
	v_cvt_pk_bf16_f32 v68, v85, v75
	v_cvt_pk_bf16_f32 v69, v74, v69
	global_store_dwordx4 v[70:71], v[66:69], off
	s_nop 1
	v_mul_f32_e32 v66, 0xbfb8aa3b, v62
	v_exp_f32_e32 v66, v66
	v_mul_f32_e32 v67, 0xbfb8aa3b, v58
	v_exp_f32_e32 v67, v67
	v_add_u32_e32 v68, 0x80, v147
	v_add_f32_e32 v66, 1.0, v66
	v_rcp_f32_e32 v69, v66
	v_add_f32_e32 v66, 1.0, v67
	v_rcp_f32_e32 v70, v66
	v_mad_i64_i32 v[66:67], s[62:63], v68, s90, v[134:135]
	v_mul_f32_e32 v62, v62, v69
	v_mul_f32_e32 v62, v62, v54
	v_mul_f32_e32 v54, v58, v70
	v_mul_f32_e32 v58, 0xbfb8aa3b, v63
	v_exp_f32_e32 v58, v58
	v_mul_f32_e32 v68, 0xbfb8aa3b, v59
	v_mul_f32_e32 v69, v54, v50
	v_exp_f32_e32 v68, v68
	v_add_f32_e32 v50, 1.0, v58
	v_rcp_f32_e32 v50, v50
	v_mul_f32_e32 v58, 0xbfb8aa3b, v64
	v_exp_f32_e32 v58, v58
	v_add_f32_e32 v54, 1.0, v68
	v_mul_f32_e32 v50, v63, v50
	v_rcp_f32_e32 v54, v54
	v_mul_f32_e32 v50, v50, v55
	v_add_f32_e32 v55, 1.0, v58
	v_rcp_f32_e32 v55, v55
	v_mul_f32_e32 v54, v59, v54
	v_mul_f32_e32 v58, 0xbfb8aa3b, v60
	v_mul_f32_e32 v59, v54, v51
	v_mul_f32_e32 v51, v64, v55
	v_exp_f32_e32 v58, v58
	v_mul_f32_e32 v51, v51, v56
	v_mul_f32_e32 v55, 0xbfb8aa3b, v65
	v_mul_f32_e32 v56, 0xbfb8aa3b, v61
	v_exp_f32_e32 v55, v55
	v_exp_f32_e32 v56, v56
	v_add_f32_e32 v54, 1.0, v58
	v_rcp_f32_e32 v54, v54
	v_add_f32_e32 v55, 1.0, v55
	v_add_f32_e32 v56, 1.0, v56
	v_rcp_f32_e32 v55, v55
	v_rcp_f32_e32 v56, v56
	v_mul_f32_e32 v54, v60, v54
	v_mul_f32_e32 v58, v54, v52
	v_mul_f32_e32 v52, v65, v55
	v_mul_f32_e32 v54, v61, v56
	v_mul_f32_e32 v52, v52, v57
	v_mul_f32_e32 v53, v54, v53
	v_lshl_add_u64 v[54:55], v[66:67], 0, v[114:115]
	v_cvt_pk_bf16_f32 v50, v62, v50
	v_cvt_pk_bf16_f32 v51, v51, v52
	v_cvt_pk_bf16_f32 v52, v69, v59
	v_cvt_pk_bf16_f32 v53, v58, v53
	global_store_dwordx4 v[54:55], v[50:53], off
	s_nop 1
	v_mul_f32_e32 v50, 0xbfb8aa3b, v46
	v_exp_f32_e32 v50, v50
	v_mul_f32_e32 v51, 0xbfb8aa3b, v42
	v_exp_f32_e32 v51, v51
	v_add_u32_e32 v52, 0x90, v147
	v_add_f32_e32 v50, 1.0, v50
	v_rcp_f32_e32 v53, v50
	v_add_f32_e32 v50, 1.0, v51
	v_rcp_f32_e32 v54, v50
	v_mad_i64_i32 v[50:51], s[62:63], v52, s90, v[134:135]
	v_mul_f32_e32 v46, v46, v53
	v_mul_f32_e32 v46, v46, v38
	v_mul_f32_e32 v38, v42, v54
	v_mul_f32_e32 v42, 0xbfb8aa3b, v47
	v_exp_f32_e32 v42, v42
	v_mul_f32_e32 v52, 0xbfb8aa3b, v43
	v_mul_f32_e32 v53, v38, v34
	v_exp_f32_e32 v52, v52
	v_add_f32_e32 v34, 1.0, v42
	v_rcp_f32_e32 v34, v34
	v_mul_f32_e32 v42, 0xbfb8aa3b, v48
	v_exp_f32_e32 v42, v42
	v_add_f32_e32 v38, 1.0, v52
	v_mul_f32_e32 v34, v47, v34
	v_rcp_f32_e32 v38, v38
	v_mul_f32_e32 v34, v34, v39
	v_add_f32_e32 v39, 1.0, v42
; __device__ __forceinline__ unsigned cvt_pk_bf16(float lo, float hi) { unsigned r; asm volatile("v_cvt_pk_bf16_f32 %0, %1, %2" : "=v"(r) : "v"(lo), "v"(hi)); return r; }
; __device__ __forceinline__ float silu_f(float x) { return x * sigmoid_f(x); }
; #define PG8_WAIT_V(n) asm volatile("s_waitcnt vmcnt(" #n ")" ::: "memory")
; #define PG8_BAR __builtin_amdgcn_s_barrier()
;     __device__ __forceinline__ void operator()(const f32x4 (&acc)[2][2][4][2], const Unit& u, int wr, int wc, int fr, int fq) const {
;     ...
;             for (int m = 0; m < 4; ++m) { bf16_t* rowp = O + (size_t)(row0 + ai * HALF + m * 16) * ldc + col0;
;                 const f32x4 g0 = acc[ai][0][m][0], g1 = acc[ai][0][m][1], u0 = acc[ai][1][m][0], u1 = acc[ai][1][m][1];
;                 f32x4 v0, v1;
; #pragma unroll
;                 for (int j = 0; j < 4; ++j) { v0[j] = silu_f(g0[j]) * u0[j]; v1[j] = silu_f(g1[j]) * u1[j]; }
;                 u32x4 w; w.x = cvt_pk_bf16(v0[0], v0[1]); w.y = cvt_pk_bf16(v0[2], v0[3]); w.z = cvt_pk_bf16(v1[0], v1[1]); w.w = cvt_pk_bf16(v1[2], v1[3]);
;                 *(u32x4*)rowp = w; }
; template <class Epi, class Sched, bool ALIGN_EPI = false, bool SP2 = false>
; __device__ __forceinline__ void gemm_phase(PG8_LAS unsigned char* lds, const Gemm g, const Sched& S, const Epi& E) {
;     ...
;         if (!has_next) break;
; #pragma unroll
;         for (int a = 0; a < 2; ++a)
; #pragma unroll
;             for (int b = 0; b < 2; ++b)
; #pragma unroll
;                 for (int m = 0; m < 4; ++m)
; #pragma unroll
;                     for (int n = 0; n < 2; ++n) acc[a][b][m][n] = (f32x4){0.f, 0.f, 0.f, 0.f};
;         cur = nxt; cA = nA; cB = nB; ++ui;
;         if constexpr (ALIGN_EPI) { if (wr == 1) PG8_BAR; }
;     }
;     PG8_WAIT_V(0);
;     if constexpr (!ALIGN_EPI) { if (wr == 0) PG8_BAR; }
;     PG8_BAR;
	v_rcp_f32_e32 v39, v39
	v_mul_f32_e32 v38, v43, v38
	v_mul_f32_e32 v42, 0xbfb8aa3b, v44
	v_mul_f32_e32 v43, v38, v35
	v_mul_f32_e32 v35, v48, v39
	v_exp_f32_e32 v42, v42
	v_mul_f32_e32 v35, v35, v40
	v_mul_f32_e32 v39, 0xbfb8aa3b, v49
	v_mul_f32_e32 v40, 0xbfb8aa3b, v45
	v_exp_f32_e32 v39, v39
	v_exp_f32_e32 v40, v40
	v_add_f32_e32 v38, 1.0, v42
	v_rcp_f32_e32 v38, v38
	v_add_f32_e32 v39, 1.0, v39
	v_add_f32_e32 v40, 1.0, v40
	v_rcp_f32_e32 v39, v39
	v_rcp_f32_e32 v40, v40
	v_mul_f32_e32 v38, v44, v38
	v_mul_f32_e32 v42, v38, v36
	v_mul_f32_e32 v36, v49, v39
	v_mul_f32_e32 v38, v45, v40
	v_mul_f32_e32 v36, v36, v41
	v_mul_f32_e32 v37, v38, v37
	v_lshl_add_u64 v[38:39], v[50:51], 0, v[114:115]
	v_cvt_pk_bf16_f32 v34, v46, v34
	v_cvt_pk_bf16_f32 v35, v35, v36
	v_cvt_pk_bf16_f32 v36, v53, v43
	v_cvt_pk_bf16_f32 v37, v42, v37
	global_store_dwordx4 v[38:39], v[34:37], off
	s_nop 1
	v_mul_f32_e32 v34, 0xbfb8aa3b, v30
	v_exp_f32_e32 v34, v34
	v_mul_f32_e32 v35, 0xbfb8aa3b, v26
	v_exp_f32_e32 v35, v35
	v_add_u32_e32 v36, 0xa0, v147
	v_add_f32_e32 v34, 1.0, v34
	v_rcp_f32_e32 v37, v34
	v_add_f32_e32 v34, 1.0, v35
	v_rcp_f32_e32 v38, v34
	v_mad_i64_i32 v[34:35], s[62:63], v36, s90, v[134:135]
	v_mul_f32_e32 v30, v30, v37
	v_mul_f32_e32 v30, v30, v22
	v_mul_f32_e32 v22, v26, v38
	v_mul_f32_e32 v26, 0xbfb8aa3b, v31
	v_exp_f32_e32 v26, v26
	v_mul_f32_e32 v36, 0xbfb8aa3b, v27
	v_mul_f32_e32 v37, v22, v18
	v_exp_f32_e32 v36, v36
	v_add_f32_e32 v18, 1.0, v26
	v_rcp_f32_e32 v18, v18
	v_mul_f32_e32 v26, 0xbfb8aa3b, v32
	v_exp_f32_e32 v26, v26
	v_add_f32_e32 v22, 1.0, v36
	v_mul_f32_e32 v18, v31, v18
	v_rcp_f32_e32 v22, v22
	v_mul_f32_e32 v18, v18, v23
	v_add_f32_e32 v23, 1.0, v26
	v_rcp_f32_e32 v23, v23
	v_mul_f32_e32 v22, v27, v22
	v_mul_f32_e32 v26, 0xbfb8aa3b, v28
	v_mul_f32_e32 v27, v22, v19
	v_mul_f32_e32 v19, v32, v23
	v_exp_f32_e32 v26, v26
	v_mul_f32_e32 v19, v19, v24
	v_mul_f32_e32 v23, 0xbfb8aa3b, v33
	v_mul_f32_e32 v24, 0xbfb8aa3b, v29
	v_exp_f32_e32 v23, v23
	v_exp_f32_e32 v24, v24
	v_add_f32_e32 v22, 1.0, v26
	v_rcp_f32_e32 v22, v22
	v_add_f32_e32 v23, 1.0, v23
	v_add_f32_e32 v24, 1.0, v24
	v_rcp_f32_e32 v23, v23
	v_rcp_f32_e32 v24, v24
	v_mul_f32_e32 v22, v28, v22
	v_mul_f32_e32 v26, v22, v20
	v_mul_f32_e32 v20, v33, v23
	v_mul_f32_e32 v22, v29, v24
	v_mul_f32_e32 v20, v20, v25
	v_mul_f32_e32 v21, v22, v21
	v_lshl_add_u64 v[22:23], v[34:35], 0, v[114:115]
	v_cvt_pk_bf16_f32 v18, v30, v18
	v_cvt_pk_bf16_f32 v19, v19, v20
	v_cvt_pk_bf16_f32 v20, v37, v27
	v_cvt_pk_bf16_f32 v21, v26, v21
	global_store_dwordx4 v[22:23], v[18:21], off
	s_nop 1
	v_mul_f32_e32 v18, 0xbfb8aa3b, v14
	v_exp_f32_e32 v18, v18
	v_mul_f32_e32 v19, 0xbfb8aa3b, v10
	v_exp_f32_e32 v19, v19
	v_add_u32_e32 v20, 0xb0, v147
	v_add_f32_e32 v18, 1.0, v18
	v_rcp_f32_e32 v21, v18
	v_add_f32_e32 v18, 1.0, v19
	v_rcp_f32_e32 v22, v18
	v_mad_i64_i32 v[18:19], s[62:63], v20, s90, v[134:135]
	v_mul_f32_e32 v14, v14, v21
	v_mul_f32_e32 v14, v14, v6
	v_mul_f32_e32 v6, v10, v22
	v_mul_f32_e32 v10, 0xbfb8aa3b, v15
	v_exp_f32_e32 v10, v10
	v_mul_f32_e32 v20, 0xbfb8aa3b, v11
	v_mul_f32_e32 v21, v6, v2
	v_exp_f32_e32 v20, v20
	v_add_f32_e32 v2, 1.0, v10
	v_rcp_f32_e32 v2, v2
	v_mul_f32_e32 v10, 0xbfb8aa3b, v16
	v_exp_f32_e32 v10, v10
	v_add_f32_e32 v6, 1.0, v20
	v_mul_f32_e32 v2, v15, v2
	v_rcp_f32_e32 v6, v6
	v_mul_f32_e32 v2, v2, v7
	v_add_f32_e32 v7, 1.0, v10
	v_rcp_f32_e32 v7, v7
	v_mul_f32_e32 v6, v11, v6
	v_mul_f32_e32 v10, 0xbfb8aa3b, v12
	v_mul_f32_e32 v11, v6, v3
	v_mul_f32_e32 v3, v16, v7
	v_exp_f32_e32 v10, v10
	v_mul_f32_e32 v3, v3, v8
	v_mul_f32_e32 v7, 0xbfb8aa3b, v17
	v_mul_f32_e32 v8, 0xbfb8aa3b, v13
	v_exp_f32_e32 v7, v7
	v_exp_f32_e32 v8, v8
	v_add_f32_e32 v6, 1.0, v10
	v_rcp_f32_e32 v6, v6
	v_add_f32_e32 v7, 1.0, v7
	v_add_f32_e32 v8, 1.0, v8
	v_rcp_f32_e32 v7, v7
	v_rcp_f32_e32 v8, v8
	v_mul_f32_e32 v6, v12, v6
	v_mul_f32_e32 v10, v6, v4
	v_mul_f32_e32 v4, v17, v7
	v_mul_f32_e32 v6, v13, v8
	v_mul_f32_e32 v4, v4, v9
	v_mul_f32_e32 v5, v6, v5
	v_lshl_add_u64 v[6:7], v[18:19], 0, v[114:115]
	s_mov_b64 s[62:63], s[16:17]
	v_cvt_pk_bf16_f32 v2, v14, v2
	v_cvt_pk_bf16_f32 v3, v3, v4
	v_cvt_pk_bf16_f32 v4, v21, v11
	v_cvt_pk_bf16_f32 v5, v10, v5
	global_store_dwordx4 v[6:7], v[2:5], off
	s_cbranch_vccz .LBB0_135
	s_waitcnt vmcnt(0)
	s_cmpk_gt_u32 s3, 0xff
	s_cbranch_scc1 .LBB0_142
	s_barrier

; #define PG8_STAGE(bufoff, gbase, voff) do { _Pragma("unroll") for (int _i = 0; _i < 2; ++_i) \
;         asm volatile("s_mov_b32 m0, %2\n\ts_nop 0\n\tglobal_load_lds_dwordx4 %0, %1" :: "v"((voff)[_i]), "s"((const char*)(gbase)), "s"(ldsbase + (unsigned)(bufoff) + ldsw + (unsigned)_i * 8192u) : "memory", "m0"); } while (0)
; #define PG8_LDA(dst, b, h) do { _Pragma("unroll") for (int m = 0; m < 4; ++m) _Pragma("unroll") for (int k = 0; k < 2; ++k) dst[m][k] = *(const PG8_LAS bf16x8*)(lds + PG8_SA(b, h) + aoff + m * 2048 + k * 1024); } while (0)
; #define PG8_WAIT_V(n) asm volatile("s_waitcnt vmcnt(" #n ")" ::: "memory")
; template <class Epi, class Sched, bool ALIGN_EPI = false, bool SP2 = false>
; __device__ __forceinline__ void gemm_phase(PG8_LAS unsigned char* lds, const Gemm g, const Sched& S, const Epi& E) {
;     ...
;             const bool last = (t == nt - 2);
;             const char* a1 = cA + (size_t)(t + 1) * kstep;
;             const char* a2 = last ? nA : cA + (size_t)(t + 2) * kstep; const char* b2 = last ? nB : cB + (size_t)(t + 2) * kstep;
;             const char* a3 = a2 + kstep; const char* b3 = b2 + kstep;
;             if (last && has_next) S.a_ready(nxt);
;             if constexpr (epi_has_mid<Epi>::value) { if (t == Epi::MID_T) E.mid(acc, cur, wr, wc, fr, fq); }
;             if constexpr (SP2) {
;             PG8_LDB(B0, 0, 0); PG8_LDB(B1, 0, 1); PG8_SCHED; PG8_LDA(At, 0, 0); PG8_STAGE(PG8_SA(1, 1), a1 + hstep, voffA);
;             PG8_WAIT_V(8); PG8_WAIT_L(0); PG8_BAR; PG8_MMA(0, 0, At, B0); PG8_MMA(0, 1, At, B1); PG8_BAR; PG8_SCHED;
;             PG8_LDA(At, 0, 1); PG8_STAGE(PG8_SB(0, 0), b2, voffB); PG8_STAGE(PG8_SB(0, 1), b2 + hstep, voffB); PG8_STAGE(PG8_SA(0, 0), a2, voffA);
;             PG8_WAIT_V(8); PG8_WAIT_L(0); PG8_BAR; PG8_MMA(1, 0, At, B0); PG8_MMA(1, 1, At, B1); PG8_BAR; PG8_SCHED;
;             PG8_LDB(B0, 1, 0); PG8_LDB(B1, 1, 1); PG8_SCHED; PG8_LDA(At, 1, 0); PG8_STAGE(PG8_SA(0, 1), a2 + hstep, voffA);
;             PG8_WAIT_V(8); PG8_WAIT_L(0); PG8_BAR; PG8_MMA(0, 0, At, B0); PG8_MMA(0, 1, At, B1); PG8_BAR; PG8_SCHED;
;             PG8_LDA(At, 1, 1); PG8_STAGE(PG8_SB(1, 0), b3, voffB); PG8_STAGE(PG8_SB(1, 1), b3 + hstep, voffB); PG8_STAGE(PG8_SA(1, 0), a3, voffA);
;             PG8_WAIT_V(8); PG8_WAIT_L(0); PG8_BAR; PG8_MMA(1, 0, At, B0); PG8_MMA(1, 1, At, B1); PG8_BAR; PG8_SCHED;
.LBB0_234:
	ds_read_b128 v[134:137], v145
	ds_read_b128 v[152:155], v145 offset:1024
	ds_read_b128 v[156:159], v145 offset:2048
	ds_read_b128 v[160:163], v145 offset:3072
	ds_read_b128 v[164:167], v146
	ds_read_b128 v[168:171], v146 offset:1024
	ds_read_b128 v[172:175], v146 offset:2048
	ds_read_b128 v[176:179], v146 offset:3072
	s_cmpk_eq_i32 s57, 0xa8
	s_cselect_b32 s76, s4, s53
	s_cselect_b32 s77, s5, s54
	s_cselect_b32 s66, s46, s55
	s_cselect_b32 s67, s47, s56
	s_add_u32 s62, s76, 0x80
	s_addc_u32 s63, s77, 0
	ds_read_b128 v[180:183], v147
	ds_read_b128 v[184:187], v147 offset:1024
	ds_read_b128 v[188:191], v147 offset:2048
	ds_read_b128 v[192:195], v147 offset:3072
	ds_read_b128 v[196:199], v147 offset:4096
	ds_read_b128 v[200:203], v147 offset:5120
	ds_read_b128 v[204:207], v147 offset:6144
	ds_read_b128 v[208:211], v147 offset:7168
	s_mov_b32 m0, s94
	s_nop 0
	global_load_lds_dwordx4 v1, s[50:51]
	s_nop 0
	s_mov_b32 m0, s95
	s_nop 0
	global_load_lds_dwordx4 v141, s[50:51]
	s_waitcnt vmcnt(8)
	s_waitcnt lgkmcnt(0)
	s_barrier
	s_setprio 1
	s_waitcnt lgkmcnt(7)
	v_mfma_f32_16x16x32_bf16 v[126:129], v[134:137], v[180:183], v[126:129]
	v_mfma_f32_16x16x32_bf16 v[122:125], v[156:159], v[180:183], v[122:125]
	s_waitcnt lgkmcnt(5)
	v_mfma_f32_16x16x32_bf16 v[110:113], v[134:137], v[188:191], v[110:113]
	v_mfma_f32_16x16x32_bf16 v[106:109], v[156:159], v[188:191], v[106:109]
	s_waitcnt lgkmcnt(3)
	v_mfma_f32_16x16x32_bf16 v[94:97], v[134:137], v[196:199], v[94:97]
	v_mfma_f32_16x16x32_bf16 v[90:93], v[156:159], v[196:199], v[90:93]
	s_waitcnt lgkmcnt(1)
	v_mfma_f32_16x16x32_bf16 v[78:81], v[134:137], v[204:207], v[78:81]
	v_mfma_f32_16x16x32_bf16 v[74:77], v[156:159], v[204:207], v[74:77]
	v_mfma_f32_16x16x32_bf16 v[126:129], v[152:155], v[184:187], v[126:129]
	v_mfma_f32_16x16x32_bf16 v[122:125], v[160:163], v[184:187], v[122:125]
	v_mfma_f32_16x16x32_bf16 v[110:113], v[152:155], v[192:195], v[110:113]
	v_mfma_f32_16x16x32_bf16 v[106:109], v[160:163], v[192:195], v[106:109]
	v_mfma_f32_16x16x32_bf16 v[94:97], v[152:155], v[200:203], v[94:97]
	v_mfma_f32_16x16x32_bf16 v[90:93], v[160:163], v[200:203], v[90:93]
	s_waitcnt lgkmcnt(0)
	v_mfma_f32_16x16x32_bf16 v[78:81], v[152:155], v[208:211], v[78:81]
	v_mfma_f32_16x16x32_bf16 v[74:77], v[160:163], v[208:211], v[74:77]
	s_setprio 0
	s_setprio 1
	v_mfma_f32_16x16x32_bf16 v[118:121], v[164:167], v[180:183], v[118:121]
	v_mfma_f32_16x16x32_bf16 v[114:117], v[172:175], v[180:183], v[114:117]
	v_mfma_f32_16x16x32_bf16 v[102:105], v[164:167], v[188:191], v[102:105]
	v_mfma_f32_16x16x32_bf16 v[98:101], v[172:175], v[188:191], v[98:101]
	v_mfma_f32_16x16x32_bf16 v[86:89], v[164:167], v[196:199], v[86:89]
	v_mfma_f32_16x16x32_bf16 v[82:85], v[172:175], v[196:199], v[82:85]
	v_mfma_f32_16x16x32_bf16 v[70:73], v[164:167], v[204:207], v[70:73]
	v_mfma_f32_16x16x32_bf16 v[66:69], v[172:175], v[204:207], v[66:69]
	v_mfma_f32_16x16x32_bf16 v[118:121], v[168:171], v[184:187], v[118:121]
	v_mfma_f32_16x16x32_bf16 v[114:117], v[176:179], v[184:187], v[114:117]
	v_mfma_f32_16x16x32_bf16 v[102:105], v[168:171], v[192:195], v[102:105]
	v_mfma_f32_16x16x32_bf16 v[98:101], v[176:179], v[192:195], v[98:101]
	v_mfma_f32_16x16x32_bf16 v[86:89], v[168:171], v[200:203], v[86:89]
	v_mfma_f32_16x16x32_bf16 v[82:85], v[176:179], v[200:203], v[82:85]
	s_setprio 2
	s_barrier
	ds_read_b128 v[180:183], v147 offset:16384
	ds_read_b128 v[184:187], v147 offset:17408
	ds_read_b128 v[188:191], v147 offset:18432
	ds_read_b128 v[192:195], v147 offset:19456
	ds_read_b128 v[196:199], v147 offset:20480
	ds_read_b128 v[200:203], v147 offset:21504
	ds_read_b128 v[204:207], v147 offset:22528
	v_mfma_f32_16x16x32_bf16 v[70:73], v[168:171], v[208:211], v[70:73]
	v_mfma_f32_16x16x32_bf16 v[66:69], v[176:179], v[208:211], v[66:69]
	s_setprio 0
	ds_read_b128 v[208:211], v147 offset:23552
	s_mov_b32 m0, s64
	s_nop 0
	global_load_lds_dwordx4 v140, s[66:67]
	s_add_u32 s58, s66, 0x2b0000
	s_mov_b32 m0, s65
	s_nop 0
	global_load_lds_dwordx4 v142, s[66:67]
	s_addc_u32 s59, s67, 0
	s_mov_b32 m0, s82
	s_nop 0
	global_load_lds_dwordx4 v140, s[58:59]
	s_nop 0
	s_mov_b32 m0, s83
	s_nop 0
	global_load_lds_dwordx4 v142, s[58:59]
	s_nop 0
	s_mov_b32 m0, s35
	s_nop 0
	global_load_lds_dwordx4 v1, s[76:77]
	s_nop 0
	s_mov_b32 m0, s84
	s_nop 0
	global_load_lds_dwordx4 v141, s[76:77]
	s_waitcnt vmcnt(8)
	s_waitcnt lgkmcnt(0)
	s_barrier
	s_setprio 1
	s_waitcnt lgkmcnt(7)
	v_mfma_f32_16x16x32_bf16 v[62:65], v[134:137], v[180:183], v[62:65]
	v_mfma_f32_16x16x32_bf16 v[58:61], v[156:159], v[180:183], v[58:61]
	s_waitcnt lgkmcnt(5)
	v_mfma_f32_16x16x32_bf16 v[46:49], v[134:137], v[188:191], v[46:49]
	v_mfma_f32_16x16x32_bf16 v[42:45], v[156:159], v[188:191], v[42:45]
	s_waitcnt lgkmcnt(3)
	v_mfma_f32_16x16x32_bf16 v[30:33], v[134:137], v[196:199], v[30:33]
	v_mfma_f32_16x16x32_bf16 v[26:29], v[156:159], v[196:199], v[26:29]
	s_waitcnt lgkmcnt(1)
	v_mfma_f32_16x16x32_bf16 v[14:17], v[134:137], v[204:207], v[14:17]
	v_mfma_f32_16x16x32_bf16 v[10:13], v[156:159], v[204:207], v[10:13]
	v_mfma_f32_16x16x32_bf16 v[62:65], v[152:155], v[184:187], v[62:65]
	v_mfma_f32_16x16x32_bf16 v[58:61], v[160:163], v[184:187], v[58:61]
	v_mfma_f32_16x16x32_bf16 v[46:49], v[152:155], v[192:195], v[46:49]
	v_mfma_f32_16x16x32_bf16 v[42:45], v[160:163], v[192:195], v[42:45]
	v_mfma_f32_16x16x32_bf16 v[30:33], v[152:155], v[200:203], v[30:33]
	v_mfma_f32_16x16x32_bf16 v[26:29], v[160:163], v[200:203], v[26:29]
	s_waitcnt lgkmcnt(0)
	v_mfma_f32_16x16x32_bf16 v[14:17], v[152:155], v[208:211], v[14:17]
	v_mfma_f32_16x16x32_bf16 v[10:13], v[160:163], v[208:211], v[10:13]
	s_setprio 0
	s_setprio 1
	v_mfma_f32_16x16x32_bf16 v[54:57], v[164:167], v[180:183], v[54:57]
	v_mfma_f32_16x16x32_bf16 v[50:53], v[172:175], v[180:183], v[50:53]
	v_mfma_f32_16x16x32_bf16 v[38:41], v[164:167], v[188:191], v[38:41]
	v_mfma_f32_16x16x32_bf16 v[34:37], v[172:175], v[188:191], v[34:37]
	v_mfma_f32_16x16x32_bf16 v[22:25], v[164:167], v[196:199], v[22:25]
	v_mfma_f32_16x16x32_bf16 v[18:21], v[172:175], v[196:199], v[18:21]
	v_mfma_f32_16x16x32_bf16 v[6:9], v[164:167], v[204:207], v[6:9]
	v_mfma_f32_16x16x32_bf16 v[2:5], v[172:175], v[204:207], v[2:5]
	v_mfma_f32_16x16x32_bf16 v[54:57], v[168:171], v[184:187], v[54:57]
	v_mfma_f32_16x16x32_bf16 v[50:53], v[176:179], v[184:187], v[50:53]
	v_mfma_f32_16x16x32_bf16 v[38:41], v[168:171], v[192:195], v[38:41]
	v_mfma_f32_16x16x32_bf16 v[34:37], v[176:179], v[192:195], v[34:37]
	v_mfma_f32_16x16x32_bf16 v[22:25], v[168:171], v[200:203], v[22:25]
	v_mfma_f32_16x16x32_bf16 v[18:21], v[176:179], v[200:203], v[18:21]
	s_setprio 2
	s_barrier
; #define PG8_STAGE(bufoff, gbase, voff) do { _Pragma("unroll") for (int _i = 0; _i < 2; ++_i) \
;         asm volatile("s_mov_b32 m0, %2\n\ts_nop 0\n\tglobal_load_lds_dwordx4 %0, %1" :: "v"((voff)[_i]), "s"((const char*)(gbase)), "s"(ldsbase + (unsigned)(bufoff) + ldsw + (unsigned)_i * 8192u) : "memory", "m0"); } while (0)
; #define PG8_LDA(dst, b, h) do { _Pragma("unroll") for (int m = 0; m < 4; ++m) _Pragma("unroll") for (int k = 0; k < 2; ++k) dst[m][k] = *(const PG8_LAS bf16x8*)(lds + PG8_SA(b, h) + aoff + m * 2048 + k * 1024); } while (0)
; #define PG8_LDB(dst, b, h) do { _Pragma("unroll") for (int n = 0; n < 2; ++n) _Pragma("unroll") for (int k = 0; k < 2; ++k) dst[n][k] = *(const PG8_LAS bf16x8*)(lds + PG8_SB(b, h) + boff + n * 2048 + k * 1024); } while (0)
; #define PG8_MMA(ai, bj, At, Bt) do { __builtin_amdgcn_s_setprio(1); _Pragma("unroll") for (int m = 0; m < 4; ++m) _Pragma("unroll") for (int n = 0; n < 2; ++n) _Pragma("unroll") for (int k = 0; k < 2; ++k) \
;         acc[ai][bj][m][n] = __builtin_amdgcn_mfma_f32_16x16x32_bf16(Bt[n][k], At[m][k], acc[ai][bj][m][n], 0, 0, 0); __builtin_amdgcn_s_setprio(0); } while (0)
; template <class Epi, class Sched, bool ALIGN_EPI = false, bool SP2 = false>
; __device__ __forceinline__ void gemm_phase(PG8_LAS unsigned char* lds, const Gemm g, const Sched& S, const Epi& E) {
;     ...
;             PG8_LDB(B0, 0, 0); PG8_LDB(B1, 0, 1); PG8_SCHED; PG8_LDA(At, 0, 0); PG8_STAGE(PG8_SA(1, 1), a1 + hstep, voffA);
;             PG8_WAIT_V(8); PG8_WAIT_L(0); PG8_BAR; PG8_MMA(0, 0, At, B0); PG8_MMA(0, 1, At, B1); PG8_BAR; PG8_SCHED;
;             PG8_LDA(At, 0, 1); PG8_STAGE(PG8_SB(0, 0), b2, voffB); PG8_STAGE(PG8_SB(0, 1), b2 + hstep, voffB); PG8_STAGE(PG8_SA(0, 0), a2, voffA);
;             PG8_WAIT_V(8); PG8_WAIT_L(0); PG8_BAR; PG8_MMA(1, 0, At, B0); PG8_MMA(1, 1, At, B1); PG8_BAR; PG8_SCHED;
;             PG8_LDB(B0, 1, 0); PG8_LDB(B1, 1, 1); PG8_SCHED; PG8_LDA(At, 1, 0); PG8_STAGE(PG8_SA(0, 1), a2 + hstep, voffA);
;             PG8_WAIT_V(8); PG8_WAIT_L(0); PG8_BAR; PG8_MMA(0, 0, At, B0); PG8_MMA(0, 1, At, B1); PG8_BAR; PG8_SCHED;
;             PG8_LDA(At, 1, 1); PG8_STAGE(PG8_SB(1, 0), b3, voffB); PG8_STAGE(PG8_SB(1, 1), b3 + hstep, voffB); PG8_STAGE(PG8_SA(1, 0), a3, voffA);
;             PG8_WAIT_V(8); PG8_WAIT_L(0); PG8_BAR; PG8_MMA(1, 0, At, B0); PG8_MMA(1, 1, At, B1); PG8_BAR; PG8_SCHED;
	ds_read_b128 v[134:137], v148
	ds_read_b128 v[152:155], v148 offset:1024
	ds_read_b128 v[156:159], v148 offset:2048
	ds_read_b128 v[160:163], v148 offset:3072
	ds_read_b128 v[164:167], v149
	v_mfma_f32_16x16x32_bf16 v[6:9], v[168:171], v[208:211], v[6:9]
	v_mfma_f32_16x16x32_bf16 v[2:5], v[176:179], v[208:211], v[2:5]
	s_setprio 0
	ds_read_b128 v[168:171], v149 offset:1024
	ds_read_b128 v[172:175], v149 offset:2048
	ds_read_b128 v[176:179], v149 offset:3072
	ds_read_b128 v[180:183], v147 offset:32768
	ds_read_b128 v[184:187], v147 offset:33792
	ds_read_b128 v[188:191], v147 offset:34816
	ds_read_b128 v[192:195], v147 offset:35840
	ds_read_b128 v[196:199], v147 offset:36864
	ds_read_b128 v[200:203], v147 offset:37888
	ds_read_b128 v[204:207], v147 offset:38912
	ds_read_b128 v[208:211], v147 offset:39936
	s_add_u32 s58, s76, 0x2b0000
	s_addc_u32 s59, s77, 0
	s_mov_b32 m0, s85
	s_nop 0
	global_load_lds_dwordx4 v1, s[58:59]
	s_nop 0
	s_mov_b32 m0, s86
	s_nop 0
	global_load_lds_dwordx4 v141, s[58:59]
	s_waitcnt vmcnt(8)
	s_waitcnt lgkmcnt(0)
	s_barrier
	s_setprio 1
	s_waitcnt lgkmcnt(7)
	v_mfma_f32_16x16x32_bf16 v[126:129], v[134:137], v[180:183], v[126:129]
	v_mfma_f32_16x16x32_bf16 v[122:125], v[156:159], v[180:183], v[122:125]
	s_waitcnt lgkmcnt(5)
	v_mfma_f32_16x16x32_bf16 v[110:113], v[134:137], v[188:191], v[110:113]
	v_mfma_f32_16x16x32_bf16 v[106:109], v[156:159], v[188:191], v[106:109]
	s_waitcnt lgkmcnt(3)
	v_mfma_f32_16x16x32_bf16 v[94:97], v[134:137], v[196:199], v[94:97]
	v_mfma_f32_16x16x32_bf16 v[90:93], v[156:159], v[196:199], v[90:93]
	s_waitcnt lgkmcnt(1)
	v_mfma_f32_16x16x32_bf16 v[78:81], v[134:137], v[204:207], v[78:81]
	v_mfma_f32_16x16x32_bf16 v[74:77], v[156:159], v[204:207], v[74:77]
	v_mfma_f32_16x16x32_bf16 v[126:129], v[152:155], v[184:187], v[126:129]
	v_mfma_f32_16x16x32_bf16 v[122:125], v[160:163], v[184:187], v[122:125]
	v_mfma_f32_16x16x32_bf16 v[110:113], v[152:155], v[192:195], v[110:113]
	v_mfma_f32_16x16x32_bf16 v[106:109], v[160:163], v[192:195], v[106:109]
	v_mfma_f32_16x16x32_bf16 v[94:97], v[152:155], v[200:203], v[94:97]
	v_mfma_f32_16x16x32_bf16 v[90:93], v[160:163], v[200:203], v[90:93]
	s_waitcnt lgkmcnt(0)
	v_mfma_f32_16x16x32_bf16 v[78:81], v[152:155], v[208:211], v[78:81]
	v_mfma_f32_16x16x32_bf16 v[74:77], v[160:163], v[208:211], v[74:77]
	s_setprio 0
	s_setprio 1
	v_mfma_f32_16x16x32_bf16 v[118:121], v[164:167], v[180:183], v[118:121]
	v_mfma_f32_16x16x32_bf16 v[114:117], v[172:175], v[180:183], v[114:117]
	v_mfma_f32_16x16x32_bf16 v[102:105], v[164:167], v[188:191], v[102:105]
	v_mfma_f32_16x16x32_bf16 v[98:101], v[172:175], v[188:191], v[98:101]
	v_mfma_f32_16x16x32_bf16 v[86:89], v[164:167], v[196:199], v[86:89]
	v_mfma_f32_16x16x32_bf16 v[82:85], v[172:175], v[196:199], v[82:85]
	v_mfma_f32_16x16x32_bf16 v[70:73], v[164:167], v[204:207], v[70:73]
	v_mfma_f32_16x16x32_bf16 v[66:69], v[172:175], v[204:207], v[66:69]
	v_mfma_f32_16x16x32_bf16 v[118:121], v[168:171], v[184:187], v[118:121]
	v_mfma_f32_16x16x32_bf16 v[114:117], v[176:179], v[184:187], v[114:117]
	v_mfma_f32_16x16x32_bf16 v[102:105], v[168:171], v[192:195], v[102:105]
	v_mfma_f32_16x16x32_bf16 v[98:101], v[176:179], v[192:195], v[98:101]
	v_mfma_f32_16x16x32_bf16 v[86:89], v[168:171], v[200:203], v[86:89]
	v_mfma_f32_16x16x32_bf16 v[82:85], v[176:179], v[200:203], v[82:85]
	s_setprio 2
	s_barrier
; #define PG8_STAGE(bufoff, gbase, voff) do { _Pragma("unroll") for (int _i = 0; _i < 2; ++_i) \
;         asm volatile("s_mov_b32 m0, %2\n\ts_nop 0\n\tglobal_load_lds_dwordx4 %0, %1" :: "v"((voff)[_i]), "s"((const char*)(gbase)), "s"(ldsbase + (unsigned)(bufoff) + ldsw + (unsigned)_i * 8192u) : "memory", "m0"); } while (0)
; #define PG8_LDA(dst, b, h) do { _Pragma("unroll") for (int m = 0; m < 4; ++m) _Pragma("unroll") for (int k = 0; k < 2; ++k) dst[m][k] = *(const PG8_LAS bf16x8*)(lds + PG8_SA(b, h) + aoff + m * 2048 + k * 1024); } while (0)
; #define PG8_BAR __builtin_amdgcn_s_barrier()
; template <class Epi, class Sched, bool ALIGN_EPI = false, bool SP2 = false>
; __device__ __forceinline__ void gemm_phase(PG8_LAS unsigned char* lds, const Gemm g, const Sched& S, const Epi& E) {
;     ...
;         for (int t = 0; t < nt; t += 2) {
;             const bool last = (t == nt - 2);
;             const char* a1 = cA + (size_t)(t + 1) * kstep;
;             const char* a2 = last ? nA : cA + (size_t)(t + 2) * kstep; const char* b2 = last ? nB : cB + (size_t)(t + 2) * kstep;
;             const char* a3 = a2 + kstep; const char* b3 = b2 + kstep;
;             if (last && has_next) S.a_ready(nxt);
;             if constexpr (epi_has_mid<Epi>::value) { if (t == Epi::MID_T) E.mid(acc, cur, wr, wc, fr, fq); }
;             if constexpr (SP2) {
;             PG8_LDB(B0, 0, 0); PG8_LDB(B1, 0, 1); PG8_SCHED; PG8_LDA(At, 0, 0); PG8_STAGE(PG8_SA(1, 1), a1 + hstep, voffA);
;             PG8_WAIT_V(8); PG8_WAIT_L(0); PG8_BAR; PG8_MMA(0, 0, At, B0); PG8_MMA(0, 1, At, B1); PG8_BAR; PG8_SCHED;
;             PG8_LDA(At, 0, 1); PG8_STAGE(PG8_SB(0, 0), b2, voffB); PG8_STAGE(PG8_SB(0, 1), b2 + hstep, voffB); PG8_STAGE(PG8_SA(0, 0), a2, voffA);
;             PG8_WAIT_V(8); PG8_WAIT_L(0); PG8_BAR; PG8_MMA(1, 0, At, B0); PG8_MMA(1, 1, At, B1); PG8_BAR; PG8_SCHED;
;             PG8_LDB(B0, 1, 0); PG8_LDB(B1, 1, 1); PG8_SCHED; PG8_LDA(At, 1, 0); PG8_STAGE(PG8_SA(0, 1), a2 + hstep, voffA);
;             PG8_WAIT_V(8); PG8_WAIT_L(0); PG8_BAR; PG8_MMA(0, 0, At, B0); PG8_MMA(0, 1, At, B1); PG8_BAR; PG8_SCHED;
;             PG8_LDA(At, 1, 1); PG8_STAGE(PG8_SB(1, 0), b3, voffB); PG8_STAGE(PG8_SB(1, 1), b3 + hstep, voffB); PG8_STAGE(PG8_SA(1, 0), a3, voffA);
;             PG8_WAIT_V(8); PG8_WAIT_L(0); PG8_BAR; PG8_MMA(1, 0, At, B0); PG8_MMA(1, 1, At, B1); PG8_BAR; PG8_SCHED;
	ds_read_b128 v[180:183], v147 offset:49152
	ds_read_b128 v[184:187], v147 offset:50176
	ds_read_b128 v[188:191], v147 offset:51200
	ds_read_b128 v[192:195], v147 offset:52224
	ds_read_b128 v[196:199], v147 offset:53248
	ds_read_b128 v[200:203], v147 offset:54272
	ds_read_b128 v[204:207], v147 offset:55296
	v_mfma_f32_16x16x32_bf16 v[70:73], v[168:171], v[208:211], v[70:73]
	v_mfma_f32_16x16x32_bf16 v[66:69], v[176:179], v[208:211], v[66:69]
	s_setprio 0
	ds_read_b128 v[208:211], v147 offset:56320
	s_add_u32 s58, s66, 0x80
	s_addc_u32 s59, s67, 0
	s_mov_b32 m0, s88
	s_nop 0
	global_load_lds_dwordx4 v140, s[58:59]
	s_nop 0
	s_mov_b32 m0, s89
	s_nop 0
	global_load_lds_dwordx4 v142, s[58:59]
	s_add_u32 s58, s66, 0x2b0080
	s_addc_u32 s59, s67, 0
	s_mov_b32 m0, s92
	s_nop 0
	global_load_lds_dwordx4 v140, s[58:59]
	s_nop 0
	s_mov_b32 m0, s93
	s_nop 0
	global_load_lds_dwordx4 v142, s[58:59]
	s_nop 0
	s_mov_b32 m0, s90
	s_nop 0
	global_load_lds_dwordx4 v1, s[62:63]
	s_nop 0
	s_mov_b32 m0, s91
	s_nop 0
	global_load_lds_dwordx4 v141, s[62:63]
	s_waitcnt vmcnt(8)
	s_waitcnt lgkmcnt(0)
	s_barrier
	s_setprio 1
	s_waitcnt lgkmcnt(7)
	v_mfma_f32_16x16x32_bf16 v[62:65], v[134:137], v[180:183], v[62:65]
	v_mfma_f32_16x16x32_bf16 v[58:61], v[156:159], v[180:183], v[58:61]
	s_waitcnt lgkmcnt(5)
	v_mfma_f32_16x16x32_bf16 v[46:49], v[134:137], v[188:191], v[46:49]
	v_mfma_f32_16x16x32_bf16 v[42:45], v[156:159], v[188:191], v[42:45]
	s_waitcnt lgkmcnt(3)
	v_mfma_f32_16x16x32_bf16 v[30:33], v[134:137], v[196:199], v[30:33]
	v_mfma_f32_16x16x32_bf16 v[26:29], v[156:159], v[196:199], v[26:29]
	s_waitcnt lgkmcnt(1)
	v_mfma_f32_16x16x32_bf16 v[14:17], v[134:137], v[204:207], v[14:17]
	v_mfma_f32_16x16x32_bf16 v[10:13], v[156:159], v[204:207], v[10:13]
	v_mfma_f32_16x16x32_bf16 v[62:65], v[152:155], v[184:187], v[62:65]
	v_mfma_f32_16x16x32_bf16 v[58:61], v[160:163], v[184:187], v[58:61]
	v_mfma_f32_16x16x32_bf16 v[46:49], v[152:155], v[192:195], v[46:49]
	v_mfma_f32_16x16x32_bf16 v[42:45], v[160:163], v[192:195], v[42:45]
	v_mfma_f32_16x16x32_bf16 v[30:33], v[152:155], v[200:203], v[30:33]
	v_mfma_f32_16x16x32_bf16 v[26:29], v[160:163], v[200:203], v[26:29]
	s_waitcnt lgkmcnt(0)
	v_mfma_f32_16x16x32_bf16 v[14:17], v[152:155], v[208:211], v[14:17]
	v_mfma_f32_16x16x32_bf16 v[10:13], v[160:163], v[208:211], v[10:13]
	s_setprio 0
	s_setprio 1
	v_mfma_f32_16x16x32_bf16 v[54:57], v[164:167], v[180:183], v[54:57]
	v_mfma_f32_16x16x32_bf16 v[50:53], v[172:175], v[180:183], v[50:53]
	v_mfma_f32_16x16x32_bf16 v[38:41], v[164:167], v[188:191], v[38:41]
	v_mfma_f32_16x16x32_bf16 v[34:37], v[172:175], v[188:191], v[34:37]
	v_mfma_f32_16x16x32_bf16 v[22:25], v[164:167], v[196:199], v[22:25]
	v_mfma_f32_16x16x32_bf16 v[18:21], v[172:175], v[196:199], v[18:21]
	v_mfma_f32_16x16x32_bf16 v[6:9], v[164:167], v[204:207], v[6:9]
	v_mfma_f32_16x16x32_bf16 v[2:5], v[172:175], v[204:207], v[2:5]
	v_mfma_f32_16x16x32_bf16 v[54:57], v[168:171], v[184:187], v[54:57]
	v_mfma_f32_16x16x32_bf16 v[50:53], v[176:179], v[184:187], v[50:53]
	v_mfma_f32_16x16x32_bf16 v[38:41], v[168:171], v[192:195], v[38:41]
	v_mfma_f32_16x16x32_bf16 v[34:37], v[176:179], v[192:195], v[34:37]
	v_mfma_f32_16x16x32_bf16 v[22:25], v[168:171], v[200:203], v[22:25]
	v_mfma_f32_16x16x32_bf16 v[18:21], v[176:179], v[200:203], v[18:21]
	v_mfma_f32_16x16x32_bf16 v[6:9], v[168:171], v[208:211], v[6:9]
	s_setprio 2
	s_barrier
	v_mfma_f32_16x16x32_bf16 v[2:5], v[176:179], v[208:211], v[2:5]
	s_setprio 0
	s_add_i32 s57, s57, 2
	s_add_u32 s53, s53, 0x100
	s_addc_u32 s54, s54, 0
	s_add_u32 s55, s55, 0x100
	s_addc_u32 s56, s56, 0
	s_add_u32 s50, s50, 0x100
	s_addc_u32 s51, s51, 0
	s_cmpk_gt_u32 s57, 0xa9
	s_cbranch_scc0 .LBB0_234
	s_and_b64 vcc, exec, s[16:17]
	s_cbranch_vccz .LBB0_237
	s_barrier

; #define PG8_STAGE(bufoff, gbase, voff) do { _Pragma("unroll") for (int _i = 0; _i < 2; ++_i) \
;         asm volatile("s_mov_b32 m0, %2\n\ts_nop 0\n\tglobal_load_lds_dwordx4 %0, %1" :: "v"((voff)[_i]), "s"((const char*)(gbase)), "s"(ldsbase + (unsigned)(bufoff) + ldsw + (unsigned)_i * 8192u) : "memory", "m0"); } while (0)
; #define PG8_LDA(dst, b, h) do { _Pragma("unroll") for (int m = 0; m < 4; ++m) _Pragma("unroll") for (int k = 0; k < 2; ++k) dst[m][k] = *(const PG8_LAS bf16x8*)(lds + PG8_SA(b, h) + aoff + m * 2048 + k * 1024); } while (0)
; #define PG8_WAIT_V(n) asm volatile("s_waitcnt vmcnt(" #n ")" ::: "memory")
; template <class Epi, class Sched, bool ALIGN_EPI = false, bool SP2 = false>
; __device__ __forceinline__ void gemm_phase(PG8_LAS unsigned char* lds, const Gemm g, const Sched& S, const Epi& E) {
;     ...
;             const bool last = (t == nt - 2);
;             const char* a1 = cA + (size_t)(t + 1) * kstep;
;             const char* a2 = last ? nA : cA + (size_t)(t + 2) * kstep; const char* b2 = last ? nB : cB + (size_t)(t + 2) * kstep;
;             const char* a3 = a2 + kstep; const char* b3 = b2 + kstep;
;             if (last && has_next) S.a_ready(nxt);
;             if constexpr (epi_has_mid<Epi>::value) { if (t == Epi::MID_T) E.mid(acc, cur, wr, wc, fr, fq); }
;             if constexpr (SP2) {
;             PG8_LDB(B0, 0, 0); PG8_LDB(B1, 0, 1); PG8_SCHED; PG8_LDA(At, 0, 0); PG8_STAGE(PG8_SA(1, 1), a1 + hstep, voffA);
;             PG8_WAIT_V(8); PG8_WAIT_L(0); PG8_BAR; PG8_MMA(0, 0, At, B0); PG8_MMA(0, 1, At, B1); PG8_BAR; PG8_SCHED;
;             PG8_LDA(At, 0, 1); PG8_STAGE(PG8_SB(0, 0), b2, voffB); PG8_STAGE(PG8_SB(0, 1), b2 + hstep, voffB); PG8_STAGE(PG8_SA(0, 0), a2, voffA);
;             PG8_WAIT_V(8); PG8_WAIT_L(0); PG8_BAR; PG8_MMA(1, 0, At, B0); PG8_MMA(1, 1, At, B1); PG8_BAR; PG8_SCHED;
;             PG8_LDB(B0, 1, 0); PG8_LDB(B1, 1, 1); PG8_SCHED; PG8_LDA(At, 1, 0); PG8_STAGE(PG8_SA(0, 1), a2 + hstep, voffA);
;             PG8_WAIT_V(8); PG8_WAIT_L(0); PG8_BAR; PG8_MMA(0, 0, At, B0); PG8_MMA(0, 1, At, B1); PG8_BAR; PG8_SCHED;
;             PG8_LDA(At, 1, 1); PG8_STAGE(PG8_SB(1, 0), b3, voffB); PG8_STAGE(PG8_SB(1, 1), b3 + hstep, voffB); PG8_STAGE(PG8_SA(1, 0), a3, voffA);
;             PG8_WAIT_V(8); PG8_WAIT_L(0); PG8_BAR; PG8_MMA(1, 0, At, B0); PG8_MMA(1, 1, At, B1); PG8_BAR; PG8_SCHED;
.LBB0_325:
	v_add_u32_e32 v138, 0x10000, v151
	ds_read_b128 v[154:157], v138
	ds_read_b128 v[158:161], v138 offset:1024
	ds_read_b128 v[162:165], v138 offset:2048
	ds_read_b128 v[166:169], v138 offset:3072
	v_add_u32_e32 v138, 0x14000, v151
	s_add_u32 s8, s82, 0x100
	ds_read_b128 v[170:173], v138
	ds_read_b128 v[174:177], v138 offset:1024
	ds_read_b128 v[178:181], v138 offset:2048
	ds_read_b128 v[182:185], v138 offset:3072
	s_addc_u32 s9, s83, 0
	s_and_b64 s[60:61], s[62:63], exec
	s_cselect_b32 s84, s54, s8
	s_cselect_b32 s85, s19, s9
	s_cselect_b32 s63, s17, s57
	s_cselect_b32 s62, s55, s56
	s_add_u32 s66, s84, 0x80
	s_addc_u32 s67, s85, 0
	s_add_u32 s76, s62, 0x80
	s_addc_u32 s77, s63, 0
	ds_read_b128 v[186:189], v152
	ds_read_b128 v[190:193], v152 offset:1024
	ds_read_b128 v[194:197], v152 offset:2048
	ds_read_b128 v[198:201], v152 offset:3072
	ds_read_b128 v[202:205], v152 offset:4096
	ds_read_b128 v[206:209], v152 offset:5120
	ds_read_b128 v[210:213], v152 offset:6144
	ds_read_b128 v[214:217], v152 offset:7168
	s_add_u32 s60, s82, 0x100080
	s_addc_u32 s61, s83, 0
	s_mov_b32 m0, s97
	s_nop 0
	global_load_lds_dwordx4 v141, s[60:61]
	s_nop 0
	s_mov_b32 m0, s70
	s_nop 0
	global_load_lds_dwordx4 v143, s[60:61]
	s_waitcnt vmcnt(8)
	s_waitcnt lgkmcnt(0)
	s_barrier
	s_setprio 1
	s_waitcnt lgkmcnt(7)
	v_mfma_f32_16x16x32_bf16 v[126:129], v[154:157], v[186:189], v[126:129]
	v_mfma_f32_16x16x32_bf16 v[122:125], v[162:165], v[186:189], v[122:125]
	s_waitcnt lgkmcnt(5)
	v_mfma_f32_16x16x32_bf16 v[110:113], v[154:157], v[194:197], v[110:113]
	v_mfma_f32_16x16x32_bf16 v[106:109], v[162:165], v[194:197], v[106:109]
	s_waitcnt lgkmcnt(3)
	v_mfma_f32_16x16x32_bf16 v[94:97], v[154:157], v[202:205], v[94:97]
	v_mfma_f32_16x16x32_bf16 v[90:93], v[162:165], v[202:205], v[90:93]
	s_waitcnt lgkmcnt(1)
	v_mfma_f32_16x16x32_bf16 v[78:81], v[154:157], v[210:213], v[78:81]
	v_mfma_f32_16x16x32_bf16 v[74:77], v[162:165], v[210:213], v[74:77]
	v_mfma_f32_16x16x32_bf16 v[126:129], v[158:161], v[190:193], v[126:129]
	v_mfma_f32_16x16x32_bf16 v[122:125], v[166:169], v[190:193], v[122:125]
	v_mfma_f32_16x16x32_bf16 v[110:113], v[158:161], v[198:201], v[110:113]
	v_mfma_f32_16x16x32_bf16 v[106:109], v[166:169], v[198:201], v[106:109]
	v_mfma_f32_16x16x32_bf16 v[94:97], v[158:161], v[206:209], v[94:97]
	v_mfma_f32_16x16x32_bf16 v[90:93], v[166:169], v[206:209], v[90:93]
	s_waitcnt lgkmcnt(0)
	v_mfma_f32_16x16x32_bf16 v[78:81], v[158:161], v[214:217], v[78:81]
	v_mfma_f32_16x16x32_bf16 v[74:77], v[166:169], v[214:217], v[74:77]
	s_setprio 0
	s_setprio 1
	v_mfma_f32_16x16x32_bf16 v[118:121], v[170:173], v[186:189], v[118:121]
	v_mfma_f32_16x16x32_bf16 v[114:117], v[178:181], v[186:189], v[114:117]
	v_mfma_f32_16x16x32_bf16 v[102:105], v[170:173], v[194:197], v[102:105]
	v_mfma_f32_16x16x32_bf16 v[98:101], v[178:181], v[194:197], v[98:101]
	v_mfma_f32_16x16x32_bf16 v[86:89], v[170:173], v[202:205], v[86:89]
	v_mfma_f32_16x16x32_bf16 v[82:85], v[178:181], v[202:205], v[82:85]
	v_mfma_f32_16x16x32_bf16 v[70:73], v[170:173], v[210:213], v[70:73]
	v_mfma_f32_16x16x32_bf16 v[66:69], v[178:181], v[210:213], v[66:69]
	v_mfma_f32_16x16x32_bf16 v[118:121], v[174:177], v[190:193], v[118:121]
	v_mfma_f32_16x16x32_bf16 v[114:117], v[182:185], v[190:193], v[114:117]
	v_mfma_f32_16x16x32_bf16 v[102:105], v[174:177], v[198:201], v[102:105]
	v_mfma_f32_16x16x32_bf16 v[98:101], v[182:185], v[198:201], v[98:101]
	v_mfma_f32_16x16x32_bf16 v[86:89], v[174:177], v[206:209], v[86:89]
	v_mfma_f32_16x16x32_bf16 v[82:85], v[182:185], v[206:209], v[82:85]
	s_setprio 2
	s_barrier
	ds_read_b128 v[186:189], v152 offset:16384
	ds_read_b128 v[190:193], v152 offset:17408
	ds_read_b128 v[194:197], v152 offset:18432
	ds_read_b128 v[198:201], v152 offset:19456
	ds_read_b128 v[202:205], v152 offset:20480
	ds_read_b128 v[206:209], v152 offset:21504
	ds_read_b128 v[210:213], v152 offset:22528
	v_mfma_f32_16x16x32_bf16 v[70:73], v[174:177], v[214:217], v[70:73]
	v_mfma_f32_16x16x32_bf16 v[66:69], v[182:185], v[214:217], v[66:69]
	s_setprio 0
	ds_read_b128 v[214:217], v152 offset:23552
	s_mov_b32 m0, s68
	s_nop 0
	global_load_lds_dwordx4 v142, s[62:63]
	s_add_u32 s60, s62, 0x100000
	s_mov_b32 m0, s69
	s_nop 0
	global_load_lds_dwordx4 v144, s[62:63]
	s_addc_u32 s61, s63, 0
	s_mov_b32 m0, s81
	s_nop 0
	global_load_lds_dwordx4 v142, s[60:61]
	s_nop 0
	s_mov_b32 m0, s86
	s_nop 0
	global_load_lds_dwordx4 v144, s[60:61]
	s_nop 0
	s_mov_b32 m0, s65
	s_nop 0
	global_load_lds_dwordx4 v141, s[84:85]
	s_nop 0
	s_mov_b32 m0, s87
	s_nop 0
	global_load_lds_dwordx4 v143, s[84:85]
	s_waitcnt vmcnt(8)
	s_waitcnt lgkmcnt(0)
	s_barrier
; #define PG8_STAGE(bufoff, gbase, voff) do { _Pragma("unroll") for (int _i = 0; _i < 2; ++_i) \
;         asm volatile("s_mov_b32 m0, %2\n\ts_nop 0\n\tglobal_load_lds_dwordx4 %0, %1" :: "v"((voff)[_i]), "s"((const char*)(gbase)), "s"(ldsbase + (unsigned)(bufoff) + ldsw + (unsigned)_i * 8192u) : "memory", "m0"); } while (0)
; #define PG8_LDA(dst, b, h) do { _Pragma("unroll") for (int m = 0; m < 4; ++m) _Pragma("unroll") for (int k = 0; k < 2; ++k) dst[m][k] = *(const PG8_LAS bf16x8*)(lds + PG8_SA(b, h) + aoff + m * 2048 + k * 1024); } while (0)
; #define PG8_LDB(dst, b, h) do { _Pragma("unroll") for (int n = 0; n < 2; ++n) _Pragma("unroll") for (int k = 0; k < 2; ++k) dst[n][k] = *(const PG8_LAS bf16x8*)(lds + PG8_SB(b, h) + boff + n * 2048 + k * 1024); } while (0)
; #define PG8_MMA(ai, bj, At, Bt) do { __builtin_amdgcn_s_setprio(1); _Pragma("unroll") for (int m = 0; m < 4; ++m) _Pragma("unroll") for (int n = 0; n < 2; ++n) _Pragma("unroll") for (int k = 0; k < 2; ++k) \
;         acc[ai][bj][m][n] = __builtin_amdgcn_mfma_f32_16x16x32_bf16(Bt[n][k], At[m][k], acc[ai][bj][m][n], 0, 0, 0); __builtin_amdgcn_s_setprio(0); } while (0)
; template <class Epi, class Sched, bool ALIGN_EPI = false, bool SP2 = false>
; __device__ __forceinline__ void gemm_phase(PG8_LAS unsigned char* lds, const Gemm g, const Sched& S, const Epi& E) {
;     ...
;             PG8_LDB(B0, 0, 0); PG8_LDB(B1, 0, 1); PG8_SCHED; PG8_LDA(At, 0, 0); PG8_STAGE(PG8_SA(1, 1), a1 + hstep, voffA);
;             PG8_WAIT_V(8); PG8_WAIT_L(0); PG8_BAR; PG8_MMA(0, 0, At, B0); PG8_MMA(0, 1, At, B1); PG8_BAR; PG8_SCHED;
;             PG8_LDA(At, 0, 1); PG8_STAGE(PG8_SB(0, 0), b2, voffB); PG8_STAGE(PG8_SB(0, 1), b2 + hstep, voffB); PG8_STAGE(PG8_SA(0, 0), a2, voffA);
;             PG8_WAIT_V(8); PG8_WAIT_L(0); PG8_BAR; PG8_MMA(1, 0, At, B0); PG8_MMA(1, 1, At, B1); PG8_BAR; PG8_SCHED;
;             PG8_LDB(B0, 1, 0); PG8_LDB(B1, 1, 1); PG8_SCHED; PG8_LDA(At, 1, 0); PG8_STAGE(PG8_SA(0, 1), a2 + hstep, voffA);
;             PG8_WAIT_V(8); PG8_WAIT_L(0); PG8_BAR; PG8_MMA(0, 0, At, B0); PG8_MMA(0, 1, At, B1); PG8_BAR; PG8_SCHED;
;             PG8_LDA(At, 1, 1); PG8_STAGE(PG8_SB(1, 0), b3, voffB); PG8_STAGE(PG8_SB(1, 1), b3 + hstep, voffB); PG8_STAGE(PG8_SA(1, 0), a3, voffA);
;             PG8_WAIT_V(8); PG8_WAIT_L(0); PG8_BAR; PG8_MMA(1, 0, At, B0); PG8_MMA(1, 1, At, B1); PG8_BAR; PG8_SCHED;
	s_setprio 1
	s_waitcnt lgkmcnt(7)
	v_mfma_f32_16x16x32_bf16 v[62:65], v[154:157], v[186:189], v[62:65]
	v_mfma_f32_16x16x32_bf16 v[58:61], v[162:165], v[186:189], v[58:61]
	s_waitcnt lgkmcnt(5)
	v_mfma_f32_16x16x32_bf16 v[46:49], v[154:157], v[194:197], v[46:49]
	v_mfma_f32_16x16x32_bf16 v[42:45], v[162:165], v[194:197], v[42:45]
	s_waitcnt lgkmcnt(3)
	v_mfma_f32_16x16x32_bf16 v[30:33], v[154:157], v[202:205], v[30:33]
	v_mfma_f32_16x16x32_bf16 v[26:29], v[162:165], v[202:205], v[26:29]
	s_waitcnt lgkmcnt(1)
	v_mfma_f32_16x16x32_bf16 v[14:17], v[154:157], v[210:213], v[14:17]
	v_mfma_f32_16x16x32_bf16 v[10:13], v[162:165], v[210:213], v[10:13]
	v_mfma_f32_16x16x32_bf16 v[62:65], v[158:161], v[190:193], v[62:65]
	v_mfma_f32_16x16x32_bf16 v[58:61], v[166:169], v[190:193], v[58:61]
	v_mfma_f32_16x16x32_bf16 v[46:49], v[158:161], v[198:201], v[46:49]
	v_mfma_f32_16x16x32_bf16 v[42:45], v[166:169], v[198:201], v[42:45]
	v_mfma_f32_16x16x32_bf16 v[30:33], v[158:161], v[206:209], v[30:33]
	v_mfma_f32_16x16x32_bf16 v[26:29], v[166:169], v[206:209], v[26:29]
	s_waitcnt lgkmcnt(0)
	v_mfma_f32_16x16x32_bf16 v[14:17], v[158:161], v[214:217], v[14:17]
	v_mfma_f32_16x16x32_bf16 v[10:13], v[166:169], v[214:217], v[10:13]
	s_setprio 0
	s_setprio 1
	v_mfma_f32_16x16x32_bf16 v[54:57], v[170:173], v[186:189], v[54:57]
	v_mfma_f32_16x16x32_bf16 v[50:53], v[178:181], v[186:189], v[50:53]
	v_mfma_f32_16x16x32_bf16 v[38:41], v[170:173], v[194:197], v[38:41]
	v_mfma_f32_16x16x32_bf16 v[34:37], v[178:181], v[194:197], v[34:37]
	v_mfma_f32_16x16x32_bf16 v[22:25], v[170:173], v[202:205], v[22:25]
	v_mfma_f32_16x16x32_bf16 v[18:21], v[178:181], v[202:205], v[18:21]
	v_mfma_f32_16x16x32_bf16 v[6:9], v[170:173], v[210:213], v[6:9]
	v_mfma_f32_16x16x32_bf16 v[2:5], v[178:181], v[210:213], v[2:5]
	v_mfma_f32_16x16x32_bf16 v[54:57], v[174:177], v[190:193], v[54:57]
	v_mfma_f32_16x16x32_bf16 v[50:53], v[182:185], v[190:193], v[50:53]
	v_mfma_f32_16x16x32_bf16 v[38:41], v[174:177], v[198:201], v[38:41]
	v_mfma_f32_16x16x32_bf16 v[34:37], v[182:185], v[198:201], v[34:37]
	v_mfma_f32_16x16x32_bf16 v[22:25], v[174:177], v[206:209], v[22:25]
	v_mfma_f32_16x16x32_bf16 v[18:21], v[182:185], v[206:209], v[18:21]
	s_setprio 2
	s_barrier
	v_mfma_f32_16x16x32_bf16 v[6:9], v[174:177], v[214:217], v[6:9]
	v_mfma_f32_16x16x32_bf16 v[2:5], v[182:185], v[214:217], v[2:5]
	s_setprio 0
	v_add_u32_e32 v138, 0x18000, v151
	ds_read_b128 v[154:157], v138
	ds_read_b128 v[158:161], v138 offset:1024
	ds_read_b128 v[162:165], v138 offset:2048
	ds_read_b128 v[166:169], v138 offset:3072
	v_add_u32_e32 v138, 0x1c000, v151
	ds_read_b128 v[170:173], v138
	ds_read_b128 v[174:177], v138 offset:1024
	ds_read_b128 v[178:181], v138 offset:2048
	ds_read_b128 v[182:185], v138 offset:3072
	ds_read_b128 v[186:189], v152 offset:32768
	ds_read_b128 v[190:193], v152 offset:33792
	ds_read_b128 v[194:197], v152 offset:34816
	ds_read_b128 v[198:201], v152 offset:35840
	ds_read_b128 v[202:205], v152 offset:36864
	ds_read_b128 v[206:209], v152 offset:37888
	ds_read_b128 v[210:213], v152 offset:38912
	ds_read_b128 v[214:217], v152 offset:39936
	s_add_u32 s60, s84, 0x100000
	s_addc_u32 s61, s85, 0
	s_mov_b32 m0, s88
	s_nop 0
	global_load_lds_dwordx4 v141, s[60:61]
	s_nop 0
	s_mov_b32 m0, s89
	s_nop 0
	global_load_lds_dwordx4 v143, s[60:61]
	s_waitcnt vmcnt(8)
	s_waitcnt lgkmcnt(0)
	s_barrier
	s_setprio 1
	s_waitcnt lgkmcnt(7)
	v_mfma_f32_16x16x32_bf16 v[126:129], v[154:157], v[186:189], v[126:129]
	v_mfma_f32_16x16x32_bf16 v[122:125], v[162:165], v[186:189], v[122:125]
	s_waitcnt lgkmcnt(5)
	v_mfma_f32_16x16x32_bf16 v[110:113], v[154:157], v[194:197], v[110:113]
	v_mfma_f32_16x16x32_bf16 v[106:109], v[162:165], v[194:197], v[106:109]
	s_waitcnt lgkmcnt(3)
	v_mfma_f32_16x16x32_bf16 v[94:97], v[154:157], v[202:205], v[94:97]
	v_mfma_f32_16x16x32_bf16 v[90:93], v[162:165], v[202:205], v[90:93]
	s_waitcnt lgkmcnt(1)
	v_mfma_f32_16x16x32_bf16 v[78:81], v[154:157], v[210:213], v[78:81]
	v_mfma_f32_16x16x32_bf16 v[74:77], v[162:165], v[210:213], v[74:77]
	v_mfma_f32_16x16x32_bf16 v[126:129], v[158:161], v[190:193], v[126:129]
	v_mfma_f32_16x16x32_bf16 v[122:125], v[166:169], v[190:193], v[122:125]
	v_mfma_f32_16x16x32_bf16 v[110:113], v[158:161], v[198:201], v[110:113]
	v_mfma_f32_16x16x32_bf16 v[106:109], v[166:169], v[198:201], v[106:109]
	v_mfma_f32_16x16x32_bf16 v[94:97], v[158:161], v[206:209], v[94:97]
	v_mfma_f32_16x16x32_bf16 v[90:93], v[166:169], v[206:209], v[90:93]
	s_waitcnt lgkmcnt(0)
	v_mfma_f32_16x16x32_bf16 v[78:81], v[158:161], v[214:217], v[78:81]
	v_mfma_f32_16x16x32_bf16 v[74:77], v[166:169], v[214:217], v[74:77]
	s_setprio 0
	s_setprio 1
	v_mfma_f32_16x16x32_bf16 v[118:121], v[170:173], v[186:189], v[118:121]
	v_mfma_f32_16x16x32_bf16 v[114:117], v[178:181], v[186:189], v[114:117]
	v_mfma_f32_16x16x32_bf16 v[102:105], v[170:173], v[194:197], v[102:105]
	v_mfma_f32_16x16x32_bf16 v[98:101], v[178:181], v[194:197], v[98:101]
	v_mfma_f32_16x16x32_bf16 v[86:89], v[170:173], v[202:205], v[86:89]
	v_mfma_f32_16x16x32_bf16 v[82:85], v[178:181], v[202:205], v[82:85]
	v_mfma_f32_16x16x32_bf16 v[70:73], v[170:173], v[210:213], v[70:73]
	v_mfma_f32_16x16x32_bf16 v[66:69], v[178:181], v[210:213], v[66:69]
	v_mfma_f32_16x16x32_bf16 v[118:121], v[174:177], v[190:193], v[118:121]
	v_mfma_f32_16x16x32_bf16 v[114:117], v[182:185], v[190:193], v[114:117]
	v_mfma_f32_16x16x32_bf16 v[102:105], v[174:177], v[198:201], v[102:105]
	v_mfma_f32_16x16x32_bf16 v[98:101], v[182:185], v[198:201], v[98:101]
	v_mfma_f32_16x16x32_bf16 v[86:89], v[174:177], v[206:209], v[86:89]
	v_mfma_f32_16x16x32_bf16 v[82:85], v[182:185], v[206:209], v[82:85]
	s_setprio 2
	s_barrier
; #define PG8_STAGE(bufoff, gbase, voff) do { _Pragma("unroll") for (int _i = 0; _i < 2; ++_i) \
;         asm volatile("s_mov_b32 m0, %2\n\ts_nop 0\n\tglobal_load_lds_dwordx4 %0, %1" :: "v"((voff)[_i]), "s"((const char*)(gbase)), "s"(ldsbase + (unsigned)(bufoff) + ldsw + (unsigned)_i * 8192u) : "memory", "m0"); } while (0)
; #define PG8_LDA(dst, b, h) do { _Pragma("unroll") for (int m = 0; m < 4; ++m) _Pragma("unroll") for (int k = 0; k < 2; ++k) dst[m][k] = *(const PG8_LAS bf16x8*)(lds + PG8_SA(b, h) + aoff + m * 2048 + k * 1024); } while (0)
; #define PG8_BAR __builtin_amdgcn_s_barrier()
; template <class Epi, class Sched, bool ALIGN_EPI = false, bool SP2 = false>
; __device__ __forceinline__ void gemm_phase(PG8_LAS unsigned char* lds, const Gemm g, const Sched& S, const Epi& E) {
;     ...
;         for (int t = 0; t < nt; t += 2) {
;             const bool last = (t == nt - 2);
;             const char* a1 = cA + (size_t)(t + 1) * kstep;
;             const char* a2 = last ? nA : cA + (size_t)(t + 2) * kstep; const char* b2 = last ? nB : cB + (size_t)(t + 2) * kstep;
;             const char* a3 = a2 + kstep; const char* b3 = b2 + kstep;
;             if (last && has_next) S.a_ready(nxt);
;             if constexpr (epi_has_mid<Epi>::value) { if (t == Epi::MID_T) E.mid(acc, cur, wr, wc, fr, fq); }
;             if constexpr (SP2) {
;             PG8_LDB(B0, 0, 0); PG8_LDB(B1, 0, 1); PG8_SCHED; PG8_LDA(At, 0, 0); PG8_STAGE(PG8_SA(1, 1), a1 + hstep, voffA);
;             PG8_WAIT_V(8); PG8_WAIT_L(0); PG8_BAR; PG8_MMA(0, 0, At, B0); PG8_MMA(0, 1, At, B1); PG8_BAR; PG8_SCHED;
;             PG8_LDA(At, 0, 1); PG8_STAGE(PG8_SB(0, 0), b2, voffB); PG8_STAGE(PG8_SB(0, 1), b2 + hstep, voffB); PG8_STAGE(PG8_SA(0, 0), a2, voffA);
;             PG8_WAIT_V(8); PG8_WAIT_L(0); PG8_BAR; PG8_MMA(1, 0, At, B0); PG8_MMA(1, 1, At, B1); PG8_BAR; PG8_SCHED;
;             PG8_LDB(B0, 1, 0); PG8_LDB(B1, 1, 1); PG8_SCHED; PG8_LDA(At, 1, 0); PG8_STAGE(PG8_SA(0, 1), a2 + hstep, voffA);
;             PG8_WAIT_V(8); PG8_WAIT_L(0); PG8_BAR; PG8_MMA(0, 0, At, B0); PG8_MMA(0, 1, At, B1); PG8_BAR; PG8_SCHED;
;             PG8_LDA(At, 1, 1); PG8_STAGE(PG8_SB(1, 0), b3, voffB); PG8_STAGE(PG8_SB(1, 1), b3 + hstep, voffB); PG8_STAGE(PG8_SA(1, 0), a3, voffA);
;             PG8_WAIT_V(8); PG8_WAIT_L(0); PG8_BAR; PG8_MMA(1, 0, At, B0); PG8_MMA(1, 1, At, B1); PG8_BAR; PG8_SCHED;
	ds_read_b128 v[186:189], v152 offset:49152
	ds_read_b128 v[190:193], v152 offset:50176
	ds_read_b128 v[194:197], v152 offset:51200
	ds_read_b128 v[198:201], v152 offset:52224
	ds_read_b128 v[202:205], v152 offset:53248
	ds_read_b128 v[206:209], v152 offset:54272
	ds_read_b128 v[210:213], v152 offset:55296
	v_mfma_f32_16x16x32_bf16 v[70:73], v[174:177], v[214:217], v[70:73]
	v_mfma_f32_16x16x32_bf16 v[66:69], v[182:185], v[214:217], v[66:69]
	s_setprio 0
	ds_read_b128 v[214:217], v152 offset:56320
	s_mov_b32 m0, s90
	s_nop 0
	global_load_lds_dwordx4 v142, s[76:77]
	s_add_u32 s60, s62, 0x100080
	s_mov_b32 m0, s91
	s_nop 0
	global_load_lds_dwordx4 v144, s[76:77]
	s_addc_u32 s61, s63, 0
	s_mov_b32 m0, s95
	s_nop 0
	global_load_lds_dwordx4 v142, s[60:61]
	s_nop 0
	s_mov_b32 m0, s96
	s_nop 0
	global_load_lds_dwordx4 v144, s[60:61]
	s_nop 0
	s_mov_b32 m0, s92
	s_nop 0
	global_load_lds_dwordx4 v141, s[66:67]
	s_nop 0
	s_mov_b32 m0, s94
	s_nop 0
	global_load_lds_dwordx4 v143, s[66:67]
	s_waitcnt vmcnt(8)
	s_waitcnt lgkmcnt(0)
	s_barrier
	s_setprio 1
	s_waitcnt lgkmcnt(7)
	v_mfma_f32_16x16x32_bf16 v[62:65], v[154:157], v[186:189], v[62:65]
	v_mfma_f32_16x16x32_bf16 v[58:61], v[162:165], v[186:189], v[58:61]
	s_waitcnt lgkmcnt(5)
	v_mfma_f32_16x16x32_bf16 v[46:49], v[154:157], v[194:197], v[46:49]
	v_mfma_f32_16x16x32_bf16 v[42:45], v[162:165], v[194:197], v[42:45]
	s_waitcnt lgkmcnt(3)
	v_mfma_f32_16x16x32_bf16 v[30:33], v[154:157], v[202:205], v[30:33]
	v_mfma_f32_16x16x32_bf16 v[26:29], v[162:165], v[202:205], v[26:29]
	s_waitcnt lgkmcnt(1)
	v_mfma_f32_16x16x32_bf16 v[14:17], v[154:157], v[210:213], v[14:17]
	v_mfma_f32_16x16x32_bf16 v[10:13], v[162:165], v[210:213], v[10:13]
	v_mfma_f32_16x16x32_bf16 v[62:65], v[158:161], v[190:193], v[62:65]
	v_mfma_f32_16x16x32_bf16 v[58:61], v[166:169], v[190:193], v[58:61]
	v_mfma_f32_16x16x32_bf16 v[46:49], v[158:161], v[198:201], v[46:49]
	v_mfma_f32_16x16x32_bf16 v[42:45], v[166:169], v[198:201], v[42:45]
	v_mfma_f32_16x16x32_bf16 v[30:33], v[158:161], v[206:209], v[30:33]
	v_mfma_f32_16x16x32_bf16 v[26:29], v[166:169], v[206:209], v[26:29]
	s_waitcnt lgkmcnt(0)
	v_mfma_f32_16x16x32_bf16 v[14:17], v[158:161], v[214:217], v[14:17]
	v_mfma_f32_16x16x32_bf16 v[10:13], v[166:169], v[214:217], v[10:13]
	s_setprio 0
	s_setprio 1
	v_mfma_f32_16x16x32_bf16 v[54:57], v[170:173], v[186:189], v[54:57]
	v_mfma_f32_16x16x32_bf16 v[50:53], v[178:181], v[186:189], v[50:53]
	v_mfma_f32_16x16x32_bf16 v[38:41], v[170:173], v[194:197], v[38:41]
	v_mfma_f32_16x16x32_bf16 v[34:37], v[178:181], v[194:197], v[34:37]
	v_mfma_f32_16x16x32_bf16 v[22:25], v[170:173], v[202:205], v[22:25]
	v_mfma_f32_16x16x32_bf16 v[18:21], v[178:181], v[202:205], v[18:21]
	v_mfma_f32_16x16x32_bf16 v[6:9], v[170:173], v[210:213], v[6:9]
	v_mfma_f32_16x16x32_bf16 v[2:5], v[178:181], v[210:213], v[2:5]
	v_mfma_f32_16x16x32_bf16 v[54:57], v[174:177], v[190:193], v[54:57]
	v_mfma_f32_16x16x32_bf16 v[50:53], v[182:185], v[190:193], v[50:53]
	v_mfma_f32_16x16x32_bf16 v[38:41], v[174:177], v[198:201], v[38:41]
	v_mfma_f32_16x16x32_bf16 v[34:37], v[182:185], v[198:201], v[34:37]
	v_mfma_f32_16x16x32_bf16 v[22:25], v[174:177], v[206:209], v[22:25]
	v_mfma_f32_16x16x32_bf16 v[18:21], v[182:185], v[206:209], v[18:21]
	v_mfma_f32_16x16x32_bf16 v[6:9], v[174:177], v[214:217], v[6:9]
	s_setprio 2
	s_barrier
	v_mfma_f32_16x16x32_bf16 v[2:5], v[182:185], v[214:217], v[2:5]
	s_setprio 0
	s_add_i32 s58, s58, 2
	s_add_u32 s56, s56, 0x100
	s_addc_u32 s57, s57, 0
	s_cmp_gt_u32 s58, 61
	s_cbranch_scc1 .LBB0_316
	s_mov_b64 s[82:83], s[8:9]
	s_branch .LBB0_320

; #define PG8_STAGE(bufoff, gbase, voff) do { _Pragma("unroll") for (int _i = 0; _i < 2; ++_i) \
;         asm volatile("s_mov_b32 m0, %2\n\ts_nop 0\n\tglobal_load_lds_dwordx4 %0, %1" :: "v"((voff)[_i]), "s"((const char*)(gbase)), "s"(ldsbase + (unsigned)(bufoff) + ldsw + (unsigned)_i * 8192u) : "memory", "m0"); } while (0)
; #define PG8_LDA(dst, b, h) do { _Pragma("unroll") for (int m = 0; m < 4; ++m) _Pragma("unroll") for (int k = 0; k < 2; ++k) dst[m][k] = *(const PG8_LAS bf16x8*)(lds + PG8_SA(b, h) + aoff + m * 2048 + k * 1024); } while (0)
; #define PG8_WAIT_V(n) asm volatile("s_waitcnt vmcnt(" #n ")" ::: "memory")
; template <class Epi, class Sched, bool ALIGN_EPI = false, bool SP2 = false>
; __device__ __forceinline__ void gemm_phase(PG8_LAS unsigned char* lds, const Gemm g, const Sched& S, const Epi& E) {
;     ...
;             const bool last = (t == nt - 2);
;             const char* a1 = cA + (size_t)(t + 1) * kstep;
;             const char* a2 = last ? nA : cA + (size_t)(t + 2) * kstep; const char* b2 = last ? nB : cB + (size_t)(t + 2) * kstep;
;             const char* a3 = a2 + kstep; const char* b3 = b2 + kstep;
;             if (last && has_next) S.a_ready(nxt);
;             if constexpr (epi_has_mid<Epi>::value) { if (t == Epi::MID_T) E.mid(acc, cur, wr, wc, fr, fq); }
;             if constexpr (SP2) {
;             PG8_LDB(B0, 0, 0); PG8_LDB(B1, 0, 1); PG8_SCHED; PG8_LDA(At, 0, 0); PG8_STAGE(PG8_SA(1, 1), a1 + hstep, voffA);
;             PG8_WAIT_V(8); PG8_WAIT_L(0); PG8_BAR; PG8_MMA(0, 0, At, B0); PG8_MMA(0, 1, At, B1); PG8_BAR; PG8_SCHED;
;             PG8_LDA(At, 0, 1); PG8_STAGE(PG8_SB(0, 0), b2, voffB); PG8_STAGE(PG8_SB(0, 1), b2 + hstep, voffB); PG8_STAGE(PG8_SA(0, 0), a2, voffA);
;             PG8_WAIT_V(8); PG8_WAIT_L(0); PG8_BAR; PG8_MMA(1, 0, At, B0); PG8_MMA(1, 1, At, B1); PG8_BAR; PG8_SCHED;
;             PG8_LDB(B0, 1, 0); PG8_LDB(B1, 1, 1); PG8_SCHED; PG8_LDA(At, 1, 0); PG8_STAGE(PG8_SA(0, 1), a2 + hstep, voffA);
;             PG8_WAIT_V(8); PG8_WAIT_L(0); PG8_BAR; PG8_MMA(0, 0, At, B0); PG8_MMA(0, 1, At, B1); PG8_BAR; PG8_SCHED;
;             PG8_LDA(At, 1, 1); PG8_STAGE(PG8_SB(1, 0), b3, voffB); PG8_STAGE(PG8_SB(1, 1), b3 + hstep, voffB); PG8_STAGE(PG8_SA(1, 0), a3, voffA);
;             PG8_WAIT_V(8); PG8_WAIT_L(0); PG8_BAR; PG8_MMA(1, 0, At, B0); PG8_MMA(1, 1, At, B1); PG8_BAR; PG8_SCHED;
.LBB0_620:
	v_add_u32_e32 v3, 0x10000, v199
	ds_read_b128 v[134:137], v3
	ds_read_b128 v[138:141], v3 offset:1024
	ds_read_b128 v[142:145], v3 offset:2048
	ds_read_b128 v[146:149], v3 offset:3072
	v_add_u32_e32 v3, 0x14000, v199
	s_add_u32 s44, s42, 0x100
	ds_read_b128 v[158:161], v3
	ds_read_b128 v[162:165], v3 offset:1024
	ds_read_b128 v[166:169], v3 offset:2048
	ds_read_b128 v[170:173], v3 offset:3072
	s_addc_u32 s45, s43, 0
	s_cmp_eq_u32 s92, 60
	s_cselect_b32 s56, s88, s44
	s_cselect_b32 s57, s23, s45
	s_cselect_b32 s47, s19, s91
	s_cselect_b32 s46, s89, s90
	s_add_u32 s50, s56, 0x80
	s_addc_u32 s51, s57, 0
	s_add_u32 s54, s46, 0x80
	s_addc_u32 s55, s47, 0
	ds_read_b128 v[174:177], v200
	ds_read_b128 v[178:181], v200 offset:1024
	ds_read_b128 v[182:185], v200 offset:2048
	ds_read_b128 v[186:189], v200 offset:3072
	ds_read_b128 v[190:193], v200 offset:4096
	ds_read_b128 v[202:205], v200 offset:5120
	ds_read_b128 v[206:209], v200 offset:6144
	ds_read_b128 v[210:213], v200 offset:7168
	s_add_u32 s42, s42, 0x100080
	s_addc_u32 s43, s43, 0
	s_mov_b32 m0, s85
	s_nop 0
	global_load_lds_dwordx4 v1, s[42:43]
	s_nop 0
	s_mov_b32 m0, s86
	s_nop 0
	global_load_lds_dwordx4 v195, s[42:43]
	s_waitcnt vmcnt(8)
	s_waitcnt lgkmcnt(0)
	s_barrier
	s_setprio 1
	s_waitcnt lgkmcnt(7)
	v_mfma_f32_16x16x32_bf16 v[130:133], v[134:137], v[174:177], v[130:133]
	v_mfma_f32_16x16x32_bf16 v[126:129], v[142:145], v[174:177], v[126:129]
	s_waitcnt lgkmcnt(5)
	v_mfma_f32_16x16x32_bf16 v[122:125], v[134:137], v[182:185], v[122:125]
	v_mfma_f32_16x16x32_bf16 v[118:121], v[142:145], v[182:185], v[118:121]
	s_waitcnt lgkmcnt(3)
	v_mfma_f32_16x16x32_bf16 v[114:117], v[134:137], v[190:193], v[114:117]
	v_mfma_f32_16x16x32_bf16 v[110:113], v[142:145], v[190:193], v[110:113]
	s_waitcnt lgkmcnt(1)
	v_mfma_f32_16x16x32_bf16 v[106:109], v[134:137], v[206:209], v[106:109]
	v_mfma_f32_16x16x32_bf16 v[102:105], v[142:145], v[206:209], v[102:105]
	v_mfma_f32_16x16x32_bf16 v[130:133], v[138:141], v[178:181], v[130:133]
	v_mfma_f32_16x16x32_bf16 v[126:129], v[146:149], v[178:181], v[126:129]
	v_mfma_f32_16x16x32_bf16 v[122:125], v[138:141], v[186:189], v[122:125]
	v_mfma_f32_16x16x32_bf16 v[118:121], v[146:149], v[186:189], v[118:121]
	v_mfma_f32_16x16x32_bf16 v[114:117], v[138:141], v[202:205], v[114:117]
	v_mfma_f32_16x16x32_bf16 v[110:113], v[146:149], v[202:205], v[110:113]
	s_waitcnt lgkmcnt(0)
	v_mfma_f32_16x16x32_bf16 v[106:109], v[138:141], v[210:213], v[106:109]
	v_mfma_f32_16x16x32_bf16 v[102:105], v[146:149], v[210:213], v[102:105]
	s_setprio 0
	s_setprio 1
	v_mfma_f32_16x16x32_bf16 v[66:69], v[158:161], v[174:177], v[66:69]
	v_mfma_f32_16x16x32_bf16 v[62:65], v[166:169], v[174:177], v[62:65]
	v_mfma_f32_16x16x32_bf16 v[58:61], v[158:161], v[182:185], v[58:61]
	v_mfma_f32_16x16x32_bf16 v[54:57], v[166:169], v[182:185], v[54:57]
	v_mfma_f32_16x16x32_bf16 v[50:53], v[158:161], v[190:193], v[50:53]
	v_mfma_f32_16x16x32_bf16 v[46:49], v[166:169], v[190:193], v[46:49]
	v_mfma_f32_16x16x32_bf16 v[42:45], v[158:161], v[206:209], v[42:45]
	v_mfma_f32_16x16x32_bf16 v[38:41], v[166:169], v[206:209], v[38:41]
	v_mfma_f32_16x16x32_bf16 v[66:69], v[162:165], v[178:181], v[66:69]
	v_mfma_f32_16x16x32_bf16 v[62:65], v[170:173], v[178:181], v[62:65]
	v_mfma_f32_16x16x32_bf16 v[58:61], v[162:165], v[186:189], v[58:61]
	v_mfma_f32_16x16x32_bf16 v[54:57], v[170:173], v[186:189], v[54:57]
	v_mfma_f32_16x16x32_bf16 v[50:53], v[162:165], v[202:205], v[50:53]
	v_mfma_f32_16x16x32_bf16 v[46:49], v[170:173], v[202:205], v[46:49]
	s_setprio 2
	s_barrier
	ds_read_b128 v[174:177], v200 offset:16384
	ds_read_b128 v[178:181], v200 offset:17408
	ds_read_b128 v[182:185], v200 offset:18432
	ds_read_b128 v[186:189], v200 offset:19456
	ds_read_b128 v[190:193], v200 offset:20480
	ds_read_b128 v[202:205], v200 offset:21504
	ds_read_b128 v[206:209], v200 offset:22528
	v_mfma_f32_16x16x32_bf16 v[42:45], v[162:165], v[210:213], v[42:45]
	v_mfma_f32_16x16x32_bf16 v[38:41], v[170:173], v[210:213], v[38:41]
	s_setprio 0
	ds_read_b128 v[210:213], v200 offset:23552
	s_mov_b32 m0, s63
	s_nop 0
	global_load_lds_dwordx4 v194, s[46:47]
	s_add_u32 s42, s46, 0x100000
	s_mov_b32 m0, s64
	s_nop 0
	global_load_lds_dwordx4 v196, s[46:47]
	s_addc_u32 s43, s47, 0
	s_mov_b32 m0, s65
	s_nop 0
	global_load_lds_dwordx4 v194, s[42:43]
	s_nop 0
	s_mov_b32 m0, s66
	s_nop 0
	global_load_lds_dwordx4 v196, s[42:43]
	s_nop 0
	s_mov_b32 m0, s62
	s_nop 0
	global_load_lds_dwordx4 v1, s[56:57]
	s_nop 0
	s_mov_b32 m0, s67
	s_nop 0
	global_load_lds_dwordx4 v195, s[56:57]
	s_waitcnt vmcnt(8)
	s_waitcnt lgkmcnt(0)
	s_barrier
; #define PG8_STAGE(bufoff, gbase, voff) do { _Pragma("unroll") for (int _i = 0; _i < 2; ++_i) \
;         asm volatile("s_mov_b32 m0, %2\n\ts_nop 0\n\tglobal_load_lds_dwordx4 %0, %1" :: "v"((voff)[_i]), "s"((const char*)(gbase)), "s"(ldsbase + (unsigned)(bufoff) + ldsw + (unsigned)_i * 8192u) : "memory", "m0"); } while (0)
; #define PG8_LDA(dst, b, h) do { _Pragma("unroll") for (int m = 0; m < 4; ++m) _Pragma("unroll") for (int k = 0; k < 2; ++k) dst[m][k] = *(const PG8_LAS bf16x8*)(lds + PG8_SA(b, h) + aoff + m * 2048 + k * 1024); } while (0)
; #define PG8_LDB(dst, b, h) do { _Pragma("unroll") for (int n = 0; n < 2; ++n) _Pragma("unroll") for (int k = 0; k < 2; ++k) dst[n][k] = *(const PG8_LAS bf16x8*)(lds + PG8_SB(b, h) + boff + n * 2048 + k * 1024); } while (0)
; #define PG8_MMA(ai, bj, At, Bt) do { __builtin_amdgcn_s_setprio(1); _Pragma("unroll") for (int m = 0; m < 4; ++m) _Pragma("unroll") for (int n = 0; n < 2; ++n) _Pragma("unroll") for (int k = 0; k < 2; ++k) \
;         acc[ai][bj][m][n] = __builtin_amdgcn_mfma_f32_16x16x32_bf16(Bt[n][k], At[m][k], acc[ai][bj][m][n], 0, 0, 0); __builtin_amdgcn_s_setprio(0); } while (0)
; template <class Epi, class Sched, bool ALIGN_EPI = false, bool SP2 = false>
; __device__ __forceinline__ void gemm_phase(PG8_LAS unsigned char* lds, const Gemm g, const Sched& S, const Epi& E) {
;     ...
;             PG8_LDB(B0, 0, 0); PG8_LDB(B1, 0, 1); PG8_SCHED; PG8_LDA(At, 0, 0); PG8_STAGE(PG8_SA(1, 1), a1 + hstep, voffA);
;             PG8_WAIT_V(8); PG8_WAIT_L(0); PG8_BAR; PG8_MMA(0, 0, At, B0); PG8_MMA(0, 1, At, B1); PG8_BAR; PG8_SCHED;
;             PG8_LDA(At, 0, 1); PG8_STAGE(PG8_SB(0, 0), b2, voffB); PG8_STAGE(PG8_SB(0, 1), b2 + hstep, voffB); PG8_STAGE(PG8_SA(0, 0), a2, voffA);
;             PG8_WAIT_V(8); PG8_WAIT_L(0); PG8_BAR; PG8_MMA(1, 0, At, B0); PG8_MMA(1, 1, At, B1); PG8_BAR; PG8_SCHED;
;             PG8_LDB(B0, 1, 0); PG8_LDB(B1, 1, 1); PG8_SCHED; PG8_LDA(At, 1, 0); PG8_STAGE(PG8_SA(0, 1), a2 + hstep, voffA);
;             PG8_WAIT_V(8); PG8_WAIT_L(0); PG8_BAR; PG8_MMA(0, 0, At, B0); PG8_MMA(0, 1, At, B1); PG8_BAR; PG8_SCHED;
;             PG8_LDA(At, 1, 1); PG8_STAGE(PG8_SB(1, 0), b3, voffB); PG8_STAGE(PG8_SB(1, 1), b3 + hstep, voffB); PG8_STAGE(PG8_SA(1, 0), a3, voffA);
;             PG8_WAIT_V(8); PG8_WAIT_L(0); PG8_BAR; PG8_MMA(1, 0, At, B0); PG8_MMA(1, 1, At, B1); PG8_BAR; PG8_SCHED;
	s_setprio 1
	s_waitcnt lgkmcnt(7)
	v_mfma_f32_16x16x32_bf16 v[98:101], v[134:137], v[174:177], v[98:101]
	v_mfma_f32_16x16x32_bf16 v[94:97], v[142:145], v[174:177], v[94:97]
	s_waitcnt lgkmcnt(5)
	v_mfma_f32_16x16x32_bf16 v[90:93], v[134:137], v[182:185], v[90:93]
	v_mfma_f32_16x16x32_bf16 v[86:89], v[142:145], v[182:185], v[86:89]
	s_waitcnt lgkmcnt(3)
	v_mfma_f32_16x16x32_bf16 v[82:85], v[134:137], v[190:193], v[82:85]
	v_mfma_f32_16x16x32_bf16 v[78:81], v[142:145], v[190:193], v[78:81]
	s_waitcnt lgkmcnt(1)
	v_mfma_f32_16x16x32_bf16 v[74:77], v[134:137], v[206:209], v[74:77]
	v_mfma_f32_16x16x32_bf16 v[70:73], v[142:145], v[206:209], v[70:73]
	v_mfma_f32_16x16x32_bf16 v[98:101], v[138:141], v[178:181], v[98:101]
	v_mfma_f32_16x16x32_bf16 v[94:97], v[146:149], v[178:181], v[94:97]
	v_mfma_f32_16x16x32_bf16 v[90:93], v[138:141], v[186:189], v[90:93]
	v_mfma_f32_16x16x32_bf16 v[86:89], v[146:149], v[186:189], v[86:89]
	v_mfma_f32_16x16x32_bf16 v[82:85], v[138:141], v[202:205], v[82:85]
	v_mfma_f32_16x16x32_bf16 v[78:81], v[146:149], v[202:205], v[78:81]
	s_waitcnt lgkmcnt(0)
	v_mfma_f32_16x16x32_bf16 v[74:77], v[138:141], v[210:213], v[74:77]
	v_mfma_f32_16x16x32_bf16 v[70:73], v[146:149], v[210:213], v[70:73]
	s_setprio 0
	s_setprio 1
	v_mfma_f32_16x16x32_bf16 v[34:37], v[158:161], v[174:177], v[34:37]
	v_mfma_f32_16x16x32_bf16 v[30:33], v[166:169], v[174:177], v[30:33]
	v_mfma_f32_16x16x32_bf16 v[26:29], v[158:161], v[182:185], v[26:29]
	v_mfma_f32_16x16x32_bf16 v[22:25], v[166:169], v[182:185], v[22:25]
	v_mfma_f32_16x16x32_bf16 v[18:21], v[158:161], v[190:193], v[18:21]
	v_mfma_f32_16x16x32_bf16 v[14:17], v[166:169], v[190:193], v[14:17]
	v_mfma_f32_16x16x32_bf16 v[10:13], v[158:161], v[206:209], v[10:13]
	v_mfma_f32_16x16x32_bf16 v[4:7], v[166:169], v[206:209], v[6:9]
	v_mfma_f32_16x16x32_bf16 v[34:37], v[162:165], v[178:181], v[34:37]
	v_mfma_f32_16x16x32_bf16 v[30:33], v[170:173], v[178:181], v[30:33]
	v_mfma_f32_16x16x32_bf16 v[26:29], v[162:165], v[186:189], v[26:29]
	v_mfma_f32_16x16x32_bf16 v[22:25], v[170:173], v[186:189], v[22:25]
	v_mfma_f32_16x16x32_bf16 v[18:21], v[162:165], v[202:205], v[18:21]
	v_mfma_f32_16x16x32_bf16 v[14:17], v[170:173], v[202:205], v[14:17]
	s_setprio 2
	s_barrier
	v_mfma_f32_16x16x32_bf16 v[10:13], v[162:165], v[210:213], v[10:13]
	v_mfma_f32_16x16x32_bf16 v[4:7], v[170:173], v[210:213], v[4:7]
	s_setprio 0
	v_add_u32_e32 v3, 0x18000, v199
	ds_read_b128 v[134:137], v3
	ds_read_b128 v[138:141], v3 offset:1024
	ds_read_b128 v[142:145], v3 offset:2048
	ds_read_b128 v[146:149], v3 offset:3072
	v_add_u32_e32 v3, 0x1c000, v199
	ds_read_b128 v[158:161], v3
	ds_read_b128 v[162:165], v3 offset:1024
	ds_read_b128 v[166:169], v3 offset:2048
	ds_read_b128 v[170:173], v3 offset:3072
	ds_read_b128 v[174:177], v200 offset:32768
	ds_read_b128 v[178:181], v200 offset:33792
	ds_read_b128 v[182:185], v200 offset:34816
	ds_read_b128 v[186:189], v200 offset:35840
	ds_read_b128 v[190:193], v200 offset:36864
	ds_read_b128 v[202:205], v200 offset:37888
	ds_read_b128 v[206:209], v200 offset:38912
	ds_read_b128 v[210:213], v200 offset:39936
	s_add_u32 s42, s56, 0x100000
	s_addc_u32 s43, s57, 0
	s_mov_b32 m0, s76
	s_nop 0
	global_load_lds_dwordx4 v1, s[42:43]
	s_nop 0
	s_mov_b32 m0, s77
	s_nop 0
	global_load_lds_dwordx4 v195, s[42:43]
	s_waitcnt vmcnt(8)
	s_waitcnt lgkmcnt(0)
	s_barrier
	s_setprio 1
	s_waitcnt lgkmcnt(7)
	v_mfma_f32_16x16x32_bf16 v[130:133], v[134:137], v[174:177], v[130:133]
	v_mfma_f32_16x16x32_bf16 v[126:129], v[142:145], v[174:177], v[126:129]
	s_waitcnt lgkmcnt(5)
	v_mfma_f32_16x16x32_bf16 v[122:125], v[134:137], v[182:185], v[122:125]
	v_mfma_f32_16x16x32_bf16 v[118:121], v[142:145], v[182:185], v[118:121]
	s_waitcnt lgkmcnt(3)
	v_mfma_f32_16x16x32_bf16 v[114:117], v[134:137], v[190:193], v[114:117]
	v_mfma_f32_16x16x32_bf16 v[110:113], v[142:145], v[190:193], v[110:113]
	s_waitcnt lgkmcnt(1)
	v_mfma_f32_16x16x32_bf16 v[106:109], v[134:137], v[206:209], v[106:109]
	v_mfma_f32_16x16x32_bf16 v[102:105], v[142:145], v[206:209], v[102:105]
	v_mfma_f32_16x16x32_bf16 v[130:133], v[138:141], v[178:181], v[130:133]
	v_mfma_f32_16x16x32_bf16 v[126:129], v[146:149], v[178:181], v[126:129]
	v_mfma_f32_16x16x32_bf16 v[122:125], v[138:141], v[186:189], v[122:125]
	v_mfma_f32_16x16x32_bf16 v[118:121], v[146:149], v[186:189], v[118:121]
	v_mfma_f32_16x16x32_bf16 v[114:117], v[138:141], v[202:205], v[114:117]
	v_mfma_f32_16x16x32_bf16 v[110:113], v[146:149], v[202:205], v[110:113]
	s_waitcnt lgkmcnt(0)
	v_mfma_f32_16x16x32_bf16 v[106:109], v[138:141], v[210:213], v[106:109]
	v_mfma_f32_16x16x32_bf16 v[102:105], v[146:149], v[210:213], v[102:105]
	s_setprio 0
	s_setprio 1
	v_mfma_f32_16x16x32_bf16 v[66:69], v[158:161], v[174:177], v[66:69]
	v_mfma_f32_16x16x32_bf16 v[62:65], v[166:169], v[174:177], v[62:65]
	v_mfma_f32_16x16x32_bf16 v[58:61], v[158:161], v[182:185], v[58:61]
	v_mfma_f32_16x16x32_bf16 v[54:57], v[166:169], v[182:185], v[54:57]
	v_mfma_f32_16x16x32_bf16 v[50:53], v[158:161], v[190:193], v[50:53]
	v_mfma_f32_16x16x32_bf16 v[46:49], v[166:169], v[190:193], v[46:49]
	v_mfma_f32_16x16x32_bf16 v[42:45], v[158:161], v[206:209], v[42:45]
	v_mfma_f32_16x16x32_bf16 v[38:41], v[166:169], v[206:209], v[38:41]
	v_mfma_f32_16x16x32_bf16 v[66:69], v[162:165], v[178:181], v[66:69]
	v_mfma_f32_16x16x32_bf16 v[62:65], v[170:173], v[178:181], v[62:65]
	v_mfma_f32_16x16x32_bf16 v[58:61], v[162:165], v[186:189], v[58:61]
	v_mfma_f32_16x16x32_bf16 v[54:57], v[170:173], v[186:189], v[54:57]
	v_mfma_f32_16x16x32_bf16 v[50:53], v[162:165], v[202:205], v[50:53]
	v_mfma_f32_16x16x32_bf16 v[46:49], v[170:173], v[202:205], v[46:49]
	s_setprio 2
	s_barrier
; #define PG8_STAGE(bufoff, gbase, voff) do { _Pragma("unroll") for (int _i = 0; _i < 2; ++_i) \
;         asm volatile("s_mov_b32 m0, %2\n\ts_nop 0\n\tglobal_load_lds_dwordx4 %0, %1" :: "v"((voff)[_i]), "s"((const char*)(gbase)), "s"(ldsbase + (unsigned)(bufoff) + ldsw + (unsigned)_i * 8192u) : "memory", "m0"); } while (0)
; #define PG8_LDA(dst, b, h) do { _Pragma("unroll") for (int m = 0; m < 4; ++m) _Pragma("unroll") for (int k = 0; k < 2; ++k) dst[m][k] = *(const PG8_LAS bf16x8*)(lds + PG8_SA(b, h) + aoff + m * 2048 + k * 1024); } while (0)
; #define PG8_BAR __builtin_amdgcn_s_barrier()
; template <class Epi, class Sched, bool ALIGN_EPI = false, bool SP2 = false>
; __device__ __forceinline__ void gemm_phase(PG8_LAS unsigned char* lds, const Gemm g, const Sched& S, const Epi& E) {
;     ...
;         for (int t = 0; t < nt; t += 2) {
;             const bool last = (t == nt - 2);
;             const char* a1 = cA + (size_t)(t + 1) * kstep;
;             const char* a2 = last ? nA : cA + (size_t)(t + 2) * kstep; const char* b2 = last ? nB : cB + (size_t)(t + 2) * kstep;
;             const char* a3 = a2 + kstep; const char* b3 = b2 + kstep;
;             if (last && has_next) S.a_ready(nxt);
;             if constexpr (epi_has_mid<Epi>::value) { if (t == Epi::MID_T) E.mid(acc, cur, wr, wc, fr, fq); }
;             if constexpr (SP2) {
;             PG8_LDB(B0, 0, 0); PG8_LDB(B1, 0, 1); PG8_SCHED; PG8_LDA(At, 0, 0); PG8_STAGE(PG8_SA(1, 1), a1 + hstep, voffA);
;             PG8_WAIT_V(8); PG8_WAIT_L(0); PG8_BAR; PG8_MMA(0, 0, At, B0); PG8_MMA(0, 1, At, B1); PG8_BAR; PG8_SCHED;
;             PG8_LDA(At, 0, 1); PG8_STAGE(PG8_SB(0, 0), b2, voffB); PG8_STAGE(PG8_SB(0, 1), b2 + hstep, voffB); PG8_STAGE(PG8_SA(0, 0), a2, voffA);
;             PG8_WAIT_V(8); PG8_WAIT_L(0); PG8_BAR; PG8_MMA(1, 0, At, B0); PG8_MMA(1, 1, At, B1); PG8_BAR; PG8_SCHED;
;             PG8_LDB(B0, 1, 0); PG8_LDB(B1, 1, 1); PG8_SCHED; PG8_LDA(At, 1, 0); PG8_STAGE(PG8_SA(0, 1), a2 + hstep, voffA);
;             PG8_WAIT_V(8); PG8_WAIT_L(0); PG8_BAR; PG8_MMA(0, 0, At, B0); PG8_MMA(0, 1, At, B1); PG8_BAR; PG8_SCHED;
;             PG8_LDA(At, 1, 1); PG8_STAGE(PG8_SB(1, 0), b3, voffB); PG8_STAGE(PG8_SB(1, 1), b3 + hstep, voffB); PG8_STAGE(PG8_SA(1, 0), a3, voffA);
;             PG8_WAIT_V(8); PG8_WAIT_L(0); PG8_BAR; PG8_MMA(1, 0, At, B0); PG8_MMA(1, 1, At, B1); PG8_BAR; PG8_SCHED;
	ds_read_b128 v[174:177], v200 offset:49152
	ds_read_b128 v[178:181], v200 offset:50176
	ds_read_b128 v[182:185], v200 offset:51200
	ds_read_b128 v[186:189], v200 offset:52224
	ds_read_b128 v[190:193], v200 offset:53248
	ds_read_b128 v[202:205], v200 offset:54272
	ds_read_b128 v[206:209], v200 offset:55296
	v_mfma_f32_16x16x32_bf16 v[42:45], v[162:165], v[210:213], v[42:45]
	v_mfma_f32_16x16x32_bf16 v[38:41], v[170:173], v[210:213], v[38:41]
	s_setprio 0
	ds_read_b128 v[210:213], v200 offset:56320
	s_mov_b32 m0, s78
	s_nop 0
	global_load_lds_dwordx4 v194, s[54:55]
	s_add_u32 s42, s46, 0x100080
	s_mov_b32 m0, s79
	s_nop 0
	global_load_lds_dwordx4 v196, s[54:55]
	s_addc_u32 s43, s47, 0
	s_mov_b32 m0, s83
	s_nop 0
	global_load_lds_dwordx4 v194, s[42:43]
	s_nop 0
	s_mov_b32 m0, s84
	s_nop 0
	global_load_lds_dwordx4 v196, s[42:43]
	s_nop 0
	s_mov_b32 m0, s80
	s_nop 0
	global_load_lds_dwordx4 v1, s[50:51]
	s_nop 0
	s_mov_b32 m0, s82
	s_nop 0
	global_load_lds_dwordx4 v195, s[50:51]
	s_waitcnt vmcnt(8)
	s_waitcnt lgkmcnt(0)
	s_barrier
	s_setprio 1
	s_waitcnt lgkmcnt(7)
	v_mfma_f32_16x16x32_bf16 v[98:101], v[134:137], v[174:177], v[98:101]
	v_mfma_f32_16x16x32_bf16 v[94:97], v[142:145], v[174:177], v[94:97]
	s_waitcnt lgkmcnt(5)
	v_mfma_f32_16x16x32_bf16 v[90:93], v[134:137], v[182:185], v[90:93]
	v_mfma_f32_16x16x32_bf16 v[86:89], v[142:145], v[182:185], v[86:89]
	s_waitcnt lgkmcnt(3)
	v_mfma_f32_16x16x32_bf16 v[82:85], v[134:137], v[190:193], v[82:85]
	v_mfma_f32_16x16x32_bf16 v[78:81], v[142:145], v[190:193], v[78:81]
	s_waitcnt lgkmcnt(1)
	v_mfma_f32_16x16x32_bf16 v[74:77], v[134:137], v[206:209], v[74:77]
	v_mfma_f32_16x16x32_bf16 v[70:73], v[142:145], v[206:209], v[70:73]
	v_mfma_f32_16x16x32_bf16 v[98:101], v[138:141], v[178:181], v[98:101]
	v_mfma_f32_16x16x32_bf16 v[94:97], v[146:149], v[178:181], v[94:97]
	v_mfma_f32_16x16x32_bf16 v[90:93], v[138:141], v[186:189], v[90:93]
	v_mfma_f32_16x16x32_bf16 v[86:89], v[146:149], v[186:189], v[86:89]
	v_mfma_f32_16x16x32_bf16 v[82:85], v[138:141], v[202:205], v[82:85]
	v_mfma_f32_16x16x32_bf16 v[78:81], v[146:149], v[202:205], v[78:81]
	s_waitcnt lgkmcnt(0)
	v_mfma_f32_16x16x32_bf16 v[74:77], v[138:141], v[210:213], v[74:77]
	v_mfma_f32_16x16x32_bf16 v[70:73], v[146:149], v[210:213], v[70:73]
	s_setprio 0
	s_setprio 1
	v_mfma_f32_16x16x32_bf16 v[34:37], v[158:161], v[174:177], v[34:37]
	v_mfma_f32_16x16x32_bf16 v[30:33], v[166:169], v[174:177], v[30:33]
	v_mfma_f32_16x16x32_bf16 v[26:29], v[158:161], v[182:185], v[26:29]
	v_mfma_f32_16x16x32_bf16 v[22:25], v[166:169], v[182:185], v[22:25]
	v_mfma_f32_16x16x32_bf16 v[18:21], v[158:161], v[190:193], v[18:21]
	v_mfma_f32_16x16x32_bf16 v[14:17], v[166:169], v[190:193], v[14:17]
	v_mfma_f32_16x16x32_bf16 v[8:11], v[158:161], v[206:209], v[10:13]
	v_mfma_f32_16x16x32_bf16 v[4:7], v[166:169], v[206:209], v[4:7]
	v_mfma_f32_16x16x32_bf16 v[34:37], v[162:165], v[178:181], v[34:37]
	v_mfma_f32_16x16x32_bf16 v[30:33], v[170:173], v[178:181], v[30:33]
	v_mfma_f32_16x16x32_bf16 v[26:29], v[162:165], v[186:189], v[26:29]
	v_mfma_f32_16x16x32_bf16 v[22:25], v[170:173], v[186:189], v[22:25]
	v_mfma_f32_16x16x32_bf16 v[18:21], v[162:165], v[202:205], v[18:21]
	v_mfma_f32_16x16x32_bf16 v[14:17], v[170:173], v[202:205], v[14:17]
	v_mfma_f32_16x16x32_bf16 v[10:13], v[162:165], v[210:213], v[8:11]
	s_setprio 2
	s_barrier
	v_mfma_f32_16x16x32_bf16 v[6:9], v[170:173], v[210:213], v[4:7]
	s_setprio 0
	s_add_i32 s92, s92, 2
	s_add_u32 s90, s90, 0x100
	s_addc_u32 s91, s91, 0
	s_cmp_gt_u32 s92, 61
	s_cbranch_scc1 .LBB0_622
	s_mov_b64 s[42:43], s[44:45]
	s_cmp_lg_u32 s92, 30
	s_cbranch_scc0 .LBB0_619
	s_branch .LBB0_620

; #define PG8_STAGE(bufoff, gbase, voff) do { _Pragma("unroll") for (int _i = 0; _i < 2; ++_i) \
;         asm volatile("s_mov_b32 m0, %2\n\ts_nop 0\n\tglobal_load_lds_dwordx4 %0, %1" :: "v"((voff)[_i]), "s"((const char*)(gbase)), "s"(ldsbase + (unsigned)(bufoff) + ldsw + (unsigned)_i * 8192u) : "memory", "m0"); } while (0)
; #define PG8_LDA(dst, b, h) do { _Pragma("unroll") for (int m = 0; m < 4; ++m) _Pragma("unroll") for (int k = 0; k < 2; ++k) dst[m][k] = *(const PG8_LAS bf16x8*)(lds + PG8_SA(b, h) + aoff + m * 2048 + k * 1024); } while (0)
; #define PG8_WAIT_V(n) asm volatile("s_waitcnt vmcnt(" #n ")" ::: "memory")
; template <class Epi, class Sched, bool ALIGN_EPI = false, bool SP2 = false>
; __device__ __forceinline__ void gemm_phase(PG8_LAS unsigned char* lds, const Gemm g, const Sched& S, const Epi& E) {
;     ...
;             const bool last = (t == nt - 2);
;             const char* a1 = cA + (size_t)(t + 1) * kstep;
;             const char* a2 = last ? nA : cA + (size_t)(t + 2) * kstep; const char* b2 = last ? nB : cB + (size_t)(t + 2) * kstep;
;             const char* a3 = a2 + kstep; const char* b3 = b2 + kstep;
;             if (last && has_next) S.a_ready(nxt);
;             if constexpr (epi_has_mid<Epi>::value) { if (t == Epi::MID_T) E.mid(acc, cur, wr, wc, fr, fq); }
;             if constexpr (SP2) {
;             PG8_LDB(B0, 0, 0); PG8_LDB(B1, 0, 1); PG8_SCHED; PG8_LDA(At, 0, 0); PG8_STAGE(PG8_SA(1, 1), a1 + hstep, voffA);
;             PG8_WAIT_V(8); PG8_WAIT_L(0); PG8_BAR; PG8_MMA(0, 0, At, B0); PG8_MMA(0, 1, At, B1); PG8_BAR; PG8_SCHED;
;             PG8_LDA(At, 0, 1); PG8_STAGE(PG8_SB(0, 0), b2, voffB); PG8_STAGE(PG8_SB(0, 1), b2 + hstep, voffB); PG8_STAGE(PG8_SA(0, 0), a2, voffA);
;             PG8_WAIT_V(8); PG8_WAIT_L(0); PG8_BAR; PG8_MMA(1, 0, At, B0); PG8_MMA(1, 1, At, B1); PG8_BAR; PG8_SCHED;
;             PG8_LDB(B0, 1, 0); PG8_LDB(B1, 1, 1); PG8_SCHED; PG8_LDA(At, 1, 0); PG8_STAGE(PG8_SA(0, 1), a2 + hstep, voffA);
;             PG8_WAIT_V(8); PG8_WAIT_L(0); PG8_BAR; PG8_MMA(0, 0, At, B0); PG8_MMA(0, 1, At, B1); PG8_BAR; PG8_SCHED;
;             PG8_LDA(At, 1, 1); PG8_STAGE(PG8_SB(1, 0), b3, voffB); PG8_STAGE(PG8_SB(1, 1), b3 + hstep, voffB); PG8_STAGE(PG8_SA(1, 0), a3, voffA);
;             PG8_WAIT_V(8); PG8_WAIT_L(0); PG8_BAR; PG8_MMA(1, 0, At, B0); PG8_MMA(1, 1, At, B1); PG8_BAR; PG8_SCHED;
.LBB0_698:
	ds_read_b128 v[134:137], v145
	ds_read_b128 v[152:155], v145 offset:1024
	ds_read_b128 v[156:159], v145 offset:2048
	ds_read_b128 v[160:163], v145 offset:3072
	ds_read_b128 v[164:167], v146
	ds_read_b128 v[168:171], v146 offset:1024
	ds_read_b128 v[172:175], v146 offset:2048
	ds_read_b128 v[176:179], v146 offset:3072
	s_cmp_eq_u32 s69, 60
	s_cselect_b32 s48, s41, s53
	s_cselect_b32 s49, s19, s58
	s_cselect_b32 s46, s52, s59
	s_cselect_b32 s47, s17, s68
	s_add_u32 s44, s48, 0x80
	s_addc_u32 s45, s49, 0
	ds_read_b128 v[180:183], v147
	ds_read_b128 v[184:187], v147 offset:1024
	ds_read_b128 v[188:191], v147 offset:2048
	ds_read_b128 v[192:195], v147 offset:3072
	ds_read_b128 v[196:199], v147 offset:4096
	ds_read_b128 v[200:203], v147 offset:5120
	ds_read_b128 v[204:207], v147 offset:6144
	ds_read_b128 v[208:211], v147 offset:7168
	s_mov_b32 m0, s67
	s_nop 0
	global_load_lds_dwordx4 v1, s[42:43]
	s_nop 0
	s_mov_b32 m0, s74
	s_nop 0
	global_load_lds_dwordx4 v141, s[42:43]
	s_waitcnt vmcnt(8)
	s_waitcnt lgkmcnt(0)
	s_barrier
	s_setprio 1
	s_waitcnt lgkmcnt(7)
	v_mfma_f32_16x16x32_bf16 v[126:129], v[134:137], v[180:183], v[126:129]
	v_mfma_f32_16x16x32_bf16 v[122:125], v[156:159], v[180:183], v[122:125]
	s_waitcnt lgkmcnt(5)
	v_mfma_f32_16x16x32_bf16 v[110:113], v[134:137], v[188:191], v[110:113]
	v_mfma_f32_16x16x32_bf16 v[106:109], v[156:159], v[188:191], v[106:109]
	s_waitcnt lgkmcnt(3)
	v_mfma_f32_16x16x32_bf16 v[94:97], v[134:137], v[196:199], v[94:97]
	v_mfma_f32_16x16x32_bf16 v[90:93], v[156:159], v[196:199], v[90:93]
	s_waitcnt lgkmcnt(1)
	v_mfma_f32_16x16x32_bf16 v[78:81], v[134:137], v[204:207], v[78:81]
	v_mfma_f32_16x16x32_bf16 v[74:77], v[156:159], v[204:207], v[74:77]
	v_mfma_f32_16x16x32_bf16 v[126:129], v[152:155], v[184:187], v[126:129]
	v_mfma_f32_16x16x32_bf16 v[122:125], v[160:163], v[184:187], v[122:125]
	v_mfma_f32_16x16x32_bf16 v[110:113], v[152:155], v[192:195], v[110:113]
	v_mfma_f32_16x16x32_bf16 v[106:109], v[160:163], v[192:195], v[106:109]
	v_mfma_f32_16x16x32_bf16 v[94:97], v[152:155], v[200:203], v[94:97]
	v_mfma_f32_16x16x32_bf16 v[90:93], v[160:163], v[200:203], v[90:93]
	s_waitcnt lgkmcnt(0)
	v_mfma_f32_16x16x32_bf16 v[78:81], v[152:155], v[208:211], v[78:81]
	v_mfma_f32_16x16x32_bf16 v[74:77], v[160:163], v[208:211], v[74:77]
	s_setprio 0
	s_setprio 1
	v_mfma_f32_16x16x32_bf16 v[118:121], v[164:167], v[180:183], v[118:121]
	v_mfma_f32_16x16x32_bf16 v[114:117], v[172:175], v[180:183], v[114:117]
	v_mfma_f32_16x16x32_bf16 v[102:105], v[164:167], v[188:191], v[102:105]
	v_mfma_f32_16x16x32_bf16 v[98:101], v[172:175], v[188:191], v[98:101]
	v_mfma_f32_16x16x32_bf16 v[86:89], v[164:167], v[196:199], v[86:89]
	v_mfma_f32_16x16x32_bf16 v[82:85], v[172:175], v[196:199], v[82:85]
	v_mfma_f32_16x16x32_bf16 v[70:73], v[164:167], v[204:207], v[70:73]
	v_mfma_f32_16x16x32_bf16 v[66:69], v[172:175], v[204:207], v[66:69]
	v_mfma_f32_16x16x32_bf16 v[118:121], v[168:171], v[184:187], v[118:121]
	v_mfma_f32_16x16x32_bf16 v[114:117], v[176:179], v[184:187], v[114:117]
	v_mfma_f32_16x16x32_bf16 v[102:105], v[168:171], v[192:195], v[102:105]
	v_mfma_f32_16x16x32_bf16 v[98:101], v[176:179], v[192:195], v[98:101]
	v_mfma_f32_16x16x32_bf16 v[86:89], v[168:171], v[200:203], v[86:89]
	v_mfma_f32_16x16x32_bf16 v[82:85], v[176:179], v[200:203], v[82:85]
	s_setprio 2
	s_barrier
	ds_read_b128 v[180:183], v147 offset:16384
	ds_read_b128 v[184:187], v147 offset:17408
	ds_read_b128 v[188:191], v147 offset:18432
	ds_read_b128 v[192:195], v147 offset:19456
	ds_read_b128 v[196:199], v147 offset:20480
	ds_read_b128 v[200:203], v147 offset:21504
	ds_read_b128 v[204:207], v147 offset:22528
	v_mfma_f32_16x16x32_bf16 v[70:73], v[168:171], v[208:211], v[70:73]
	v_mfma_f32_16x16x32_bf16 v[66:69], v[176:179], v[208:211], v[66:69]
	s_setprio 0
	ds_read_b128 v[208:211], v147 offset:23552
	s_mov_b32 m0, s35
	s_nop 0
	global_load_lds_dwordx4 v140, s[46:47]
	s_add_u32 s70, s46, 0x100000
	s_mov_b32 m0, s50
	s_nop 0
	global_load_lds_dwordx4 v142, s[46:47]
	s_addc_u32 s71, s47, 0
	s_mov_b32 m0, s51
	s_nop 0
	global_load_lds_dwordx4 v140, s[70:71]
	s_nop 0
	s_mov_b32 m0, s54
	s_nop 0
	global_load_lds_dwordx4 v142, s[70:71]
	s_nop 0
	s_mov_b32 m0, s3
	s_nop 0
	global_load_lds_dwordx4 v1, s[48:49]
	s_nop 0
	s_mov_b32 m0, s55
	s_nop 0
	global_load_lds_dwordx4 v141, s[48:49]
	s_waitcnt vmcnt(8)
	s_waitcnt lgkmcnt(0)
	s_barrier
	s_setprio 1
	s_waitcnt lgkmcnt(7)
	v_mfma_f32_16x16x32_bf16 v[62:65], v[134:137], v[180:183], v[62:65]
	v_mfma_f32_16x16x32_bf16 v[58:61], v[156:159], v[180:183], v[58:61]
	s_waitcnt lgkmcnt(5)
	v_mfma_f32_16x16x32_bf16 v[46:49], v[134:137], v[188:191], v[46:49]
	v_mfma_f32_16x16x32_bf16 v[42:45], v[156:159], v[188:191], v[42:45]
	s_waitcnt lgkmcnt(3)
	v_mfma_f32_16x16x32_bf16 v[30:33], v[134:137], v[196:199], v[30:33]
	v_mfma_f32_16x16x32_bf16 v[26:29], v[156:159], v[196:199], v[26:29]
	s_waitcnt lgkmcnt(1)
	v_mfma_f32_16x16x32_bf16 v[14:17], v[134:137], v[204:207], v[14:17]
	v_mfma_f32_16x16x32_bf16 v[10:13], v[156:159], v[204:207], v[10:13]
	v_mfma_f32_16x16x32_bf16 v[62:65], v[152:155], v[184:187], v[62:65]
	v_mfma_f32_16x16x32_bf16 v[58:61], v[160:163], v[184:187], v[58:61]
	v_mfma_f32_16x16x32_bf16 v[46:49], v[152:155], v[192:195], v[46:49]
	v_mfma_f32_16x16x32_bf16 v[42:45], v[160:163], v[192:195], v[42:45]
	v_mfma_f32_16x16x32_bf16 v[30:33], v[152:155], v[200:203], v[30:33]
	v_mfma_f32_16x16x32_bf16 v[26:29], v[160:163], v[200:203], v[26:29]
	s_waitcnt lgkmcnt(0)
	v_mfma_f32_16x16x32_bf16 v[14:17], v[152:155], v[208:211], v[14:17]
	v_mfma_f32_16x16x32_bf16 v[10:13], v[160:163], v[208:211], v[10:13]
	s_setprio 0
	s_setprio 1
	v_mfma_f32_16x16x32_bf16 v[54:57], v[164:167], v[180:183], v[54:57]
	v_mfma_f32_16x16x32_bf16 v[50:53], v[172:175], v[180:183], v[50:53]
	v_mfma_f32_16x16x32_bf16 v[38:41], v[164:167], v[188:191], v[38:41]
	v_mfma_f32_16x16x32_bf16 v[34:37], v[172:175], v[188:191], v[34:37]
	v_mfma_f32_16x16x32_bf16 v[22:25], v[164:167], v[196:199], v[22:25]
	v_mfma_f32_16x16x32_bf16 v[18:21], v[172:175], v[196:199], v[18:21]
	v_mfma_f32_16x16x32_bf16 v[6:9], v[164:167], v[204:207], v[6:9]
	v_mfma_f32_16x16x32_bf16 v[2:5], v[172:175], v[204:207], v[2:5]
	v_mfma_f32_16x16x32_bf16 v[54:57], v[168:171], v[184:187], v[54:57]
	v_mfma_f32_16x16x32_bf16 v[50:53], v[176:179], v[184:187], v[50:53]
	v_mfma_f32_16x16x32_bf16 v[38:41], v[168:171], v[192:195], v[38:41]
	v_mfma_f32_16x16x32_bf16 v[34:37], v[176:179], v[192:195], v[34:37]
	v_mfma_f32_16x16x32_bf16 v[22:25], v[168:171], v[200:203], v[22:25]
	v_mfma_f32_16x16x32_bf16 v[18:21], v[176:179], v[200:203], v[18:21]
	s_setprio 2
	s_barrier
; #define PG8_STAGE(bufoff, gbase, voff) do { _Pragma("unroll") for (int _i = 0; _i < 2; ++_i) \
;         asm volatile("s_mov_b32 m0, %2\n\ts_nop 0\n\tglobal_load_lds_dwordx4 %0, %1" :: "v"((voff)[_i]), "s"((const char*)(gbase)), "s"(ldsbase + (unsigned)(bufoff) + ldsw + (unsigned)_i * 8192u) : "memory", "m0"); } while (0)
; #define PG8_LDA(dst, b, h) do { _Pragma("unroll") for (int m = 0; m < 4; ++m) _Pragma("unroll") for (int k = 0; k < 2; ++k) dst[m][k] = *(const PG8_LAS bf16x8*)(lds + PG8_SA(b, h) + aoff + m * 2048 + k * 1024); } while (0)
; #define PG8_LDB(dst, b, h) do { _Pragma("unroll") for (int n = 0; n < 2; ++n) _Pragma("unroll") for (int k = 0; k < 2; ++k) dst[n][k] = *(const PG8_LAS bf16x8*)(lds + PG8_SB(b, h) + boff + n * 2048 + k * 1024); } while (0)
; #define PG8_MMA(ai, bj, At, Bt) do { __builtin_amdgcn_s_setprio(1); _Pragma("unroll") for (int m = 0; m < 4; ++m) _Pragma("unroll") for (int n = 0; n < 2; ++n) _Pragma("unroll") for (int k = 0; k < 2; ++k) \
;         acc[ai][bj][m][n] = __builtin_amdgcn_mfma_f32_16x16x32_bf16(Bt[n][k], At[m][k], acc[ai][bj][m][n], 0, 0, 0); __builtin_amdgcn_s_setprio(0); } while (0)
; template <class Epi, class Sched, bool ALIGN_EPI = false, bool SP2 = false>
; __device__ __forceinline__ void gemm_phase(PG8_LAS unsigned char* lds, const Gemm g, const Sched& S, const Epi& E) {
;     ...
;             PG8_LDB(B0, 0, 0); PG8_LDB(B1, 0, 1); PG8_SCHED; PG8_LDA(At, 0, 0); PG8_STAGE(PG8_SA(1, 1), a1 + hstep, voffA);
;             PG8_WAIT_V(8); PG8_WAIT_L(0); PG8_BAR; PG8_MMA(0, 0, At, B0); PG8_MMA(0, 1, At, B1); PG8_BAR; PG8_SCHED;
;             PG8_LDA(At, 0, 1); PG8_STAGE(PG8_SB(0, 0), b2, voffB); PG8_STAGE(PG8_SB(0, 1), b2 + hstep, voffB); PG8_STAGE(PG8_SA(0, 0), a2, voffA);
;             PG8_WAIT_V(8); PG8_WAIT_L(0); PG8_BAR; PG8_MMA(1, 0, At, B0); PG8_MMA(1, 1, At, B1); PG8_BAR; PG8_SCHED;
;             PG8_LDB(B0, 1, 0); PG8_LDB(B1, 1, 1); PG8_SCHED; PG8_LDA(At, 1, 0); PG8_STAGE(PG8_SA(0, 1), a2 + hstep, voffA);
;             PG8_WAIT_V(8); PG8_WAIT_L(0); PG8_BAR; PG8_MMA(0, 0, At, B0); PG8_MMA(0, 1, At, B1); PG8_BAR; PG8_SCHED;
;             PG8_LDA(At, 1, 1); PG8_STAGE(PG8_SB(1, 0), b3, voffB); PG8_STAGE(PG8_SB(1, 1), b3 + hstep, voffB); PG8_STAGE(PG8_SA(1, 0), a3, voffA);
;             PG8_WAIT_V(8); PG8_WAIT_L(0); PG8_BAR; PG8_MMA(1, 0, At, B0); PG8_MMA(1, 1, At, B1); PG8_BAR; PG8_SCHED;
	ds_read_b128 v[134:137], v148
	ds_read_b128 v[152:155], v148 offset:1024
	ds_read_b128 v[156:159], v148 offset:2048
	ds_read_b128 v[160:163], v148 offset:3072
	ds_read_b128 v[164:167], v149
	v_mfma_f32_16x16x32_bf16 v[6:9], v[168:171], v[208:211], v[6:9]
	v_mfma_f32_16x16x32_bf16 v[2:5], v[176:179], v[208:211], v[2:5]
	s_setprio 0
	ds_read_b128 v[168:171], v149 offset:1024
	ds_read_b128 v[172:175], v149 offset:2048
	ds_read_b128 v[176:179], v149 offset:3072
	ds_read_b128 v[180:183], v147 offset:32768
	ds_read_b128 v[184:187], v147 offset:33792
	ds_read_b128 v[188:191], v147 offset:34816
	ds_read_b128 v[192:195], v147 offset:35840
	ds_read_b128 v[196:199], v147 offset:36864
	ds_read_b128 v[200:203], v147 offset:37888
	ds_read_b128 v[204:207], v147 offset:38912
	ds_read_b128 v[208:211], v147 offset:39936
	s_add_u32 s48, s48, 0x100000
	s_addc_u32 s49, s49, 0
	s_mov_b32 m0, s56
	s_nop 0
	global_load_lds_dwordx4 v1, s[48:49]
	s_nop 0
	s_mov_b32 m0, s57
	s_nop 0
	global_load_lds_dwordx4 v141, s[48:49]
	s_waitcnt vmcnt(8)
	s_waitcnt lgkmcnt(0)
	s_barrier
	s_setprio 1
	s_waitcnt lgkmcnt(7)
	v_mfma_f32_16x16x32_bf16 v[126:129], v[134:137], v[180:183], v[126:129]
	v_mfma_f32_16x16x32_bf16 v[122:125], v[156:159], v[180:183], v[122:125]
	s_waitcnt lgkmcnt(5)
	v_mfma_f32_16x16x32_bf16 v[110:113], v[134:137], v[188:191], v[110:113]
	v_mfma_f32_16x16x32_bf16 v[106:109], v[156:159], v[188:191], v[106:109]
	s_waitcnt lgkmcnt(3)
	v_mfma_f32_16x16x32_bf16 v[94:97], v[134:137], v[196:199], v[94:97]
	v_mfma_f32_16x16x32_bf16 v[90:93], v[156:159], v[196:199], v[90:93]
	s_waitcnt lgkmcnt(1)
	v_mfma_f32_16x16x32_bf16 v[78:81], v[134:137], v[204:207], v[78:81]
	v_mfma_f32_16x16x32_bf16 v[74:77], v[156:159], v[204:207], v[74:77]
	v_mfma_f32_16x16x32_bf16 v[126:129], v[152:155], v[184:187], v[126:129]
	v_mfma_f32_16x16x32_bf16 v[122:125], v[160:163], v[184:187], v[122:125]
	v_mfma_f32_16x16x32_bf16 v[110:113], v[152:155], v[192:195], v[110:113]
	v_mfma_f32_16x16x32_bf16 v[106:109], v[160:163], v[192:195], v[106:109]
	v_mfma_f32_16x16x32_bf16 v[94:97], v[152:155], v[200:203], v[94:97]
	v_mfma_f32_16x16x32_bf16 v[90:93], v[160:163], v[200:203], v[90:93]
	s_waitcnt lgkmcnt(0)
	v_mfma_f32_16x16x32_bf16 v[78:81], v[152:155], v[208:211], v[78:81]
	v_mfma_f32_16x16x32_bf16 v[74:77], v[160:163], v[208:211], v[74:77]
	s_setprio 0
	s_setprio 1
	v_mfma_f32_16x16x32_bf16 v[118:121], v[164:167], v[180:183], v[118:121]
	v_mfma_f32_16x16x32_bf16 v[114:117], v[172:175], v[180:183], v[114:117]
	v_mfma_f32_16x16x32_bf16 v[102:105], v[164:167], v[188:191], v[102:105]
	v_mfma_f32_16x16x32_bf16 v[98:101], v[172:175], v[188:191], v[98:101]
	v_mfma_f32_16x16x32_bf16 v[86:89], v[164:167], v[196:199], v[86:89]
	v_mfma_f32_16x16x32_bf16 v[82:85], v[172:175], v[196:199], v[82:85]
	v_mfma_f32_16x16x32_bf16 v[70:73], v[164:167], v[204:207], v[70:73]
	v_mfma_f32_16x16x32_bf16 v[66:69], v[172:175], v[204:207], v[66:69]
	v_mfma_f32_16x16x32_bf16 v[118:121], v[168:171], v[184:187], v[118:121]
	v_mfma_f32_16x16x32_bf16 v[114:117], v[176:179], v[184:187], v[114:117]
	v_mfma_f32_16x16x32_bf16 v[102:105], v[168:171], v[192:195], v[102:105]
	v_mfma_f32_16x16x32_bf16 v[98:101], v[176:179], v[192:195], v[98:101]
	v_mfma_f32_16x16x32_bf16 v[86:89], v[168:171], v[200:203], v[86:89]
	v_mfma_f32_16x16x32_bf16 v[82:85], v[176:179], v[200:203], v[82:85]
	s_setprio 2
	s_barrier
; #define PG8_STAGE(bufoff, gbase, voff) do { _Pragma("unroll") for (int _i = 0; _i < 2; ++_i) \
;         asm volatile("s_mov_b32 m0, %2\n\ts_nop 0\n\tglobal_load_lds_dwordx4 %0, %1" :: "v"((voff)[_i]), "s"((const char*)(gbase)), "s"(ldsbase + (unsigned)(bufoff) + ldsw + (unsigned)_i * 8192u) : "memory", "m0"); } while (0)
; #define PG8_LDA(dst, b, h) do { _Pragma("unroll") for (int m = 0; m < 4; ++m) _Pragma("unroll") for (int k = 0; k < 2; ++k) dst[m][k] = *(const PG8_LAS bf16x8*)(lds + PG8_SA(b, h) + aoff + m * 2048 + k * 1024); } while (0)
; #define PG8_BAR __builtin_amdgcn_s_barrier()
; template <class Epi, class Sched, bool ALIGN_EPI = false, bool SP2 = false>
; __device__ __forceinline__ void gemm_phase(PG8_LAS unsigned char* lds, const Gemm g, const Sched& S, const Epi& E) {
;     ...
;         for (int t = 0; t < nt; t += 2) {
;             const bool last = (t == nt - 2);
;             const char* a1 = cA + (size_t)(t + 1) * kstep;
;             const char* a2 = last ? nA : cA + (size_t)(t + 2) * kstep; const char* b2 = last ? nB : cB + (size_t)(t + 2) * kstep;
;             const char* a3 = a2 + kstep; const char* b3 = b2 + kstep;
;             if (last && has_next) S.a_ready(nxt);
;             if constexpr (epi_has_mid<Epi>::value) { if (t == Epi::MID_T) E.mid(acc, cur, wr, wc, fr, fq); }
;             if constexpr (SP2) {
;             PG8_LDB(B0, 0, 0); PG8_LDB(B1, 0, 1); PG8_SCHED; PG8_LDA(At, 0, 0); PG8_STAGE(PG8_SA(1, 1), a1 + hstep, voffA);
;             PG8_WAIT_V(8); PG8_WAIT_L(0); PG8_BAR; PG8_MMA(0, 0, At, B0); PG8_MMA(0, 1, At, B1); PG8_BAR; PG8_SCHED;
;             PG8_LDA(At, 0, 1); PG8_STAGE(PG8_SB(0, 0), b2, voffB); PG8_STAGE(PG8_SB(0, 1), b2 + hstep, voffB); PG8_STAGE(PG8_SA(0, 0), a2, voffA);
;             PG8_WAIT_V(8); PG8_WAIT_L(0); PG8_BAR; PG8_MMA(1, 0, At, B0); PG8_MMA(1, 1, At, B1); PG8_BAR; PG8_SCHED;
;             PG8_LDB(B0, 1, 0); PG8_LDB(B1, 1, 1); PG8_SCHED; PG8_LDA(At, 1, 0); PG8_STAGE(PG8_SA(0, 1), a2 + hstep, voffA);
;             PG8_WAIT_V(8); PG8_WAIT_L(0); PG8_BAR; PG8_MMA(0, 0, At, B0); PG8_MMA(0, 1, At, B1); PG8_BAR; PG8_SCHED;
;             PG8_LDA(At, 1, 1); PG8_STAGE(PG8_SB(1, 0), b3, voffB); PG8_STAGE(PG8_SB(1, 1), b3 + hstep, voffB); PG8_STAGE(PG8_SA(1, 0), a3, voffA);
;             PG8_WAIT_V(8); PG8_WAIT_L(0); PG8_BAR; PG8_MMA(1, 0, At, B0); PG8_MMA(1, 1, At, B1); PG8_BAR; PG8_SCHED;
	ds_read_b128 v[180:183], v147 offset:49152
	ds_read_b128 v[184:187], v147 offset:50176
	ds_read_b128 v[188:191], v147 offset:51200
	ds_read_b128 v[192:195], v147 offset:52224
	ds_read_b128 v[196:199], v147 offset:53248
	ds_read_b128 v[200:203], v147 offset:54272
	ds_read_b128 v[204:207], v147 offset:55296
	v_mfma_f32_16x16x32_bf16 v[70:73], v[168:171], v[208:211], v[70:73]
	v_mfma_f32_16x16x32_bf16 v[66:69], v[176:179], v[208:211], v[66:69]
	s_setprio 0
	ds_read_b128 v[208:211], v147 offset:56320
	s_add_u32 s48, s46, 0x80
	s_addc_u32 s49, s47, 0
	s_mov_b32 m0, s61
	s_nop 0
	global_load_lds_dwordx4 v140, s[48:49]
	s_add_u32 s46, s46, 0x100080
	s_mov_b32 m0, s62
	s_nop 0
	global_load_lds_dwordx4 v142, s[48:49]
	s_addc_u32 s47, s47, 0
	s_mov_b32 m0, s65
	s_nop 0
	global_load_lds_dwordx4 v140, s[46:47]
	s_nop 0
	s_mov_b32 m0, s66
	s_nop 0
	global_load_lds_dwordx4 v142, s[46:47]
	s_nop 0
	s_mov_b32 m0, s63
	s_nop 0
	global_load_lds_dwordx4 v1, s[44:45]
	s_nop 0
	s_mov_b32 m0, s64
	s_nop 0
	global_load_lds_dwordx4 v141, s[44:45]
	s_waitcnt vmcnt(8)
	s_waitcnt lgkmcnt(0)
	s_barrier
	s_setprio 1
	s_waitcnt lgkmcnt(7)
	v_mfma_f32_16x16x32_bf16 v[62:65], v[134:137], v[180:183], v[62:65]
	v_mfma_f32_16x16x32_bf16 v[58:61], v[156:159], v[180:183], v[58:61]
	s_waitcnt lgkmcnt(5)
	v_mfma_f32_16x16x32_bf16 v[46:49], v[134:137], v[188:191], v[46:49]
	v_mfma_f32_16x16x32_bf16 v[42:45], v[156:159], v[188:191], v[42:45]
	s_waitcnt lgkmcnt(3)
	v_mfma_f32_16x16x32_bf16 v[30:33], v[134:137], v[196:199], v[30:33]
	v_mfma_f32_16x16x32_bf16 v[26:29], v[156:159], v[196:199], v[26:29]
	s_waitcnt lgkmcnt(1)
	v_mfma_f32_16x16x32_bf16 v[14:17], v[134:137], v[204:207], v[14:17]
	v_mfma_f32_16x16x32_bf16 v[10:13], v[156:159], v[204:207], v[10:13]
	v_mfma_f32_16x16x32_bf16 v[62:65], v[152:155], v[184:187], v[62:65]
	v_mfma_f32_16x16x32_bf16 v[58:61], v[160:163], v[184:187], v[58:61]
	v_mfma_f32_16x16x32_bf16 v[46:49], v[152:155], v[192:195], v[46:49]
	v_mfma_f32_16x16x32_bf16 v[42:45], v[160:163], v[192:195], v[42:45]
	v_mfma_f32_16x16x32_bf16 v[30:33], v[152:155], v[200:203], v[30:33]
	v_mfma_f32_16x16x32_bf16 v[26:29], v[160:163], v[200:203], v[26:29]
	s_waitcnt lgkmcnt(0)
	v_mfma_f32_16x16x32_bf16 v[14:17], v[152:155], v[208:211], v[14:17]
	v_mfma_f32_16x16x32_bf16 v[10:13], v[160:163], v[208:211], v[10:13]
	s_setprio 0
	s_setprio 1
	v_mfma_f32_16x16x32_bf16 v[54:57], v[164:167], v[180:183], v[54:57]
	v_mfma_f32_16x16x32_bf16 v[50:53], v[172:175], v[180:183], v[50:53]
	v_mfma_f32_16x16x32_bf16 v[38:41], v[164:167], v[188:191], v[38:41]
	v_mfma_f32_16x16x32_bf16 v[34:37], v[172:175], v[188:191], v[34:37]
	v_mfma_f32_16x16x32_bf16 v[22:25], v[164:167], v[196:199], v[22:25]
	v_mfma_f32_16x16x32_bf16 v[18:21], v[172:175], v[196:199], v[18:21]
	v_mfma_f32_16x16x32_bf16 v[6:9], v[164:167], v[204:207], v[6:9]
	v_mfma_f32_16x16x32_bf16 v[2:5], v[172:175], v[204:207], v[2:5]
	v_mfma_f32_16x16x32_bf16 v[54:57], v[168:171], v[184:187], v[54:57]
	v_mfma_f32_16x16x32_bf16 v[50:53], v[176:179], v[184:187], v[50:53]
	v_mfma_f32_16x16x32_bf16 v[38:41], v[168:171], v[192:195], v[38:41]
	v_mfma_f32_16x16x32_bf16 v[34:37], v[176:179], v[192:195], v[34:37]
	v_mfma_f32_16x16x32_bf16 v[22:25], v[168:171], v[200:203], v[22:25]
	v_mfma_f32_16x16x32_bf16 v[18:21], v[176:179], v[200:203], v[18:21]
	v_mfma_f32_16x16x32_bf16 v[6:9], v[168:171], v[208:211], v[6:9]
	s_setprio 2
	s_barrier
	v_mfma_f32_16x16x32_bf16 v[2:5], v[176:179], v[208:211], v[2:5]
	s_setprio 0
	s_add_i32 s69, s69, 2
	s_add_u32 s53, s53, 0x100
	s_addc_u32 s58, s58, 0
	s_add_u32 s59, s59, 0x100
	s_addc_u32 s68, s68, 0
	s_add_u32 s42, s42, 0x100
	s_addc_u32 s43, s43, 0
	s_cmp_gt_u32 s69, 61
	s_cbranch_scc0 .LBB0_698
	s_and_b64 vcc, exec, s[14:15]
	s_cbranch_vccz .LBB0_701
	s_barrier

; #define PG8_STAGE(bufoff, gbase, voff) do { _Pragma("unroll") for (int _i = 0; _i < 2; ++_i) \
;         asm volatile("s_mov_b32 m0, %2\n\ts_nop 0\n\tglobal_load_lds_dwordx4 %0, %1" :: "v"((voff)[_i]), "s"((const char*)(gbase)), "s"(ldsbase + (unsigned)(bufoff) + ldsw + (unsigned)_i * 8192u) : "memory", "m0"); } while (0)
; #define PG8_LDA(dst, b, h) do { _Pragma("unroll") for (int m = 0; m < 4; ++m) _Pragma("unroll") for (int k = 0; k < 2; ++k) dst[m][k] = *(const PG8_LAS bf16x8*)(lds + PG8_SA(b, h) + aoff + m * 2048 + k * 1024); } while (0)
; #define PG8_WAIT_V(n) asm volatile("s_waitcnt vmcnt(" #n ")" ::: "memory")
; template <class Epi, class Sched, bool ALIGN_EPI = false, bool SP2 = false>
; __device__ __forceinline__ void gemm_phase(PG8_LAS unsigned char* lds, const Gemm g, const Sched& S, const Epi& E) {
;     ...
;             const bool last = (t == nt - 2);
;             const char* a1 = cA + (size_t)(t + 1) * kstep;
;             const char* a2 = last ? nA : cA + (size_t)(t + 2) * kstep; const char* b2 = last ? nB : cB + (size_t)(t + 2) * kstep;
;             const char* a3 = a2 + kstep; const char* b3 = b2 + kstep;
;             if (last && has_next) S.a_ready(nxt);
;             if constexpr (epi_has_mid<Epi>::value) { if (t == Epi::MID_T) E.mid(acc, cur, wr, wc, fr, fq); }
;             if constexpr (SP2) {
;             PG8_LDB(B0, 0, 0); PG8_LDB(B1, 0, 1); PG8_SCHED; PG8_LDA(At, 0, 0); PG8_STAGE(PG8_SA(1, 1), a1 + hstep, voffA);
;             PG8_WAIT_V(8); PG8_WAIT_L(0); PG8_BAR; PG8_MMA(0, 0, At, B0); PG8_MMA(0, 1, At, B1); PG8_BAR; PG8_SCHED;
;             PG8_LDA(At, 0, 1); PG8_STAGE(PG8_SB(0, 0), b2, voffB); PG8_STAGE(PG8_SB(0, 1), b2 + hstep, voffB); PG8_STAGE(PG8_SA(0, 0), a2, voffA);
;             PG8_WAIT_V(8); PG8_WAIT_L(0); PG8_BAR; PG8_MMA(1, 0, At, B0); PG8_MMA(1, 1, At, B1); PG8_BAR; PG8_SCHED;
;             PG8_LDB(B0, 1, 0); PG8_LDB(B1, 1, 1); PG8_SCHED; PG8_LDA(At, 1, 0); PG8_STAGE(PG8_SA(0, 1), a2 + hstep, voffA);
;             PG8_WAIT_V(8); PG8_WAIT_L(0); PG8_BAR; PG8_MMA(0, 0, At, B0); PG8_MMA(0, 1, At, B1); PG8_BAR; PG8_SCHED;
;             PG8_LDA(At, 1, 1); PG8_STAGE(PG8_SB(1, 0), b3, voffB); PG8_STAGE(PG8_SB(1, 1), b3 + hstep, voffB); PG8_STAGE(PG8_SA(1, 0), a3, voffA);
;             PG8_WAIT_V(8); PG8_WAIT_L(0); PG8_BAR; PG8_MMA(1, 0, At, B0); PG8_MMA(1, 1, At, B1); PG8_BAR; PG8_SCHED;
.LBB0_789:
	v_add_u32_e32 v164, 0x10000, v149
	v_add_u32_e32 v180, 0x14000, v149
	s_add_u32 s8, s40, 0x100
	s_waitcnt lgkmcnt(0)
	ds_read_b128 v[152:155], v164
	ds_read_b128 v[156:159], v164 offset:1024
	ds_read_b128 v[160:163], v164 offset:2048
	ds_read_b128 v[164:167], v164 offset:3072
	ds_read_b128 v[168:171], v180
	ds_read_b128 v[172:175], v180 offset:1024
	ds_read_b128 v[176:179], v180 offset:2048
	ds_read_b128 v[180:183], v180 offset:3072
	s_addc_u32 s9, s41, 0
	s_and_b64 s[38:39], s[38:39], exec
	s_cselect_b32 s46, s59, s8
	s_cselect_b32 s47, s17, s9
	s_cselect_b32 s39, s15, s75
	s_cselect_b32 s38, s71, s74
	s_add_u32 s42, s46, 0x80
	s_addc_u32 s43, s47, 0
	s_add_u32 s44, s38, 0x80
	s_addc_u32 s45, s39, 0
	ds_read_b128 v[184:187], v150
	ds_read_b128 v[188:191], v150 offset:1024
	ds_read_b128 v[192:195], v150 offset:2048
	ds_read_b128 v[196:199], v150 offset:3072
	ds_read_b128 v[200:203], v150 offset:4096
	ds_read_b128 v[204:207], v150 offset:5120
	ds_read_b128 v[208:211], v150 offset:6144
	ds_read_b128 v[212:215], v150 offset:7168
	s_add_u32 s40, s40, 0x100080
	s_addc_u32 s41, s41, 0
	s_mov_b32 m0, s64
	s_nop 0
	global_load_lds_dwordx4 v139, s[40:41]
	s_nop 0
	s_mov_b32 m0, s65
	s_nop 0
	global_load_lds_dwordx4 v141, s[40:41]
	s_waitcnt vmcnt(8)
	s_waitcnt lgkmcnt(0)
	s_barrier
	s_setprio 1
	s_waitcnt lgkmcnt(7)
	v_mfma_f32_16x16x32_bf16 v[126:129], v[152:155], v[184:187], v[126:129]
	v_mfma_f32_16x16x32_bf16 v[122:125], v[160:163], v[184:187], v[122:125]
	s_waitcnt lgkmcnt(5)
	v_mfma_f32_16x16x32_bf16 v[110:113], v[152:155], v[192:195], v[110:113]
	v_mfma_f32_16x16x32_bf16 v[106:109], v[160:163], v[192:195], v[106:109]
	s_waitcnt lgkmcnt(3)
	v_mfma_f32_16x16x32_bf16 v[94:97], v[152:155], v[200:203], v[94:97]
	v_mfma_f32_16x16x32_bf16 v[90:93], v[160:163], v[200:203], v[90:93]
	s_waitcnt lgkmcnt(1)
	v_mfma_f32_16x16x32_bf16 v[78:81], v[152:155], v[208:211], v[78:81]
	v_mfma_f32_16x16x32_bf16 v[74:77], v[160:163], v[208:211], v[74:77]
	v_mfma_f32_16x16x32_bf16 v[126:129], v[156:159], v[188:191], v[126:129]
	v_mfma_f32_16x16x32_bf16 v[122:125], v[164:167], v[188:191], v[122:125]
	v_mfma_f32_16x16x32_bf16 v[110:113], v[156:159], v[196:199], v[110:113]
	v_mfma_f32_16x16x32_bf16 v[106:109], v[164:167], v[196:199], v[106:109]
	v_mfma_f32_16x16x32_bf16 v[94:97], v[156:159], v[204:207], v[94:97]
	v_mfma_f32_16x16x32_bf16 v[90:93], v[164:167], v[204:207], v[90:93]
	s_waitcnt lgkmcnt(0)
	v_mfma_f32_16x16x32_bf16 v[78:81], v[156:159], v[212:215], v[78:81]
	v_mfma_f32_16x16x32_bf16 v[74:77], v[164:167], v[212:215], v[74:77]
	s_setprio 0
	s_setprio 1
	v_mfma_f32_16x16x32_bf16 v[118:121], v[168:171], v[184:187], v[118:121]
	v_mfma_f32_16x16x32_bf16 v[114:117], v[176:179], v[184:187], v[114:117]
	v_mfma_f32_16x16x32_bf16 v[102:105], v[168:171], v[192:195], v[102:105]
	v_mfma_f32_16x16x32_bf16 v[98:101], v[176:179], v[192:195], v[98:101]
	v_mfma_f32_16x16x32_bf16 v[86:89], v[168:171], v[200:203], v[86:89]
	v_mfma_f32_16x16x32_bf16 v[82:85], v[176:179], v[200:203], v[82:85]
	v_mfma_f32_16x16x32_bf16 v[70:73], v[168:171], v[208:211], v[70:73]
	v_mfma_f32_16x16x32_bf16 v[66:69], v[176:179], v[208:211], v[66:69]
	v_mfma_f32_16x16x32_bf16 v[118:121], v[172:175], v[188:191], v[118:121]
	v_mfma_f32_16x16x32_bf16 v[114:117], v[180:183], v[188:191], v[114:117]
	v_mfma_f32_16x16x32_bf16 v[102:105], v[172:175], v[196:199], v[102:105]
	v_mfma_f32_16x16x32_bf16 v[98:101], v[180:183], v[196:199], v[98:101]
	v_mfma_f32_16x16x32_bf16 v[86:89], v[172:175], v[204:207], v[86:89]
	v_mfma_f32_16x16x32_bf16 v[82:85], v[180:183], v[204:207], v[82:85]
	s_setprio 2
	s_barrier
	ds_read_b128 v[184:187], v150 offset:16384
	ds_read_b128 v[188:191], v150 offset:17408
	ds_read_b128 v[192:195], v150 offset:18432
	ds_read_b128 v[196:199], v150 offset:19456
	ds_read_b128 v[200:203], v150 offset:20480
	ds_read_b128 v[204:207], v150 offset:21504
	ds_read_b128 v[208:211], v150 offset:22528
	v_mfma_f32_16x16x32_bf16 v[70:73], v[172:175], v[212:215], v[70:73]
	v_mfma_f32_16x16x32_bf16 v[66:69], v[180:183], v[212:215], v[66:69]
	s_setprio 0
	ds_read_b128 v[212:215], v150 offset:23552
	s_mov_b32 m0, s49
	s_nop 0
	global_load_lds_dwordx4 v140, s[38:39]
	s_add_u32 s40, s38, 0x100000
	s_mov_b32 m0, s50
	s_nop 0
	global_load_lds_dwordx4 v142, s[38:39]
	s_addc_u32 s41, s39, 0
	s_mov_b32 m0, s51
	s_nop 0
	global_load_lds_dwordx4 v140, s[40:41]
	s_nop 0
	s_mov_b32 m0, s52
	s_nop 0
	global_load_lds_dwordx4 v142, s[40:41]
	s_nop 0
	s_mov_b32 m0, s37
	s_nop 0
	global_load_lds_dwordx4 v139, s[46:47]
	s_nop 0
	s_mov_b32 m0, s53
	s_nop 0
	global_load_lds_dwordx4 v141, s[46:47]
	s_waitcnt vmcnt(8)
	s_waitcnt lgkmcnt(0)
	s_barrier
; #define PG8_STAGE(bufoff, gbase, voff) do { _Pragma("unroll") for (int _i = 0; _i < 2; ++_i) \
;         asm volatile("s_mov_b32 m0, %2\n\ts_nop 0\n\tglobal_load_lds_dwordx4 %0, %1" :: "v"((voff)[_i]), "s"((const char*)(gbase)), "s"(ldsbase + (unsigned)(bufoff) + ldsw + (unsigned)_i * 8192u) : "memory", "m0"); } while (0)
; #define PG8_LDA(dst, b, h) do { _Pragma("unroll") for (int m = 0; m < 4; ++m) _Pragma("unroll") for (int k = 0; k < 2; ++k) dst[m][k] = *(const PG8_LAS bf16x8*)(lds + PG8_SA(b, h) + aoff + m * 2048 + k * 1024); } while (0)
; #define PG8_LDB(dst, b, h) do { _Pragma("unroll") for (int n = 0; n < 2; ++n) _Pragma("unroll") for (int k = 0; k < 2; ++k) dst[n][k] = *(const PG8_LAS bf16x8*)(lds + PG8_SB(b, h) + boff + n * 2048 + k * 1024); } while (0)
; #define PG8_MMA(ai, bj, At, Bt) do { __builtin_amdgcn_s_setprio(1); _Pragma("unroll") for (int m = 0; m < 4; ++m) _Pragma("unroll") for (int n = 0; n < 2; ++n) _Pragma("unroll") for (int k = 0; k < 2; ++k) \
;         acc[ai][bj][m][n] = __builtin_amdgcn_mfma_f32_16x16x32_bf16(Bt[n][k], At[m][k], acc[ai][bj][m][n], 0, 0, 0); __builtin_amdgcn_s_setprio(0); } while (0)
; template <class Epi, class Sched, bool ALIGN_EPI = false, bool SP2 = false>
; __device__ __forceinline__ void gemm_phase(PG8_LAS unsigned char* lds, const Gemm g, const Sched& S, const Epi& E) {
;     ...
;             PG8_LDB(B0, 0, 0); PG8_LDB(B1, 0, 1); PG8_SCHED; PG8_LDA(At, 0, 0); PG8_STAGE(PG8_SA(1, 1), a1 + hstep, voffA);
;             PG8_WAIT_V(8); PG8_WAIT_L(0); PG8_BAR; PG8_MMA(0, 0, At, B0); PG8_MMA(0, 1, At, B1); PG8_BAR; PG8_SCHED;
;             PG8_LDA(At, 0, 1); PG8_STAGE(PG8_SB(0, 0), b2, voffB); PG8_STAGE(PG8_SB(0, 1), b2 + hstep, voffB); PG8_STAGE(PG8_SA(0, 0), a2, voffA);
;             PG8_WAIT_V(8); PG8_WAIT_L(0); PG8_BAR; PG8_MMA(1, 0, At, B0); PG8_MMA(1, 1, At, B1); PG8_BAR; PG8_SCHED;
;             PG8_LDB(B0, 1, 0); PG8_LDB(B1, 1, 1); PG8_SCHED; PG8_LDA(At, 1, 0); PG8_STAGE(PG8_SA(0, 1), a2 + hstep, voffA);
;             PG8_WAIT_V(8); PG8_WAIT_L(0); PG8_BAR; PG8_MMA(0, 0, At, B0); PG8_MMA(0, 1, At, B1); PG8_BAR; PG8_SCHED;
;             PG8_LDA(At, 1, 1); PG8_STAGE(PG8_SB(1, 0), b3, voffB); PG8_STAGE(PG8_SB(1, 1), b3 + hstep, voffB); PG8_STAGE(PG8_SA(1, 0), a3, voffA);
;             PG8_WAIT_V(8); PG8_WAIT_L(0); PG8_BAR; PG8_MMA(1, 0, At, B0); PG8_MMA(1, 1, At, B1); PG8_BAR; PG8_SCHED;
	s_setprio 1
	s_waitcnt lgkmcnt(7)
	v_mfma_f32_16x16x32_bf16 v[62:65], v[152:155], v[184:187], v[62:65]
	v_mfma_f32_16x16x32_bf16 v[58:61], v[160:163], v[184:187], v[58:61]
	s_waitcnt lgkmcnt(5)
	v_mfma_f32_16x16x32_bf16 v[46:49], v[152:155], v[192:195], v[46:49]
	v_mfma_f32_16x16x32_bf16 v[42:45], v[160:163], v[192:195], v[42:45]
	s_waitcnt lgkmcnt(3)
	v_mfma_f32_16x16x32_bf16 v[30:33], v[152:155], v[200:203], v[30:33]
	v_mfma_f32_16x16x32_bf16 v[26:29], v[160:163], v[200:203], v[26:29]
	s_waitcnt lgkmcnt(1)
	v_mfma_f32_16x16x32_bf16 v[14:17], v[152:155], v[208:211], v[14:17]
	v_mfma_f32_16x16x32_bf16 v[10:13], v[160:163], v[208:211], v[10:13]
	v_mfma_f32_16x16x32_bf16 v[62:65], v[156:159], v[188:191], v[62:65]
	v_mfma_f32_16x16x32_bf16 v[58:61], v[164:167], v[188:191], v[58:61]
	v_mfma_f32_16x16x32_bf16 v[46:49], v[156:159], v[196:199], v[46:49]
	v_mfma_f32_16x16x32_bf16 v[42:45], v[164:167], v[196:199], v[42:45]
	v_mfma_f32_16x16x32_bf16 v[30:33], v[156:159], v[204:207], v[30:33]
	v_mfma_f32_16x16x32_bf16 v[26:29], v[164:167], v[204:207], v[26:29]
	s_waitcnt lgkmcnt(0)
	v_mfma_f32_16x16x32_bf16 v[14:17], v[156:159], v[212:215], v[14:17]
	v_mfma_f32_16x16x32_bf16 v[10:13], v[164:167], v[212:215], v[10:13]
	s_setprio 0
	s_setprio 1
	v_mfma_f32_16x16x32_bf16 v[54:57], v[168:171], v[184:187], v[54:57]
	v_mfma_f32_16x16x32_bf16 v[50:53], v[176:179], v[184:187], v[50:53]
	v_mfma_f32_16x16x32_bf16 v[38:41], v[168:171], v[192:195], v[38:41]
	v_mfma_f32_16x16x32_bf16 v[34:37], v[176:179], v[192:195], v[34:37]
	v_mfma_f32_16x16x32_bf16 v[22:25], v[168:171], v[200:203], v[22:25]
	v_mfma_f32_16x16x32_bf16 v[18:21], v[176:179], v[200:203], v[18:21]
	v_mfma_f32_16x16x32_bf16 v[6:9], v[168:171], v[208:211], v[6:9]
	v_mfma_f32_16x16x32_bf16 v[2:5], v[176:179], v[208:211], v[2:5]
	v_mfma_f32_16x16x32_bf16 v[54:57], v[172:175], v[188:191], v[54:57]
	v_mfma_f32_16x16x32_bf16 v[50:53], v[180:183], v[188:191], v[50:53]
	v_mfma_f32_16x16x32_bf16 v[38:41], v[172:175], v[196:199], v[38:41]
	v_mfma_f32_16x16x32_bf16 v[34:37], v[180:183], v[196:199], v[34:37]
	v_mfma_f32_16x16x32_bf16 v[22:25], v[172:175], v[204:207], v[22:25]
	v_mfma_f32_16x16x32_bf16 v[18:21], v[180:183], v[204:207], v[18:21]
	s_setprio 2
	s_barrier
	v_mfma_f32_16x16x32_bf16 v[6:9], v[172:175], v[212:215], v[6:9]
	v_mfma_f32_16x16x32_bf16 v[2:5], v[180:183], v[212:215], v[2:5]
	s_setprio 0
	v_add_u32_e32 v164, 0x18000, v149
	v_add_u32_e32 v180, 0x1c000, v149
	ds_read_b128 v[152:155], v164
	ds_read_b128 v[156:159], v164 offset:1024
	ds_read_b128 v[160:163], v164 offset:2048
	ds_read_b128 v[164:167], v164 offset:3072
	ds_read_b128 v[168:171], v180
	ds_read_b128 v[172:175], v180 offset:1024
	ds_read_b128 v[176:179], v180 offset:2048
	ds_read_b128 v[180:183], v180 offset:3072
	ds_read_b128 v[184:187], v150 offset:32768
	ds_read_b128 v[188:191], v150 offset:33792
	ds_read_b128 v[192:195], v150 offset:34816
	ds_read_b128 v[196:199], v150 offset:35840
	ds_read_b128 v[200:203], v150 offset:36864
	ds_read_b128 v[204:207], v150 offset:37888
	ds_read_b128 v[208:211], v150 offset:38912
	ds_read_b128 v[212:215], v150 offset:39936
	s_add_u32 s40, s46, 0x100000
	s_addc_u32 s41, s47, 0
	s_mov_b32 m0, s54
	s_nop 0
	global_load_lds_dwordx4 v139, s[40:41]
	s_nop 0
	s_mov_b32 m0, s55
	s_nop 0
	global_load_lds_dwordx4 v141, s[40:41]
	s_waitcnt vmcnt(8)
	s_waitcnt lgkmcnt(0)
	s_barrier
	s_setprio 1
	s_waitcnt lgkmcnt(7)
	v_mfma_f32_16x16x32_bf16 v[126:129], v[152:155], v[184:187], v[126:129]
	v_mfma_f32_16x16x32_bf16 v[122:125], v[160:163], v[184:187], v[122:125]
	s_waitcnt lgkmcnt(5)
	v_mfma_f32_16x16x32_bf16 v[110:113], v[152:155], v[192:195], v[110:113]
	v_mfma_f32_16x16x32_bf16 v[106:109], v[160:163], v[192:195], v[106:109]
	s_waitcnt lgkmcnt(3)
	v_mfma_f32_16x16x32_bf16 v[94:97], v[152:155], v[200:203], v[94:97]
	v_mfma_f32_16x16x32_bf16 v[90:93], v[160:163], v[200:203], v[90:93]
	s_waitcnt lgkmcnt(1)
	v_mfma_f32_16x16x32_bf16 v[78:81], v[152:155], v[208:211], v[78:81]
	v_mfma_f32_16x16x32_bf16 v[74:77], v[160:163], v[208:211], v[74:77]
	v_mfma_f32_16x16x32_bf16 v[126:129], v[156:159], v[188:191], v[126:129]
	v_mfma_f32_16x16x32_bf16 v[122:125], v[164:167], v[188:191], v[122:125]
	v_mfma_f32_16x16x32_bf16 v[110:113], v[156:159], v[196:199], v[110:113]
	v_mfma_f32_16x16x32_bf16 v[106:109], v[164:167], v[196:199], v[106:109]
	v_mfma_f32_16x16x32_bf16 v[94:97], v[156:159], v[204:207], v[94:97]
	v_mfma_f32_16x16x32_bf16 v[90:93], v[164:167], v[204:207], v[90:93]
	s_waitcnt lgkmcnt(0)
	v_mfma_f32_16x16x32_bf16 v[78:81], v[156:159], v[212:215], v[78:81]
	v_mfma_f32_16x16x32_bf16 v[74:77], v[164:167], v[212:215], v[74:77]
	s_setprio 0
	s_setprio 1
	v_mfma_f32_16x16x32_bf16 v[118:121], v[168:171], v[184:187], v[118:121]
	v_mfma_f32_16x16x32_bf16 v[114:117], v[176:179], v[184:187], v[114:117]
	v_mfma_f32_16x16x32_bf16 v[102:105], v[168:171], v[192:195], v[102:105]
	v_mfma_f32_16x16x32_bf16 v[98:101], v[176:179], v[192:195], v[98:101]
	v_mfma_f32_16x16x32_bf16 v[86:89], v[168:171], v[200:203], v[86:89]
	v_mfma_f32_16x16x32_bf16 v[82:85], v[176:179], v[200:203], v[82:85]
	v_mfma_f32_16x16x32_bf16 v[70:73], v[168:171], v[208:211], v[70:73]
	v_mfma_f32_16x16x32_bf16 v[66:69], v[176:179], v[208:211], v[66:69]
	v_mfma_f32_16x16x32_bf16 v[118:121], v[172:175], v[188:191], v[118:121]
	v_mfma_f32_16x16x32_bf16 v[114:117], v[180:183], v[188:191], v[114:117]
	v_mfma_f32_16x16x32_bf16 v[102:105], v[172:175], v[196:199], v[102:105]
	v_mfma_f32_16x16x32_bf16 v[98:101], v[180:183], v[196:199], v[98:101]
	v_mfma_f32_16x16x32_bf16 v[86:89], v[172:175], v[204:207], v[86:89]
	v_mfma_f32_16x16x32_bf16 v[82:85], v[180:183], v[204:207], v[82:85]
	s_setprio 2
	s_barrier
; #define PG8_STAGE(bufoff, gbase, voff) do { _Pragma("unroll") for (int _i = 0; _i < 2; ++_i) \
;         asm volatile("s_mov_b32 m0, %2\n\ts_nop 0\n\tglobal_load_lds_dwordx4 %0, %1" :: "v"((voff)[_i]), "s"((const char*)(gbase)), "s"(ldsbase + (unsigned)(bufoff) + ldsw + (unsigned)_i * 8192u) : "memory", "m0"); } while (0)
; #define PG8_LDA(dst, b, h) do { _Pragma("unroll") for (int m = 0; m < 4; ++m) _Pragma("unroll") for (int k = 0; k < 2; ++k) dst[m][k] = *(const PG8_LAS bf16x8*)(lds + PG8_SA(b, h) + aoff + m * 2048 + k * 1024); } while (0)
; #define PG8_BAR __builtin_amdgcn_s_barrier()
; template <class Epi, class Sched, bool ALIGN_EPI = false, bool SP2 = false>
; __device__ __forceinline__ void gemm_phase(PG8_LAS unsigned char* lds, const Gemm g, const Sched& S, const Epi& E) {
;     ...
;         for (int t = 0; t < nt; t += 2) {
;             const bool last = (t == nt - 2);
;             const char* a1 = cA + (size_t)(t + 1) * kstep;
;             const char* a2 = last ? nA : cA + (size_t)(t + 2) * kstep; const char* b2 = last ? nB : cB + (size_t)(t + 2) * kstep;
;             const char* a3 = a2 + kstep; const char* b3 = b2 + kstep;
;             if (last && has_next) S.a_ready(nxt);
;             if constexpr (epi_has_mid<Epi>::value) { if (t == Epi::MID_T) E.mid(acc, cur, wr, wc, fr, fq); }
;             if constexpr (SP2) {
;             PG8_LDB(B0, 0, 0); PG8_LDB(B1, 0, 1); PG8_SCHED; PG8_LDA(At, 0, 0); PG8_STAGE(PG8_SA(1, 1), a1 + hstep, voffA);
;             PG8_WAIT_V(8); PG8_WAIT_L(0); PG8_BAR; PG8_MMA(0, 0, At, B0); PG8_MMA(0, 1, At, B1); PG8_BAR; PG8_SCHED;
;             PG8_LDA(At, 0, 1); PG8_STAGE(PG8_SB(0, 0), b2, voffB); PG8_STAGE(PG8_SB(0, 1), b2 + hstep, voffB); PG8_STAGE(PG8_SA(0, 0), a2, voffA);
;             PG8_WAIT_V(8); PG8_WAIT_L(0); PG8_BAR; PG8_MMA(1, 0, At, B0); PG8_MMA(1, 1, At, B1); PG8_BAR; PG8_SCHED;
;             PG8_LDB(B0, 1, 0); PG8_LDB(B1, 1, 1); PG8_SCHED; PG8_LDA(At, 1, 0); PG8_STAGE(PG8_SA(0, 1), a2 + hstep, voffA);
;             PG8_WAIT_V(8); PG8_WAIT_L(0); PG8_BAR; PG8_MMA(0, 0, At, B0); PG8_MMA(0, 1, At, B1); PG8_BAR; PG8_SCHED;
;             PG8_LDA(At, 1, 1); PG8_STAGE(PG8_SB(1, 0), b3, voffB); PG8_STAGE(PG8_SB(1, 1), b3 + hstep, voffB); PG8_STAGE(PG8_SA(1, 0), a3, voffA);
;             PG8_WAIT_V(8); PG8_WAIT_L(0); PG8_BAR; PG8_MMA(1, 0, At, B0); PG8_MMA(1, 1, At, B1); PG8_BAR; PG8_SCHED;
	ds_read_b128 v[184:187], v150 offset:49152
	ds_read_b128 v[188:191], v150 offset:50176
	ds_read_b128 v[192:195], v150 offset:51200
	ds_read_b128 v[196:199], v150 offset:52224
	ds_read_b128 v[200:203], v150 offset:53248
	ds_read_b128 v[204:207], v150 offset:54272
	ds_read_b128 v[208:211], v150 offset:55296
	v_mfma_f32_16x16x32_bf16 v[70:73], v[172:175], v[212:215], v[70:73]
	v_mfma_f32_16x16x32_bf16 v[66:69], v[180:183], v[212:215], v[66:69]
	s_setprio 0
	ds_read_b128 v[212:215], v150 offset:56320
	s_mov_b32 m0, s56
	s_nop 0
	global_load_lds_dwordx4 v140, s[44:45]
	s_add_u32 s38, s38, 0x100080
	s_mov_b32 m0, s57
	s_nop 0
	global_load_lds_dwordx4 v142, s[44:45]
	s_addc_u32 s39, s39, 0
	s_mov_b32 m0, s62
	s_nop 0
	global_load_lds_dwordx4 v140, s[38:39]
	s_nop 0
	s_mov_b32 m0, s63
	s_nop 0
	global_load_lds_dwordx4 v142, s[38:39]
	s_nop 0
	s_mov_b32 m0, s60
	s_nop 0
	global_load_lds_dwordx4 v139, s[42:43]
	s_nop 0
	s_mov_b32 m0, s61
	s_nop 0
	global_load_lds_dwordx4 v141, s[42:43]
	s_waitcnt vmcnt(8)
	s_waitcnt lgkmcnt(0)
	s_barrier
	s_setprio 1
	s_waitcnt lgkmcnt(7)
	v_mfma_f32_16x16x32_bf16 v[62:65], v[152:155], v[184:187], v[62:65]
	v_mfma_f32_16x16x32_bf16 v[58:61], v[160:163], v[184:187], v[58:61]
	s_waitcnt lgkmcnt(5)
	v_mfma_f32_16x16x32_bf16 v[46:49], v[152:155], v[192:195], v[46:49]
	v_mfma_f32_16x16x32_bf16 v[42:45], v[160:163], v[192:195], v[42:45]
	s_waitcnt lgkmcnt(3)
	v_mfma_f32_16x16x32_bf16 v[30:33], v[152:155], v[200:203], v[30:33]
	v_mfma_f32_16x16x32_bf16 v[26:29], v[160:163], v[200:203], v[26:29]
	s_waitcnt lgkmcnt(1)
	v_mfma_f32_16x16x32_bf16 v[14:17], v[152:155], v[208:211], v[14:17]
	v_mfma_f32_16x16x32_bf16 v[10:13], v[160:163], v[208:211], v[10:13]
	v_mfma_f32_16x16x32_bf16 v[62:65], v[156:159], v[188:191], v[62:65]
	v_mfma_f32_16x16x32_bf16 v[58:61], v[164:167], v[188:191], v[58:61]
	v_mfma_f32_16x16x32_bf16 v[46:49], v[156:159], v[196:199], v[46:49]
	v_mfma_f32_16x16x32_bf16 v[42:45], v[164:167], v[196:199], v[42:45]
	v_mfma_f32_16x16x32_bf16 v[30:33], v[156:159], v[204:207], v[30:33]
	v_mfma_f32_16x16x32_bf16 v[26:29], v[164:167], v[204:207], v[26:29]
	s_waitcnt lgkmcnt(0)
	v_mfma_f32_16x16x32_bf16 v[14:17], v[156:159], v[212:215], v[14:17]
	v_mfma_f32_16x16x32_bf16 v[10:13], v[164:167], v[212:215], v[10:13]
	s_setprio 0
	s_setprio 1
	v_mfma_f32_16x16x32_bf16 v[54:57], v[168:171], v[184:187], v[54:57]
	v_mfma_f32_16x16x32_bf16 v[50:53], v[176:179], v[184:187], v[50:53]
	v_mfma_f32_16x16x32_bf16 v[38:41], v[168:171], v[192:195], v[38:41]
	v_mfma_f32_16x16x32_bf16 v[34:37], v[176:179], v[192:195], v[34:37]
	v_mfma_f32_16x16x32_bf16 v[22:25], v[168:171], v[200:203], v[22:25]
	v_mfma_f32_16x16x32_bf16 v[18:21], v[176:179], v[200:203], v[18:21]
	v_mfma_f32_16x16x32_bf16 v[6:9], v[168:171], v[208:211], v[6:9]
	v_mfma_f32_16x16x32_bf16 v[2:5], v[176:179], v[208:211], v[2:5]
	v_mfma_f32_16x16x32_bf16 v[54:57], v[172:175], v[188:191], v[54:57]
	v_mfma_f32_16x16x32_bf16 v[50:53], v[180:183], v[188:191], v[50:53]
	v_mfma_f32_16x16x32_bf16 v[38:41], v[172:175], v[196:199], v[38:41]
	v_mfma_f32_16x16x32_bf16 v[34:37], v[180:183], v[196:199], v[34:37]
	v_mfma_f32_16x16x32_bf16 v[22:25], v[172:175], v[204:207], v[22:25]
	v_mfma_f32_16x16x32_bf16 v[18:21], v[180:183], v[204:207], v[18:21]
	v_mfma_f32_16x16x32_bf16 v[6:9], v[172:175], v[212:215], v[6:9]
	s_setprio 2
	s_barrier
	v_mfma_f32_16x16x32_bf16 v[2:5], v[180:183], v[212:215], v[2:5]
	s_setprio 0
	s_add_i32 s76, s76, 2
	s_add_u32 s74, s74, 0x100
	s_addc_u32 s75, s75, 0
	s_cmp_gt_u32 s76, 61
	s_cbranch_scc1 .LBB0_780
	s_mov_b64 s[40:41], s[8:9]
	s_branch .LBB0_784

; #define PG8_STAGE(bufoff, gbase, voff) do { _Pragma("unroll") for (int _i = 0; _i < 2; ++_i) \
;         asm volatile("s_mov_b32 m0, %2\n\ts_nop 0\n\tglobal_load_lds_dwordx4 %0, %1" :: "v"((voff)[_i]), "s"((const char*)(gbase)), "s"(ldsbase + (unsigned)(bufoff) + ldsw + (unsigned)_i * 8192u) : "memory", "m0"); } while (0)
; #define PG8_LDA(dst, b, h) do { _Pragma("unroll") for (int m = 0; m < 4; ++m) _Pragma("unroll") for (int k = 0; k < 2; ++k) dst[m][k] = *(const PG8_LAS bf16x8*)(lds + PG8_SA(b, h) + aoff + m * 2048 + k * 1024); } while (0)
; #define PG8_WAIT_V(n) asm volatile("s_waitcnt vmcnt(" #n ")" ::: "memory")
; template <class Epi, class Sched, bool ALIGN_EPI = false, bool SP2 = false>
; __device__ __forceinline__ void gemm_phase(PG8_LAS unsigned char* lds, const Gemm g, const Sched& S, const Epi& E) {
;     ...
;             const bool last = (t == nt - 2);
;             const char* a1 = cA + (size_t)(t + 1) * kstep;
;             const char* a2 = last ? nA : cA + (size_t)(t + 2) * kstep; const char* b2 = last ? nB : cB + (size_t)(t + 2) * kstep;
;             const char* a3 = a2 + kstep; const char* b3 = b2 + kstep;
;             if (last && has_next) S.a_ready(nxt);
;             if constexpr (epi_has_mid<Epi>::value) { if (t == Epi::MID_T) E.mid(acc, cur, wr, wc, fr, fq); }
;             if constexpr (SP2) {
;             PG8_LDB(B0, 0, 0); PG8_LDB(B1, 0, 1); PG8_SCHED; PG8_LDA(At, 0, 0); PG8_STAGE(PG8_SA(1, 1), a1 + hstep, voffA);
;             PG8_WAIT_V(8); PG8_WAIT_L(0); PG8_BAR; PG8_MMA(0, 0, At, B0); PG8_MMA(0, 1, At, B1); PG8_BAR; PG8_SCHED;
;             PG8_LDA(At, 0, 1); PG8_STAGE(PG8_SB(0, 0), b2, voffB); PG8_STAGE(PG8_SB(0, 1), b2 + hstep, voffB); PG8_STAGE(PG8_SA(0, 0), a2, voffA);
;             PG8_WAIT_V(8); PG8_WAIT_L(0); PG8_BAR; PG8_MMA(1, 0, At, B0); PG8_MMA(1, 1, At, B1); PG8_BAR; PG8_SCHED;
;             PG8_LDB(B0, 1, 0); PG8_LDB(B1, 1, 1); PG8_SCHED; PG8_LDA(At, 1, 0); PG8_STAGE(PG8_SA(0, 1), a2 + hstep, voffA);
;             PG8_WAIT_V(8); PG8_WAIT_L(0); PG8_BAR; PG8_MMA(0, 0, At, B0); PG8_MMA(0, 1, At, B1); PG8_BAR; PG8_SCHED;
;             PG8_LDA(At, 1, 1); PG8_STAGE(PG8_SB(1, 0), b3, voffB); PG8_STAGE(PG8_SB(1, 1), b3 + hstep, voffB); PG8_STAGE(PG8_SA(1, 0), a3, voffA);
;             PG8_WAIT_V(8); PG8_WAIT_L(0); PG8_BAR; PG8_MMA(1, 0, At, B0); PG8_MMA(1, 1, At, B1); PG8_BAR; PG8_SCHED;
.LBB0_873:
	ds_read_b128 v[134:137], v145
	ds_read_b128 v[150:153], v145 offset:1024
	ds_read_b128 v[154:157], v145 offset:2048
	ds_read_b128 v[158:161], v145 offset:3072
	ds_read_b128 v[162:165], v146
	ds_read_b128 v[166:169], v146 offset:1024
	ds_read_b128 v[170:173], v146 offset:2048
	ds_read_b128 v[174:177], v146 offset:3072
	s_add_u32 s38, s36, 0x100
	s_addc_u32 s39, s37, 0
	s_cmpk_eq_i32 s69, 0xa8
	s_cselect_b32 s44, s4, s38
	s_cselect_b32 s45, s5, s39
	s_cselect_b32 s42, s22, s67
	s_cselect_b32 s43, s23, s68
	s_add_u32 s40, s44, 0x80
	s_addc_u32 s41, s45, 0
	ds_read_b128 v[178:181], v147
	ds_read_b128 v[182:185], v147 offset:1024
	ds_read_b128 v[186:189], v147 offset:2048
	ds_read_b128 v[190:193], v147 offset:3072
	ds_read_b128 v[194:197], v147 offset:4096
	ds_read_b128 v[198:201], v147 offset:5120
	ds_read_b128 v[202:205], v147 offset:6144
	ds_read_b128 v[206:209], v147 offset:7168
	s_add_u32 s36, s36, 0x2b0080
	s_addc_u32 s37, s37, 0
	s_mov_b32 m0, s60
	s_nop 0
	global_load_lds_dwordx4 v1, s[36:37]
	s_nop 0
	s_mov_b32 m0, s61
	s_nop 0
	global_load_lds_dwordx4 v141, s[36:37]
	s_waitcnt vmcnt(8)
	s_waitcnt lgkmcnt(0)
	s_barrier
	s_setprio 1
	s_waitcnt lgkmcnt(7)
	v_mfma_f32_16x16x32_bf16 v[126:129], v[134:137], v[178:181], v[126:129]
	v_mfma_f32_16x16x32_bf16 v[122:125], v[154:157], v[178:181], v[122:125]
	s_waitcnt lgkmcnt(5)
	v_mfma_f32_16x16x32_bf16 v[110:113], v[134:137], v[186:189], v[110:113]
	v_mfma_f32_16x16x32_bf16 v[106:109], v[154:157], v[186:189], v[106:109]
	s_waitcnt lgkmcnt(3)
	v_mfma_f32_16x16x32_bf16 v[94:97], v[134:137], v[194:197], v[94:97]
	v_mfma_f32_16x16x32_bf16 v[90:93], v[154:157], v[194:197], v[90:93]
	s_waitcnt lgkmcnt(1)
	v_mfma_f32_16x16x32_bf16 v[78:81], v[134:137], v[202:205], v[78:81]
	v_mfma_f32_16x16x32_bf16 v[74:77], v[154:157], v[202:205], v[74:77]
	v_mfma_f32_16x16x32_bf16 v[126:129], v[150:153], v[182:185], v[126:129]
	v_mfma_f32_16x16x32_bf16 v[122:125], v[158:161], v[182:185], v[122:125]
	v_mfma_f32_16x16x32_bf16 v[110:113], v[150:153], v[190:193], v[110:113]
	v_mfma_f32_16x16x32_bf16 v[106:109], v[158:161], v[190:193], v[106:109]
	v_mfma_f32_16x16x32_bf16 v[94:97], v[150:153], v[198:201], v[94:97]
	v_mfma_f32_16x16x32_bf16 v[90:93], v[158:161], v[198:201], v[90:93]
	s_waitcnt lgkmcnt(0)
	v_mfma_f32_16x16x32_bf16 v[78:81], v[150:153], v[206:209], v[78:81]
	v_mfma_f32_16x16x32_bf16 v[74:77], v[158:161], v[206:209], v[74:77]
	s_setprio 0
	s_setprio 1
	v_mfma_f32_16x16x32_bf16 v[118:121], v[162:165], v[178:181], v[118:121]
	v_mfma_f32_16x16x32_bf16 v[114:117], v[170:173], v[178:181], v[114:117]
	v_mfma_f32_16x16x32_bf16 v[102:105], v[162:165], v[186:189], v[102:105]
	v_mfma_f32_16x16x32_bf16 v[98:101], v[170:173], v[186:189], v[98:101]
	v_mfma_f32_16x16x32_bf16 v[86:89], v[162:165], v[194:197], v[86:89]
	v_mfma_f32_16x16x32_bf16 v[82:85], v[170:173], v[194:197], v[82:85]
	v_mfma_f32_16x16x32_bf16 v[70:73], v[162:165], v[202:205], v[70:73]
	v_mfma_f32_16x16x32_bf16 v[66:69], v[170:173], v[202:205], v[66:69]
	v_mfma_f32_16x16x32_bf16 v[118:121], v[166:169], v[182:185], v[118:121]
	v_mfma_f32_16x16x32_bf16 v[114:117], v[174:177], v[182:185], v[114:117]
	v_mfma_f32_16x16x32_bf16 v[102:105], v[166:169], v[190:193], v[102:105]
	v_mfma_f32_16x16x32_bf16 v[98:101], v[174:177], v[190:193], v[98:101]
	v_mfma_f32_16x16x32_bf16 v[86:89], v[166:169], v[198:201], v[86:89]
	v_mfma_f32_16x16x32_bf16 v[82:85], v[174:177], v[198:201], v[82:85]
	s_setprio 2
	s_barrier
	ds_read_b128 v[178:181], v147 offset:16384
	ds_read_b128 v[182:185], v147 offset:17408
	ds_read_b128 v[186:189], v147 offset:18432
	ds_read_b128 v[190:193], v147 offset:19456
	ds_read_b128 v[194:197], v147 offset:20480
	ds_read_b128 v[198:201], v147 offset:21504
	ds_read_b128 v[202:205], v147 offset:22528
	v_mfma_f32_16x16x32_bf16 v[70:73], v[166:169], v[206:209], v[70:73]
	v_mfma_f32_16x16x32_bf16 v[66:69], v[174:177], v[206:209], v[66:69]
	s_setprio 0
	ds_read_b128 v[206:209], v147 offset:23552
	s_mov_b32 m0, s47
	s_nop 0
	global_load_lds_dwordx4 v140, s[42:43]
	s_add_u32 s36, s42, 0x2b0000
	s_mov_b32 m0, s48
	s_nop 0
	global_load_lds_dwordx4 v142, s[42:43]
	s_addc_u32 s37, s43, 0
	s_mov_b32 m0, s49
	s_nop 0
	global_load_lds_dwordx4 v140, s[36:37]
	s_nop 0
	s_mov_b32 m0, s50
	s_nop 0
	global_load_lds_dwordx4 v142, s[36:37]
	s_nop 0
	s_mov_b32 m0, s46
	s_nop 0
	global_load_lds_dwordx4 v1, s[44:45]
	s_nop 0
	s_mov_b32 m0, s51
	s_nop 0
	global_load_lds_dwordx4 v141, s[44:45]
	s_waitcnt vmcnt(8)
	s_waitcnt lgkmcnt(0)
	s_barrier
	s_setprio 1
	s_waitcnt lgkmcnt(7)
	v_mfma_f32_16x16x32_bf16 v[62:65], v[134:137], v[178:181], v[62:65]
	v_mfma_f32_16x16x32_bf16 v[58:61], v[154:157], v[178:181], v[58:61]
	s_waitcnt lgkmcnt(5)
	v_mfma_f32_16x16x32_bf16 v[46:49], v[134:137], v[186:189], v[46:49]
	v_mfma_f32_16x16x32_bf16 v[42:45], v[154:157], v[186:189], v[42:45]
	s_waitcnt lgkmcnt(3)
	v_mfma_f32_16x16x32_bf16 v[30:33], v[134:137], v[194:197], v[30:33]
	v_mfma_f32_16x16x32_bf16 v[26:29], v[154:157], v[194:197], v[26:29]
	s_waitcnt lgkmcnt(1)
	v_mfma_f32_16x16x32_bf16 v[14:17], v[134:137], v[202:205], v[14:17]
	v_mfma_f32_16x16x32_bf16 v[10:13], v[154:157], v[202:205], v[10:13]
	v_mfma_f32_16x16x32_bf16 v[62:65], v[150:153], v[182:185], v[62:65]
	v_mfma_f32_16x16x32_bf16 v[58:61], v[158:161], v[182:185], v[58:61]
	v_mfma_f32_16x16x32_bf16 v[46:49], v[150:153], v[190:193], v[46:49]
	v_mfma_f32_16x16x32_bf16 v[42:45], v[158:161], v[190:193], v[42:45]
	v_mfma_f32_16x16x32_bf16 v[30:33], v[150:153], v[198:201], v[30:33]
	v_mfma_f32_16x16x32_bf16 v[26:29], v[158:161], v[198:201], v[26:29]
	s_waitcnt lgkmcnt(0)
	v_mfma_f32_16x16x32_bf16 v[14:17], v[150:153], v[206:209], v[14:17]
	v_mfma_f32_16x16x32_bf16 v[10:13], v[158:161], v[206:209], v[10:13]
	s_setprio 0
	s_setprio 1
	v_mfma_f32_16x16x32_bf16 v[54:57], v[162:165], v[178:181], v[54:57]
	v_mfma_f32_16x16x32_bf16 v[50:53], v[170:173], v[178:181], v[50:53]
	v_mfma_f32_16x16x32_bf16 v[38:41], v[162:165], v[186:189], v[38:41]
	v_mfma_f32_16x16x32_bf16 v[34:37], v[170:173], v[186:189], v[34:37]
	v_mfma_f32_16x16x32_bf16 v[22:25], v[162:165], v[194:197], v[22:25]
	v_mfma_f32_16x16x32_bf16 v[18:21], v[170:173], v[194:197], v[18:21]
	v_mfma_f32_16x16x32_bf16 v[6:9], v[162:165], v[202:205], v[6:9]
	v_mfma_f32_16x16x32_bf16 v[2:5], v[170:173], v[202:205], v[2:5]
	v_mfma_f32_16x16x32_bf16 v[54:57], v[166:169], v[182:185], v[54:57]
	v_mfma_f32_16x16x32_bf16 v[50:53], v[174:177], v[182:185], v[50:53]
	v_mfma_f32_16x16x32_bf16 v[38:41], v[166:169], v[190:193], v[38:41]
	v_mfma_f32_16x16x32_bf16 v[34:37], v[174:177], v[190:193], v[34:37]
	v_mfma_f32_16x16x32_bf16 v[22:25], v[166:169], v[198:201], v[22:25]
	v_mfma_f32_16x16x32_bf16 v[18:21], v[174:177], v[198:201], v[18:21]
	s_setprio 2
	s_barrier
; #define PG8_STAGE(bufoff, gbase, voff) do { _Pragma("unroll") for (int _i = 0; _i < 2; ++_i) \
;         asm volatile("s_mov_b32 m0, %2\n\ts_nop 0\n\tglobal_load_lds_dwordx4 %0, %1" :: "v"((voff)[_i]), "s"((const char*)(gbase)), "s"(ldsbase + (unsigned)(bufoff) + ldsw + (unsigned)_i * 8192u) : "memory", "m0"); } while (0)
; #define PG8_LDA(dst, b, h) do { _Pragma("unroll") for (int m = 0; m < 4; ++m) _Pragma("unroll") for (int k = 0; k < 2; ++k) dst[m][k] = *(const PG8_LAS bf16x8*)(lds + PG8_SA(b, h) + aoff + m * 2048 + k * 1024); } while (0)
; #define PG8_LDB(dst, b, h) do { _Pragma("unroll") for (int n = 0; n < 2; ++n) _Pragma("unroll") for (int k = 0; k < 2; ++k) dst[n][k] = *(const PG8_LAS bf16x8*)(lds + PG8_SB(b, h) + boff + n * 2048 + k * 1024); } while (0)
; #define PG8_MMA(ai, bj, At, Bt) do { __builtin_amdgcn_s_setprio(1); _Pragma("unroll") for (int m = 0; m < 4; ++m) _Pragma("unroll") for (int n = 0; n < 2; ++n) _Pragma("unroll") for (int k = 0; k < 2; ++k) \
;         acc[ai][bj][m][n] = __builtin_amdgcn_mfma_f32_16x16x32_bf16(Bt[n][k], At[m][k], acc[ai][bj][m][n], 0, 0, 0); __builtin_amdgcn_s_setprio(0); } while (0)
; template <class Epi, class Sched, bool ALIGN_EPI = false, bool SP2 = false>
; __device__ __forceinline__ void gemm_phase(PG8_LAS unsigned char* lds, const Gemm g, const Sched& S, const Epi& E) {
;     ...
;             PG8_LDB(B0, 0, 0); PG8_LDB(B1, 0, 1); PG8_SCHED; PG8_LDA(At, 0, 0); PG8_STAGE(PG8_SA(1, 1), a1 + hstep, voffA);
;             PG8_WAIT_V(8); PG8_WAIT_L(0); PG8_BAR; PG8_MMA(0, 0, At, B0); PG8_MMA(0, 1, At, B1); PG8_BAR; PG8_SCHED;
;             PG8_LDA(At, 0, 1); PG8_STAGE(PG8_SB(0, 0), b2, voffB); PG8_STAGE(PG8_SB(0, 1), b2 + hstep, voffB); PG8_STAGE(PG8_SA(0, 0), a2, voffA);
;             PG8_WAIT_V(8); PG8_WAIT_L(0); PG8_BAR; PG8_MMA(1, 0, At, B0); PG8_MMA(1, 1, At, B1); PG8_BAR; PG8_SCHED;
;             PG8_LDB(B0, 1, 0); PG8_LDB(B1, 1, 1); PG8_SCHED; PG8_LDA(At, 1, 0); PG8_STAGE(PG8_SA(0, 1), a2 + hstep, voffA);
;             PG8_WAIT_V(8); PG8_WAIT_L(0); PG8_BAR; PG8_MMA(0, 0, At, B0); PG8_MMA(0, 1, At, B1); PG8_BAR; PG8_SCHED;
;             PG8_LDA(At, 1, 1); PG8_STAGE(PG8_SB(1, 0), b3, voffB); PG8_STAGE(PG8_SB(1, 1), b3 + hstep, voffB); PG8_STAGE(PG8_SA(1, 0), a3, voffA);
;             PG8_WAIT_V(8); PG8_WAIT_L(0); PG8_BAR; PG8_MMA(1, 0, At, B0); PG8_MMA(1, 1, At, B1); PG8_BAR; PG8_SCHED;
	ds_read_b128 v[134:137], v148
	ds_read_b128 v[150:153], v148 offset:1024
	ds_read_b128 v[154:157], v148 offset:2048
	ds_read_b128 v[158:161], v148 offset:3072
	ds_read_b128 v[162:165], v149
	v_mfma_f32_16x16x32_bf16 v[6:9], v[166:169], v[206:209], v[6:9]
	v_mfma_f32_16x16x32_bf16 v[2:5], v[174:177], v[206:209], v[2:5]
	s_setprio 0
	ds_read_b128 v[166:169], v149 offset:1024
	ds_read_b128 v[170:173], v149 offset:2048
	ds_read_b128 v[174:177], v149 offset:3072
	ds_read_b128 v[178:181], v147 offset:32768
	ds_read_b128 v[182:185], v147 offset:33792
	ds_read_b128 v[186:189], v147 offset:34816
	ds_read_b128 v[190:193], v147 offset:35840
	ds_read_b128 v[194:197], v147 offset:36864
	ds_read_b128 v[198:201], v147 offset:37888
	ds_read_b128 v[202:205], v147 offset:38912
	ds_read_b128 v[206:209], v147 offset:39936
	s_add_u32 s36, s44, 0x2b0000
	s_addc_u32 s37, s45, 0
	s_mov_b32 m0, s52
	s_nop 0
	global_load_lds_dwordx4 v1, s[36:37]
	s_nop 0
	s_mov_b32 m0, s53
	s_nop 0
	global_load_lds_dwordx4 v141, s[36:37]
	s_waitcnt vmcnt(8)
	s_waitcnt lgkmcnt(0)
	s_barrier
	s_setprio 1
	s_waitcnt lgkmcnt(7)
	v_mfma_f32_16x16x32_bf16 v[126:129], v[134:137], v[178:181], v[126:129]
	v_mfma_f32_16x16x32_bf16 v[122:125], v[154:157], v[178:181], v[122:125]
	s_waitcnt lgkmcnt(5)
	v_mfma_f32_16x16x32_bf16 v[110:113], v[134:137], v[186:189], v[110:113]
	v_mfma_f32_16x16x32_bf16 v[106:109], v[154:157], v[186:189], v[106:109]
	s_waitcnt lgkmcnt(3)
	v_mfma_f32_16x16x32_bf16 v[94:97], v[134:137], v[194:197], v[94:97]
	v_mfma_f32_16x16x32_bf16 v[90:93], v[154:157], v[194:197], v[90:93]
	s_waitcnt lgkmcnt(1)
	v_mfma_f32_16x16x32_bf16 v[78:81], v[134:137], v[202:205], v[78:81]
	v_mfma_f32_16x16x32_bf16 v[74:77], v[154:157], v[202:205], v[74:77]
	v_mfma_f32_16x16x32_bf16 v[126:129], v[150:153], v[182:185], v[126:129]
	v_mfma_f32_16x16x32_bf16 v[122:125], v[158:161], v[182:185], v[122:125]
	v_mfma_f32_16x16x32_bf16 v[110:113], v[150:153], v[190:193], v[110:113]
	v_mfma_f32_16x16x32_bf16 v[106:109], v[158:161], v[190:193], v[106:109]
	v_mfma_f32_16x16x32_bf16 v[94:97], v[150:153], v[198:201], v[94:97]
	v_mfma_f32_16x16x32_bf16 v[90:93], v[158:161], v[198:201], v[90:93]
	s_waitcnt lgkmcnt(0)
	v_mfma_f32_16x16x32_bf16 v[78:81], v[150:153], v[206:209], v[78:81]
	v_mfma_f32_16x16x32_bf16 v[74:77], v[158:161], v[206:209], v[74:77]
	s_setprio 0
	s_setprio 1
	v_mfma_f32_16x16x32_bf16 v[118:121], v[162:165], v[178:181], v[118:121]
	v_mfma_f32_16x16x32_bf16 v[114:117], v[170:173], v[178:181], v[114:117]
	v_mfma_f32_16x16x32_bf16 v[102:105], v[162:165], v[186:189], v[102:105]
	v_mfma_f32_16x16x32_bf16 v[98:101], v[170:173], v[186:189], v[98:101]
	v_mfma_f32_16x16x32_bf16 v[86:89], v[162:165], v[194:197], v[86:89]
	v_mfma_f32_16x16x32_bf16 v[82:85], v[170:173], v[194:197], v[82:85]
	v_mfma_f32_16x16x32_bf16 v[70:73], v[162:165], v[202:205], v[70:73]
	v_mfma_f32_16x16x32_bf16 v[66:69], v[170:173], v[202:205], v[66:69]
	v_mfma_f32_16x16x32_bf16 v[118:121], v[166:169], v[182:185], v[118:121]
	v_mfma_f32_16x16x32_bf16 v[114:117], v[174:177], v[182:185], v[114:117]
	v_mfma_f32_16x16x32_bf16 v[102:105], v[166:169], v[190:193], v[102:105]
	v_mfma_f32_16x16x32_bf16 v[98:101], v[174:177], v[190:193], v[98:101]
	v_mfma_f32_16x16x32_bf16 v[86:89], v[166:169], v[198:201], v[86:89]
	v_mfma_f32_16x16x32_bf16 v[82:85], v[174:177], v[198:201], v[82:85]
	s_setprio 2
	s_barrier
; #define PG8_STAGE(bufoff, gbase, voff) do { _Pragma("unroll") for (int _i = 0; _i < 2; ++_i) \
;         asm volatile("s_mov_b32 m0, %2\n\ts_nop 0\n\tglobal_load_lds_dwordx4 %0, %1" :: "v"((voff)[_i]), "s"((const char*)(gbase)), "s"(ldsbase + (unsigned)(bufoff) + ldsw + (unsigned)_i * 8192u) : "memory", "m0"); } while (0)
; #define PG8_LDA(dst, b, h) do { _Pragma("unroll") for (int m = 0; m < 4; ++m) _Pragma("unroll") for (int k = 0; k < 2; ++k) dst[m][k] = *(const PG8_LAS bf16x8*)(lds + PG8_SA(b, h) + aoff + m * 2048 + k * 1024); } while (0)
; #define PG8_BAR __builtin_amdgcn_s_barrier()
; template <class Epi, class Sched, bool ALIGN_EPI = false, bool SP2 = false>
; __device__ __forceinline__ void gemm_phase(PG8_LAS unsigned char* lds, const Gemm g, const Sched& S, const Epi& E) {
;     ...
;         for (int t = 0; t < nt; t += 2) {
;             const bool last = (t == nt - 2);
;             const char* a1 = cA + (size_t)(t + 1) * kstep;
;             const char* a2 = last ? nA : cA + (size_t)(t + 2) * kstep; const char* b2 = last ? nB : cB + (size_t)(t + 2) * kstep;
;             const char* a3 = a2 + kstep; const char* b3 = b2 + kstep;
;             if (last && has_next) S.a_ready(nxt);
;             if constexpr (epi_has_mid<Epi>::value) { if (t == Epi::MID_T) E.mid(acc, cur, wr, wc, fr, fq); }
;             if constexpr (SP2) {
;             PG8_LDB(B0, 0, 0); PG8_LDB(B1, 0, 1); PG8_SCHED; PG8_LDA(At, 0, 0); PG8_STAGE(PG8_SA(1, 1), a1 + hstep, voffA);
;             PG8_WAIT_V(8); PG8_WAIT_L(0); PG8_BAR; PG8_MMA(0, 0, At, B0); PG8_MMA(0, 1, At, B1); PG8_BAR; PG8_SCHED;
;             PG8_LDA(At, 0, 1); PG8_STAGE(PG8_SB(0, 0), b2, voffB); PG8_STAGE(PG8_SB(0, 1), b2 + hstep, voffB); PG8_STAGE(PG8_SA(0, 0), a2, voffA);
;             PG8_WAIT_V(8); PG8_WAIT_L(0); PG8_BAR; PG8_MMA(1, 0, At, B0); PG8_MMA(1, 1, At, B1); PG8_BAR; PG8_SCHED;
;             PG8_LDB(B0, 1, 0); PG8_LDB(B1, 1, 1); PG8_SCHED; PG8_LDA(At, 1, 0); PG8_STAGE(PG8_SA(0, 1), a2 + hstep, voffA);
;             PG8_WAIT_V(8); PG8_WAIT_L(0); PG8_BAR; PG8_MMA(0, 0, At, B0); PG8_MMA(0, 1, At, B1); PG8_BAR; PG8_SCHED;
;             PG8_LDA(At, 1, 1); PG8_STAGE(PG8_SB(1, 0), b3, voffB); PG8_STAGE(PG8_SB(1, 1), b3 + hstep, voffB); PG8_STAGE(PG8_SA(1, 0), a3, voffA);
;             PG8_WAIT_V(8); PG8_WAIT_L(0); PG8_BAR; PG8_MMA(1, 0, At, B0); PG8_MMA(1, 1, At, B1); PG8_BAR; PG8_SCHED;
	ds_read_b128 v[178:181], v147 offset:49152
	ds_read_b128 v[182:185], v147 offset:50176
	ds_read_b128 v[186:189], v147 offset:51200
	ds_read_b128 v[190:193], v147 offset:52224
	ds_read_b128 v[194:197], v147 offset:53248
	ds_read_b128 v[198:201], v147 offset:54272
	ds_read_b128 v[202:205], v147 offset:55296
	v_mfma_f32_16x16x32_bf16 v[70:73], v[166:169], v[206:209], v[70:73]
	v_mfma_f32_16x16x32_bf16 v[66:69], v[174:177], v[206:209], v[66:69]
	s_setprio 0
	ds_read_b128 v[206:209], v147 offset:56320
	s_add_u32 s36, s42, 0x80
	s_addc_u32 s37, s43, 0
	s_mov_b32 m0, s54
	s_nop 0
	global_load_lds_dwordx4 v140, s[36:37]
	s_nop 0
	s_mov_b32 m0, s55
	s_nop 0
	global_load_lds_dwordx4 v142, s[36:37]
	s_add_u32 s36, s42, 0x2b0080
	s_addc_u32 s37, s43, 0
	s_mov_b32 m0, s58
	s_nop 0
	global_load_lds_dwordx4 v140, s[36:37]
	s_nop 0
	s_mov_b32 m0, s59
	s_nop 0
	global_load_lds_dwordx4 v142, s[36:37]
	s_nop 0
	s_mov_b32 m0, s56
	s_nop 0
	global_load_lds_dwordx4 v1, s[40:41]
	s_nop 0
	s_mov_b32 m0, s57
	s_nop 0
	global_load_lds_dwordx4 v141, s[40:41]
	s_waitcnt vmcnt(8)
	s_waitcnt lgkmcnt(0)
	s_barrier
	s_setprio 1
	s_waitcnt lgkmcnt(7)
	v_mfma_f32_16x16x32_bf16 v[62:65], v[134:137], v[178:181], v[62:65]
	v_mfma_f32_16x16x32_bf16 v[58:61], v[154:157], v[178:181], v[58:61]
	s_waitcnt lgkmcnt(5)
	v_mfma_f32_16x16x32_bf16 v[46:49], v[134:137], v[186:189], v[46:49]
	v_mfma_f32_16x16x32_bf16 v[42:45], v[154:157], v[186:189], v[42:45]
	s_waitcnt lgkmcnt(3)
	v_mfma_f32_16x16x32_bf16 v[30:33], v[134:137], v[194:197], v[30:33]
	v_mfma_f32_16x16x32_bf16 v[26:29], v[154:157], v[194:197], v[26:29]
	s_waitcnt lgkmcnt(1)
	v_mfma_f32_16x16x32_bf16 v[14:17], v[134:137], v[202:205], v[14:17]
	v_mfma_f32_16x16x32_bf16 v[10:13], v[154:157], v[202:205], v[10:13]
	v_mfma_f32_16x16x32_bf16 v[62:65], v[150:153], v[182:185], v[62:65]
	v_mfma_f32_16x16x32_bf16 v[58:61], v[158:161], v[182:185], v[58:61]
	v_mfma_f32_16x16x32_bf16 v[46:49], v[150:153], v[190:193], v[46:49]
	v_mfma_f32_16x16x32_bf16 v[42:45], v[158:161], v[190:193], v[42:45]
	v_mfma_f32_16x16x32_bf16 v[30:33], v[150:153], v[198:201], v[30:33]
	v_mfma_f32_16x16x32_bf16 v[26:29], v[158:161], v[198:201], v[26:29]
	s_waitcnt lgkmcnt(0)
	v_mfma_f32_16x16x32_bf16 v[14:17], v[150:153], v[206:209], v[14:17]
	v_mfma_f32_16x16x32_bf16 v[10:13], v[158:161], v[206:209], v[10:13]
	s_setprio 0
	s_setprio 1
	v_mfma_f32_16x16x32_bf16 v[54:57], v[162:165], v[178:181], v[54:57]
	v_mfma_f32_16x16x32_bf16 v[50:53], v[170:173], v[178:181], v[50:53]
	v_mfma_f32_16x16x32_bf16 v[38:41], v[162:165], v[186:189], v[38:41]
	v_mfma_f32_16x16x32_bf16 v[34:37], v[170:173], v[186:189], v[34:37]
	v_mfma_f32_16x16x32_bf16 v[22:25], v[162:165], v[194:197], v[22:25]
	v_mfma_f32_16x16x32_bf16 v[18:21], v[170:173], v[194:197], v[18:21]
	v_mfma_f32_16x16x32_bf16 v[6:9], v[162:165], v[202:205], v[6:9]
	v_mfma_f32_16x16x32_bf16 v[2:5], v[170:173], v[202:205], v[2:5]
	v_mfma_f32_16x16x32_bf16 v[54:57], v[166:169], v[182:185], v[54:57]
	v_mfma_f32_16x16x32_bf16 v[50:53], v[174:177], v[182:185], v[50:53]
	v_mfma_f32_16x16x32_bf16 v[38:41], v[166:169], v[190:193], v[38:41]
	v_mfma_f32_16x16x32_bf16 v[34:37], v[174:177], v[190:193], v[34:37]
	v_mfma_f32_16x16x32_bf16 v[22:25], v[166:169], v[198:201], v[22:25]
	v_mfma_f32_16x16x32_bf16 v[18:21], v[174:177], v[198:201], v[18:21]
	v_mfma_f32_16x16x32_bf16 v[6:9], v[166:169], v[206:209], v[6:9]
	s_setprio 2
	s_barrier
	v_mfma_f32_16x16x32_bf16 v[2:5], v[174:177], v[206:209], v[2:5]
	s_setprio 0
	s_add_i32 s69, s69, 2
	s_add_u32 s67, s67, 0x100
	s_addc_u32 s68, s68, 0
	s_cmpk_gt_u32 s69, 0xa9
	s_mov_b64 s[36:37], s[38:39]
	s_cbranch_scc0 .LBB0_873
	s_and_b64 vcc, exec, s[10:11]
	s_cbranch_vccz .LBB0_876
	s_barrier
